# GEMM K-loops regrouped to 4 phases per 2 K-tiles (32 MFMA per barrier interval), WAR/RAW-safe staging order, vmcnt(4) at phases 2 and 4
# speedup vs baseline: 1.0253x; 1.0175x over previous
.LBB0_44:
	s_add_u32 s50, s28, 0x100
	s_addc_u32 s51, s29, 0
	s_cmpk_eq_i32 s75, 0x7c
	s_cselect_b32 s55, s27, s51
	s_cselect_b32 s54, s71, s50
	s_cselect_b32 s53, s25, s74
	s_cselect_b32 s52, s72, s73
	v_lshl_add_u64 v[156:157], s[28:29], 0, v[150:151]
	s_add_i32 m0, s9, 0xc000
	s_nop 0
	global_load_lds_dwordx4 v[156:157], off
	v_lshl_add_u64 v[156:157], s[28:29], 0, v[148:149]
	s_add_i32 m0, s9, 0xe000
	s_nop 0
	global_load_lds_dwordx4 v[156:157], off
	s_add_i32 s38, 0, 0x10000
	v_add_u32_e32 v78, s38, v163
	ds_read_b128 v[66:69], v78
	ds_read_b128 v[70:73], v78 offset:1024
	ds_read_b128 v[74:77], v78 offset:2048
	ds_read_b128 v[78:81], v78 offset:3072
	ds_read_b128 v[152:155], v165
	ds_read_b128 v[166:169], v165 offset:1024
	ds_read_b128 v[170:173], v165 offset:2048
	ds_read_b128 v[174:177], v165 offset:3072
	ds_read_b128 v[178:181], v165 offset:4096
	ds_read_b128 v[182:185], v165 offset:5120
	ds_read_b128 v[186:189], v165 offset:6144
	ds_read_b128 v[190:193], v165 offset:7168
	s_add_i32 s39, 0, 0x14000
	v_add_u32_e32 v156, s39, v163
	ds_read_b128 v[194:197], v156
	ds_read_b128 v[198:201], v156 offset:1024
	ds_read_b128 v[202:205], v156 offset:2048
	ds_read_b128 v[210:213], v156 offset:3072
	s_waitcnt lgkmcnt(0)
	s_barrier
	s_setprio 1
	v_mfma_f32_16x16x32_bf16 v[142:145], v[66:69], v[152:155], v[142:145]
	v_mfma_f32_16x16x32_bf16 v[138:141], v[74:77], v[152:155], v[138:141]
	v_mfma_f32_16x16x32_bf16 v[126:129], v[66:69], v[170:173], v[126:129]
	v_mfma_f32_16x16x32_bf16 v[122:125], v[74:77], v[170:173], v[122:125]
	v_mfma_f32_16x16x32_bf16 v[110:113], v[66:69], v[178:181], v[110:113]
	v_mfma_f32_16x16x32_bf16 v[106:109], v[74:77], v[178:181], v[106:109]
	v_mfma_f32_16x16x32_bf16 v[102:105], v[66:69], v[186:189], v[102:105]
	v_mfma_f32_16x16x32_bf16 v[98:101], v[74:77], v[186:189], v[98:101]
	v_mfma_f32_16x16x32_bf16 v[142:145], v[70:73], v[166:169], v[142:145]
	v_mfma_f32_16x16x32_bf16 v[138:141], v[78:81], v[166:169], v[138:141]
	v_mfma_f32_16x16x32_bf16 v[126:129], v[70:73], v[174:177], v[126:129]
	v_mfma_f32_16x16x32_bf16 v[122:125], v[78:81], v[174:177], v[122:125]
	v_mfma_f32_16x16x32_bf16 v[110:113], v[70:73], v[182:185], v[110:113]
	v_mfma_f32_16x16x32_bf16 v[106:109], v[78:81], v[182:185], v[106:109]
	v_mfma_f32_16x16x32_bf16 v[102:105], v[70:73], v[190:193], v[102:105]
	v_mfma_f32_16x16x32_bf16 v[98:101], v[78:81], v[190:193], v[98:101]
	v_mfma_f32_16x16x32_bf16 v[134:137], v[194:197], v[152:155], v[134:137]
	v_mfma_f32_16x16x32_bf16 v[130:133], v[202:205], v[152:155], v[130:133]
	v_mfma_f32_16x16x32_bf16 v[118:121], v[194:197], v[170:173], v[118:121]
	v_mfma_f32_16x16x32_bf16 v[114:117], v[202:205], v[170:173], v[114:117]
	v_mfma_f32_16x16x32_bf16 v[94:97], v[194:197], v[178:181], v[94:97]
	v_mfma_f32_16x16x32_bf16 v[90:93], v[202:205], v[178:181], v[90:93]
	v_mfma_f32_16x16x32_bf16 v[86:89], v[194:197], v[186:189], v[86:89]
	v_mfma_f32_16x16x32_bf16 v[82:85], v[202:205], v[186:189], v[82:85]
	v_mfma_f32_16x16x32_bf16 v[134:137], v[198:201], v[166:169], v[134:137]
	v_mfma_f32_16x16x32_bf16 v[130:133], v[210:213], v[166:169], v[130:133]
	v_mfma_f32_16x16x32_bf16 v[118:121], v[198:201], v[174:177], v[118:121]
	v_mfma_f32_16x16x32_bf16 v[114:117], v[210:213], v[174:177], v[114:117]
	v_mfma_f32_16x16x32_bf16 v[94:97], v[198:201], v[182:185], v[94:97]
	v_mfma_f32_16x16x32_bf16 v[90:93], v[210:213], v[182:185], v[90:93]
	v_mfma_f32_16x16x32_bf16 v[86:89], v[198:201], v[190:193], v[86:89]
	v_mfma_f32_16x16x32_bf16 v[82:85], v[210:213], v[190:193], v[82:85]
	s_setprio 0
	s_barrier
	s_add_i32 s28, s38, s60
	v_lshl_add_u64 v[156:157], s[52:53], 0, v[0:1]
	s_mov_b32 m0, s28
	v_lshl_add_u64 v[160:161], s[52:53], 0, v[146:147]
	global_load_lds_dwordx4 v[156:157], off
	s_add_i32 m0, s28, 0x2000
	s_nop 0
	global_load_lds_dwordx4 v[160:161], off
	s_mov_b32 m0, s9
	v_lshl_add_u64 v[206:207], s[54:55], 0, v[0:1]
	global_load_lds_dwordx4 v[206:207], off
	v_lshl_add_u64 v[214:215], s[54:55], 0, v[146:147]
	s_mov_b32 m0, s61
	s_nop 0
	global_load_lds_dwordx4 v[214:215], off
	ds_read_b128 v[152:155], v165 offset:16384
	ds_read_b128 v[166:169], v165 offset:17408
	ds_read_b128 v[170:173], v165 offset:18432
	ds_read_b128 v[174:177], v165 offset:19456
	ds_read_b128 v[178:181], v165 offset:20480
	ds_read_b128 v[182:185], v165 offset:21504
	ds_read_b128 v[186:189], v165 offset:22528
	ds_read_b128 v[190:193], v165 offset:23552
	s_waitcnt vmcnt(4)
	s_waitcnt lgkmcnt(0)
	s_barrier
	s_setprio 1
	v_mfma_f32_16x16x32_bf16 v[62:65], v[66:69], v[152:155], v[62:65]
	v_mfma_f32_16x16x32_bf16 v[58:61], v[74:77], v[152:155], v[58:61]
	v_mfma_f32_16x16x32_bf16 v[46:49], v[66:69], v[170:173], v[46:49]
	v_mfma_f32_16x16x32_bf16 v[42:45], v[74:77], v[170:173], v[42:45]
	v_mfma_f32_16x16x32_bf16 v[30:33], v[66:69], v[178:181], v[30:33]
	v_mfma_f32_16x16x32_bf16 v[26:29], v[74:77], v[178:181], v[26:29]
	v_mfma_f32_16x16x32_bf16 v[22:25], v[66:69], v[186:189], v[22:25]
	v_mfma_f32_16x16x32_bf16 v[14:17], v[74:77], v[186:189], v[14:17]
	v_mfma_f32_16x16x32_bf16 v[62:65], v[70:73], v[166:169], v[62:65]
	v_mfma_f32_16x16x32_bf16 v[58:61], v[78:81], v[166:169], v[58:61]
	v_mfma_f32_16x16x32_bf16 v[46:49], v[70:73], v[174:177], v[46:49]
	v_mfma_f32_16x16x32_bf16 v[42:45], v[78:81], v[174:177], v[42:45]
	v_mfma_f32_16x16x32_bf16 v[30:33], v[70:73], v[182:185], v[30:33]
	v_mfma_f32_16x16x32_bf16 v[26:29], v[78:81], v[182:185], v[26:29]
	v_mfma_f32_16x16x32_bf16 v[22:25], v[70:73], v[190:193], v[22:25]
	v_mfma_f32_16x16x32_bf16 v[14:17], v[78:81], v[190:193], v[14:17]
	v_mfma_f32_16x16x32_bf16 v[54:57], v[194:197], v[152:155], v[54:57]
	v_mfma_f32_16x16x32_bf16 v[50:53], v[202:205], v[152:155], v[50:53]
	v_mfma_f32_16x16x32_bf16 v[38:41], v[194:197], v[170:173], v[38:41]
	v_mfma_f32_16x16x32_bf16 v[34:37], v[202:205], v[170:173], v[34:37]
	v_mfma_f32_16x16x32_bf16 v[18:21], v[194:197], v[178:181], v[18:21]
	v_mfma_f32_16x16x32_bf16 v[10:13], v[202:205], v[178:181], v[10:13]
	v_mfma_f32_16x16x32_bf16 v[6:9], v[194:197], v[186:189], v[6:9]
	v_mfma_f32_16x16x32_bf16 v[2:5], v[202:205], v[186:189], v[2:5]
	v_mfma_f32_16x16x32_bf16 v[54:57], v[198:201], v[166:169], v[54:57]
	v_mfma_f32_16x16x32_bf16 v[50:53], v[210:213], v[166:169], v[50:53]
	v_mfma_f32_16x16x32_bf16 v[38:41], v[198:201], v[174:177], v[38:41]
	v_mfma_f32_16x16x32_bf16 v[34:37], v[210:213], v[174:177], v[34:37]
	v_mfma_f32_16x16x32_bf16 v[18:21], v[198:201], v[182:185], v[18:21]
	v_mfma_f32_16x16x32_bf16 v[10:13], v[210:213], v[182:185], v[10:13]
	v_mfma_f32_16x16x32_bf16 v[6:9], v[198:201], v[190:193], v[6:9]
	v_mfma_f32_16x16x32_bf16 v[2:5], v[210:213], v[190:193], v[2:5]
	s_setprio 0
	s_barrier
	s_add_u32 s28, s52, 0x200000
	s_addc_u32 s29, s53, 0
	s_add_i32 s38, s39, s60
	v_lshl_add_u64 v[66:67], s[28:29], 0, v[0:1]
	s_mov_b32 m0, s38
	s_nop 0
	global_load_lds_dwordx4 v[66:67], off
	v_lshl_add_u64 v[66:67], s[28:29], 0, v[146:147]
	s_add_i32 m0, s38, 0x2000
	s_nop 0
	global_load_lds_dwordx4 v[66:67], off
	s_add_u32 s28, s54, 0x200000
	s_addc_u32 s29, s55, 0
	s_mov_b32 m0, s62
	v_lshl_add_u64 v[194:195], s[28:29], 0, v[0:1]
	global_load_lds_dwordx4 v[194:195], off
	v_lshl_add_u64 v[194:195], s[28:29], 0, v[146:147]
	s_mov_b32 m0, s63
	s_nop 0
	global_load_lds_dwordx4 v[194:195], off
	s_add_i32 s38, 0, 0x18000
	v_add_u32_e32 v78, s38, v163
	ds_read_b128 v[66:69], v78
	ds_read_b128 v[70:73], v78 offset:1024
	ds_read_b128 v[74:77], v78 offset:2048
	ds_read_b128 v[78:81], v78 offset:3072
	ds_read_b128 v[152:155], v165 offset:32768
	ds_read_b128 v[166:169], v165 offset:33792
	ds_read_b128 v[170:173], v165 offset:34816
	ds_read_b128 v[174:177], v165 offset:35840
	ds_read_b128 v[178:181], v165 offset:36864
	ds_read_b128 v[182:185], v165 offset:37888
	ds_read_b128 v[186:189], v165 offset:38912
	ds_read_b128 v[190:193], v165 offset:39936
	s_add_i32 s39, 0, 0x1c000
	v_add_u32_e32 v210, s39, v163
	ds_read_b128 v[194:197], v210
	ds_read_b128 v[198:201], v210 offset:1024
	ds_read_b128 v[202:205], v210 offset:2048
	ds_read_b128 v[210:213], v210 offset:3072
	s_waitcnt lgkmcnt(0)
	s_barrier
	s_setprio 1
	v_mfma_f32_16x16x32_bf16 v[142:145], v[66:69], v[152:155], v[142:145]
	v_mfma_f32_16x16x32_bf16 v[138:141], v[74:77], v[152:155], v[138:141]
	v_mfma_f32_16x16x32_bf16 v[126:129], v[66:69], v[170:173], v[126:129]
	v_mfma_f32_16x16x32_bf16 v[122:125], v[74:77], v[170:173], v[122:125]
	v_mfma_f32_16x16x32_bf16 v[110:113], v[66:69], v[178:181], v[110:113]
	v_mfma_f32_16x16x32_bf16 v[106:109], v[74:77], v[178:181], v[106:109]
	v_mfma_f32_16x16x32_bf16 v[102:105], v[66:69], v[186:189], v[102:105]
	v_mfma_f32_16x16x32_bf16 v[98:101], v[74:77], v[186:189], v[98:101]
	v_mfma_f32_16x16x32_bf16 v[142:145], v[70:73], v[166:169], v[142:145]
	v_mfma_f32_16x16x32_bf16 v[138:141], v[78:81], v[166:169], v[138:141]
	v_mfma_f32_16x16x32_bf16 v[126:129], v[70:73], v[174:177], v[126:129]
	v_mfma_f32_16x16x32_bf16 v[122:125], v[78:81], v[174:177], v[122:125]
	v_mfma_f32_16x16x32_bf16 v[110:113], v[70:73], v[182:185], v[110:113]
	v_mfma_f32_16x16x32_bf16 v[106:109], v[78:81], v[182:185], v[106:109]
	v_mfma_f32_16x16x32_bf16 v[102:105], v[70:73], v[190:193], v[102:105]
	v_mfma_f32_16x16x32_bf16 v[98:101], v[78:81], v[190:193], v[98:101]
	v_mfma_f32_16x16x32_bf16 v[134:137], v[194:197], v[152:155], v[134:137]
	v_mfma_f32_16x16x32_bf16 v[130:133], v[202:205], v[152:155], v[130:133]
	v_mfma_f32_16x16x32_bf16 v[118:121], v[194:197], v[170:173], v[118:121]
	v_mfma_f32_16x16x32_bf16 v[114:117], v[202:205], v[170:173], v[114:117]
	v_mfma_f32_16x16x32_bf16 v[94:97], v[194:197], v[178:181], v[94:97]
	v_mfma_f32_16x16x32_bf16 v[90:93], v[202:205], v[178:181], v[90:93]
	v_mfma_f32_16x16x32_bf16 v[86:89], v[194:197], v[186:189], v[86:89]
	v_mfma_f32_16x16x32_bf16 v[82:85], v[202:205], v[186:189], v[82:85]
	v_mfma_f32_16x16x32_bf16 v[134:137], v[198:201], v[166:169], v[134:137]
	v_mfma_f32_16x16x32_bf16 v[130:133], v[210:213], v[166:169], v[130:133]
	v_mfma_f32_16x16x32_bf16 v[118:121], v[198:201], v[174:177], v[118:121]
	v_mfma_f32_16x16x32_bf16 v[114:117], v[210:213], v[174:177], v[114:117]
	v_mfma_f32_16x16x32_bf16 v[94:97], v[198:201], v[182:185], v[94:97]
	v_mfma_f32_16x16x32_bf16 v[90:93], v[210:213], v[182:185], v[90:93]
	v_mfma_f32_16x16x32_bf16 v[86:89], v[198:201], v[190:193], v[86:89]
	v_mfma_f32_16x16x32_bf16 v[82:85], v[210:213], v[190:193], v[82:85]
	s_setprio 0
	s_barrier
	s_add_i32 s28, s38, s60
	v_lshl_add_u64 v[156:157], v[156:157], 0, s[36:37]
	s_mov_b32 m0, s28
	s_nop 0
	global_load_lds_dwordx4 v[156:157], off
	v_lshl_add_u64 v[156:157], v[160:161], 0, s[36:37]
	s_add_i32 m0, s28, 0x2000
	s_nop 0
	global_load_lds_dwordx4 v[156:157], off
	s_mov_b32 m0, s66
	v_lshl_add_u64 v[156:157], v[206:207], 0, s[36:37]
	global_load_lds_dwordx4 v[156:157], off
	v_lshl_add_u64 v[156:157], v[214:215], 0, s[36:37]
	s_mov_b32 m0, s67
	s_nop 0
	global_load_lds_dwordx4 v[156:157], off
	ds_read_b128 v[152:155], v165 offset:49152
	ds_read_b128 v[166:169], v165 offset:50176
	ds_read_b128 v[170:173], v165 offset:51200
	ds_read_b128 v[174:177], v165 offset:52224
	ds_read_b128 v[178:181], v165 offset:53248
	ds_read_b128 v[182:185], v165 offset:54272
	ds_read_b128 v[186:189], v165 offset:55296
	ds_read_b128 v[190:193], v165 offset:56320
	s_waitcnt vmcnt(4)
	s_waitcnt lgkmcnt(0)
	s_barrier
	s_setprio 1
	v_mfma_f32_16x16x32_bf16 v[62:65], v[66:69], v[152:155], v[62:65]
	v_mfma_f32_16x16x32_bf16 v[58:61], v[74:77], v[152:155], v[58:61]
	v_mfma_f32_16x16x32_bf16 v[46:49], v[66:69], v[170:173], v[46:49]
	v_mfma_f32_16x16x32_bf16 v[42:45], v[74:77], v[170:173], v[42:45]
	v_mfma_f32_16x16x32_bf16 v[30:33], v[66:69], v[178:181], v[30:33]
	v_mfma_f32_16x16x32_bf16 v[26:29], v[74:77], v[178:181], v[26:29]
	v_mfma_f32_16x16x32_bf16 v[22:25], v[66:69], v[186:189], v[22:25]
	v_mfma_f32_16x16x32_bf16 v[14:17], v[74:77], v[186:189], v[14:17]
	v_mfma_f32_16x16x32_bf16 v[62:65], v[70:73], v[166:169], v[62:65]
	v_mfma_f32_16x16x32_bf16 v[58:61], v[78:81], v[166:169], v[58:61]
	v_mfma_f32_16x16x32_bf16 v[46:49], v[70:73], v[174:177], v[46:49]
	v_mfma_f32_16x16x32_bf16 v[42:45], v[78:81], v[174:177], v[42:45]
	v_mfma_f32_16x16x32_bf16 v[30:33], v[70:73], v[182:185], v[30:33]
	v_mfma_f32_16x16x32_bf16 v[26:29], v[78:81], v[182:185], v[26:29]
	v_mfma_f32_16x16x32_bf16 v[22:25], v[70:73], v[190:193], v[22:25]
	v_mfma_f32_16x16x32_bf16 v[14:17], v[78:81], v[190:193], v[14:17]
	s_add_u32 s28, s52, 0x200080
	s_addc_u32 s29, s53, 0
	s_add_i32 s38, s39, s60
	v_lshl_add_u64 v[66:67], s[28:29], 0, v[0:1]
	s_mov_b32 m0, s38
	s_nop 0
	global_load_lds_dwordx4 v[66:67], off
	v_lshl_add_u64 v[66:67], s[28:29], 0, v[146:147]
	s_add_i32 m0, s38, 0x2000
	s_nop 0
	global_load_lds_dwordx4 v[66:67], off
	v_mfma_f32_16x16x32_bf16 v[54:57], v[194:197], v[152:155], v[54:57]
	v_mfma_f32_16x16x32_bf16 v[50:53], v[202:205], v[152:155], v[50:53]
	v_mfma_f32_16x16x32_bf16 v[38:41], v[194:197], v[170:173], v[38:41]
	v_mfma_f32_16x16x32_bf16 v[34:37], v[202:205], v[170:173], v[34:37]
	v_mfma_f32_16x16x32_bf16 v[18:21], v[194:197], v[178:181], v[18:21]
	v_mfma_f32_16x16x32_bf16 v[10:13], v[202:205], v[178:181], v[10:13]
	v_mfma_f32_16x16x32_bf16 v[6:9], v[194:197], v[186:189], v[6:9]
	v_mfma_f32_16x16x32_bf16 v[2:5], v[202:205], v[186:189], v[2:5]
	v_mfma_f32_16x16x32_bf16 v[54:57], v[198:201], v[166:169], v[54:57]
	v_mfma_f32_16x16x32_bf16 v[50:53], v[210:213], v[166:169], v[50:53]
	v_mfma_f32_16x16x32_bf16 v[38:41], v[198:201], v[174:177], v[38:41]
	v_mfma_f32_16x16x32_bf16 v[34:37], v[210:213], v[174:177], v[34:37]
	v_mfma_f32_16x16x32_bf16 v[18:21], v[198:201], v[182:185], v[18:21]
	v_mfma_f32_16x16x32_bf16 v[10:13], v[210:213], v[182:185], v[10:13]
	v_mfma_f32_16x16x32_bf16 v[6:9], v[198:201], v[190:193], v[6:9]
	v_mfma_f32_16x16x32_bf16 v[2:5], v[210:213], v[190:193], v[2:5]
	s_setprio 0
	s_add_i32 s75, s75, 2
	s_add_u32 s73, s73, 0x100
	s_addc_u32 s74, s74, 0
	s_cmpk_gt_u32 s75, 0x7d
	s_mov_b64 s[28:29], s[50:51]
	s_barrier
	s_cbranch_scc0 .LBB0_44
	s_cmp_lt_i32 s8, 64
	s_cselect_b64 s[50:51], -1, 0
	s_cmp_gt_i32 s8, 63
	s_cbranch_scc0 .LBB0_35
	s_mov_b64 s[52:53], 0x18000
	s_mov_b64 s[28:29], s[46:47]
	s_branch .LBB0_36

.LBB0_58:
	s_add_u32 s52, s50, 0x100
	s_addc_u32 s53, s51, 0
	s_cmp_eq_u32 s71, 28
	s_cselect_b32 s57, s11, s53
	s_cselect_b32 s56, s29, s52
	s_cselect_b32 s55, s41, s70
	s_cselect_b32 s54, s43, s69
	v_lshl_add_u64 v[156:157], s[50:51], 0, v[134:135]
	s_add_i32 m0, s25, 0xc000
	s_nop 0
	global_load_lds_dwordx4 v[156:157], off
	v_lshl_add_u64 v[156:157], s[50:51], 0, v[132:133]
	s_add_i32 m0, s25, 0xe000
	s_nop 0
	global_load_lds_dwordx4 v[156:157], off
	s_add_i32 s38, 0, 0x10000
	v_add_u32_e32 v152, s38, v137
	ds_read_b128 v[140:143], v152
	ds_read_b128 v[144:147], v152 offset:1024
	ds_read_b128 v[148:151], v152 offset:2048
	ds_read_b128 v[152:155], v152 offset:3072
	ds_read_b128 v[160:163], v139
	ds_read_b128 v[164:167], v139 offset:1024
	ds_read_b128 v[168:171], v139 offset:2048
	ds_read_b128 v[172:175], v139 offset:3072
	ds_read_b128 v[176:179], v139 offset:4096
	ds_read_b128 v[180:183], v139 offset:5120
	ds_read_b128 v[184:187], v139 offset:6144
	ds_read_b128 v[188:191], v139 offset:7168
	s_add_i32 s50, 0, 0x14000
	v_add_u32_e32 v156, s50, v137
	ds_read_b128 v[192:195], v156
	ds_read_b128 v[196:199], v156 offset:1024
	ds_read_b128 v[200:203], v156 offset:2048
	ds_read_b128 v[204:207], v156 offset:3072
	s_waitcnt lgkmcnt(0)
	s_barrier
	s_setprio 1
	v_mfma_f32_16x16x32_bf16 v[126:129], v[140:143], v[160:163], v[126:129]
	v_mfma_f32_16x16x32_bf16 v[122:125], v[148:151], v[160:163], v[122:125]
	v_mfma_f32_16x16x32_bf16 v[118:121], v[140:143], v[168:171], v[118:121]
	v_mfma_f32_16x16x32_bf16 v[114:117], v[148:151], v[168:171], v[114:117]
	v_mfma_f32_16x16x32_bf16 v[106:109], v[140:143], v[176:179], v[106:109]
	v_mfma_f32_16x16x32_bf16 v[98:101], v[148:151], v[176:179], v[98:101]
	v_mfma_f32_16x16x32_bf16 v[90:93], v[140:143], v[184:187], v[90:93]
	v_mfma_f32_16x16x32_bf16 v[82:85], v[148:151], v[184:187], v[82:85]
	v_mfma_f32_16x16x32_bf16 v[126:129], v[144:147], v[164:167], v[126:129]
	v_mfma_f32_16x16x32_bf16 v[122:125], v[152:155], v[164:167], v[122:125]
	v_mfma_f32_16x16x32_bf16 v[118:121], v[144:147], v[172:175], v[118:121]
	v_mfma_f32_16x16x32_bf16 v[114:117], v[152:155], v[172:175], v[114:117]
	v_mfma_f32_16x16x32_bf16 v[106:109], v[144:147], v[180:183], v[106:109]
	v_mfma_f32_16x16x32_bf16 v[98:101], v[152:155], v[180:183], v[98:101]
	v_mfma_f32_16x16x32_bf16 v[90:93], v[144:147], v[188:191], v[90:93]
	v_mfma_f32_16x16x32_bf16 v[82:85], v[152:155], v[188:191], v[82:85]
	v_mfma_f32_16x16x32_bf16 v[110:113], v[192:195], v[160:163], v[110:113]
	v_mfma_f32_16x16x32_bf16 v[102:105], v[200:203], v[160:163], v[102:105]
	v_mfma_f32_16x16x32_bf16 v[94:97], v[192:195], v[168:171], v[94:97]
	v_mfma_f32_16x16x32_bf16 v[86:89], v[200:203], v[168:171], v[86:89]
	v_mfma_f32_16x16x32_bf16 v[78:81], v[192:195], v[176:179], v[78:81]
	v_mfma_f32_16x16x32_bf16 v[74:77], v[200:203], v[176:179], v[74:77]
	v_mfma_f32_16x16x32_bf16 v[70:73], v[192:195], v[184:187], v[70:73]
	v_mfma_f32_16x16x32_bf16 v[66:69], v[200:203], v[184:187], v[66:69]
	v_mfma_f32_16x16x32_bf16 v[110:113], v[196:199], v[164:167], v[110:113]
	v_mfma_f32_16x16x32_bf16 v[102:105], v[204:207], v[164:167], v[102:105]
	v_mfma_f32_16x16x32_bf16 v[94:97], v[196:199], v[172:175], v[94:97]
	v_mfma_f32_16x16x32_bf16 v[86:89], v[204:207], v[172:175], v[86:89]
	v_mfma_f32_16x16x32_bf16 v[78:81], v[196:199], v[180:183], v[78:81]
	v_mfma_f32_16x16x32_bf16 v[74:77], v[204:207], v[180:183], v[74:77]
	v_mfma_f32_16x16x32_bf16 v[70:73], v[196:199], v[188:191], v[70:73]
	v_mfma_f32_16x16x32_bf16 v[66:69], v[204:207], v[188:191], v[66:69]
	s_setprio 0
	s_barrier
	s_add_i32 s38, s38, s63
	v_lshl_add_u64 v[156:157], s[54:55], 0, v[0:1]
	s_mov_b32 m0, s38
	v_lshl_add_u64 v[210:211], s[54:55], 0, v[130:131]
	global_load_lds_dwordx4 v[156:157], off
	s_add_i32 m0, s38, 0x2000
	s_nop 0
	global_load_lds_dwordx4 v[210:211], off
	s_mov_b32 m0, s25
	v_lshl_add_u64 v[212:213], s[56:57], 0, v[0:1]
	global_load_lds_dwordx4 v[212:213], off
	v_lshl_add_u64 v[214:215], s[56:57], 0, v[130:131]
	s_mov_b32 m0, s27
	s_nop 0
	global_load_lds_dwordx4 v[214:215], off
	ds_read_b128 v[160:163], v139 offset:16384
	ds_read_b128 v[164:167], v139 offset:17408
	ds_read_b128 v[168:171], v139 offset:18432
	ds_read_b128 v[172:175], v139 offset:19456
	ds_read_b128 v[176:179], v139 offset:20480
	ds_read_b128 v[180:183], v139 offset:21504
	ds_read_b128 v[184:187], v139 offset:22528
	ds_read_b128 v[188:191], v139 offset:23552
	s_waitcnt vmcnt(4)
	s_waitcnt lgkmcnt(0)
	s_barrier
	s_setprio 1
	v_mfma_f32_16x16x32_bf16 v[62:65], v[140:143], v[160:163], v[62:65]
	v_mfma_f32_16x16x32_bf16 v[58:61], v[148:151], v[160:163], v[58:61]
	v_mfma_f32_16x16x32_bf16 v[54:57], v[140:143], v[168:171], v[54:57]
	v_mfma_f32_16x16x32_bf16 v[50:53], v[148:151], v[168:171], v[50:53]
	v_mfma_f32_16x16x32_bf16 v[38:41], v[140:143], v[176:179], v[38:41]
	v_mfma_f32_16x16x32_bf16 v[34:37], v[148:151], v[176:179], v[34:37]
	v_mfma_f32_16x16x32_bf16 v[22:25], v[140:143], v[184:187], v[22:25]
	v_mfma_f32_16x16x32_bf16 v[18:21], v[148:151], v[184:187], v[18:21]
	v_mfma_f32_16x16x32_bf16 v[62:65], v[144:147], v[164:167], v[62:65]
	v_mfma_f32_16x16x32_bf16 v[58:61], v[152:155], v[164:167], v[58:61]
	v_mfma_f32_16x16x32_bf16 v[54:57], v[144:147], v[172:175], v[54:57]
	v_mfma_f32_16x16x32_bf16 v[50:53], v[152:155], v[172:175], v[50:53]
	v_mfma_f32_16x16x32_bf16 v[38:41], v[144:147], v[180:183], v[38:41]
	v_mfma_f32_16x16x32_bf16 v[34:37], v[152:155], v[180:183], v[34:37]
	v_mfma_f32_16x16x32_bf16 v[22:25], v[144:147], v[188:191], v[22:25]
	v_mfma_f32_16x16x32_bf16 v[18:21], v[152:155], v[188:191], v[18:21]
	v_mfma_f32_16x16x32_bf16 v[46:49], v[192:195], v[160:163], v[46:49]
	v_mfma_f32_16x16x32_bf16 v[42:45], v[200:203], v[160:163], v[42:45]
	v_mfma_f32_16x16x32_bf16 v[30:33], v[192:195], v[168:171], v[30:33]
	v_mfma_f32_16x16x32_bf16 v[26:29], v[200:203], v[168:171], v[26:29]
	v_mfma_f32_16x16x32_bf16 v[14:17], v[192:195], v[176:179], v[14:17]
	v_mfma_f32_16x16x32_bf16 v[10:13], v[200:203], v[176:179], v[10:13]
	v_mfma_f32_16x16x32_bf16 v[6:9], v[192:195], v[184:187], v[6:9]
	v_mfma_f32_16x16x32_bf16 v[2:5], v[200:203], v[184:187], v[2:5]
	v_mfma_f32_16x16x32_bf16 v[46:49], v[196:199], v[164:167], v[46:49]
	v_mfma_f32_16x16x32_bf16 v[42:45], v[204:207], v[164:167], v[42:45]
	v_mfma_f32_16x16x32_bf16 v[30:33], v[196:199], v[172:175], v[30:33]
	v_mfma_f32_16x16x32_bf16 v[26:29], v[204:207], v[172:175], v[26:29]
	v_mfma_f32_16x16x32_bf16 v[14:17], v[196:199], v[180:183], v[14:17]
	v_mfma_f32_16x16x32_bf16 v[10:13], v[204:207], v[180:183], v[10:13]
	v_mfma_f32_16x16x32_bf16 v[6:9], v[196:199], v[188:191], v[6:9]
	v_mfma_f32_16x16x32_bf16 v[2:5], v[204:207], v[188:191], v[2:5]
	s_setprio 0
	s_barrier
	s_add_u32 s38, s54, 0x200000
	s_addc_u32 s39, s55, 0
	s_add_i32 s50, s50, s63
	v_lshl_add_u64 v[140:141], s[38:39], 0, v[0:1]
	s_mov_b32 m0, s50
	s_nop 0
	global_load_lds_dwordx4 v[140:141], off
	v_lshl_add_u64 v[140:141], s[38:39], 0, v[130:131]
	s_add_i32 m0, s50, 0x2000
	s_nop 0
	global_load_lds_dwordx4 v[140:141], off
	s_add_u32 s38, s56, 0x200000
	s_addc_u32 s39, s57, 0
	s_mov_b32 m0, s64
	v_lshl_add_u64 v[192:193], s[38:39], 0, v[0:1]
	global_load_lds_dwordx4 v[192:193], off
	v_lshl_add_u64 v[192:193], s[38:39], 0, v[130:131]
	s_mov_b32 m0, s65
	s_nop 0
	global_load_lds_dwordx4 v[192:193], off
	s_add_i32 s50, 0, 0x18000
	v_add_u32_e32 v152, s50, v137
	ds_read_b128 v[140:143], v152
	ds_read_b128 v[144:147], v152 offset:1024
	ds_read_b128 v[148:151], v152 offset:2048
	ds_read_b128 v[152:155], v152 offset:3072
	ds_read_b128 v[160:163], v139 offset:32768
	ds_read_b128 v[164:167], v139 offset:33792
	ds_read_b128 v[168:171], v139 offset:34816
	ds_read_b128 v[172:175], v139 offset:35840
	ds_read_b128 v[176:179], v139 offset:36864
	ds_read_b128 v[180:183], v139 offset:37888
	ds_read_b128 v[184:187], v139 offset:38912
	ds_read_b128 v[188:191], v139 offset:39936
	s_add_i32 s51, 0, 0x1c000
	v_add_u32_e32 v204, s51, v137
	ds_read_b128 v[192:195], v204
	ds_read_b128 v[196:199], v204 offset:1024
	ds_read_b128 v[200:203], v204 offset:2048
	ds_read_b128 v[204:207], v204 offset:3072
	s_waitcnt lgkmcnt(0)
	s_barrier
	s_setprio 1
	v_mfma_f32_16x16x32_bf16 v[126:129], v[140:143], v[160:163], v[126:129]
	v_mfma_f32_16x16x32_bf16 v[122:125], v[148:151], v[160:163], v[122:125]
	v_mfma_f32_16x16x32_bf16 v[118:121], v[140:143], v[168:171], v[118:121]
	v_mfma_f32_16x16x32_bf16 v[114:117], v[148:151], v[168:171], v[114:117]
	v_mfma_f32_16x16x32_bf16 v[106:109], v[140:143], v[176:179], v[106:109]
	v_mfma_f32_16x16x32_bf16 v[98:101], v[148:151], v[176:179], v[98:101]
	v_mfma_f32_16x16x32_bf16 v[90:93], v[140:143], v[184:187], v[90:93]
	v_mfma_f32_16x16x32_bf16 v[82:85], v[148:151], v[184:187], v[82:85]
	v_mfma_f32_16x16x32_bf16 v[126:129], v[144:147], v[164:167], v[126:129]
	v_mfma_f32_16x16x32_bf16 v[122:125], v[152:155], v[164:167], v[122:125]
	v_mfma_f32_16x16x32_bf16 v[118:121], v[144:147], v[172:175], v[118:121]
	v_mfma_f32_16x16x32_bf16 v[114:117], v[152:155], v[172:175], v[114:117]
	v_mfma_f32_16x16x32_bf16 v[106:109], v[144:147], v[180:183], v[106:109]
	v_mfma_f32_16x16x32_bf16 v[98:101], v[152:155], v[180:183], v[98:101]
	v_mfma_f32_16x16x32_bf16 v[90:93], v[144:147], v[188:191], v[90:93]
	v_mfma_f32_16x16x32_bf16 v[82:85], v[152:155], v[188:191], v[82:85]
	v_mfma_f32_16x16x32_bf16 v[110:113], v[192:195], v[160:163], v[110:113]
	v_mfma_f32_16x16x32_bf16 v[102:105], v[200:203], v[160:163], v[102:105]
	v_mfma_f32_16x16x32_bf16 v[94:97], v[192:195], v[168:171], v[94:97]
	v_mfma_f32_16x16x32_bf16 v[86:89], v[200:203], v[168:171], v[86:89]
	v_mfma_f32_16x16x32_bf16 v[78:81], v[192:195], v[176:179], v[78:81]
	v_mfma_f32_16x16x32_bf16 v[74:77], v[200:203], v[176:179], v[74:77]
	v_mfma_f32_16x16x32_bf16 v[70:73], v[192:195], v[184:187], v[70:73]
	v_mfma_f32_16x16x32_bf16 v[66:69], v[200:203], v[184:187], v[66:69]
	v_mfma_f32_16x16x32_bf16 v[110:113], v[196:199], v[164:167], v[110:113]
	v_mfma_f32_16x16x32_bf16 v[102:105], v[204:207], v[164:167], v[102:105]
	v_mfma_f32_16x16x32_bf16 v[94:97], v[196:199], v[172:175], v[94:97]
	v_mfma_f32_16x16x32_bf16 v[86:89], v[204:207], v[172:175], v[86:89]
	v_mfma_f32_16x16x32_bf16 v[78:81], v[196:199], v[180:183], v[78:81]
	v_mfma_f32_16x16x32_bf16 v[74:77], v[204:207], v[180:183], v[74:77]
	v_mfma_f32_16x16x32_bf16 v[70:73], v[196:199], v[188:191], v[70:73]
	v_mfma_f32_16x16x32_bf16 v[66:69], v[204:207], v[188:191], v[66:69]
	s_setprio 0
	s_barrier
	s_add_i32 s38, s50, s63
	v_lshl_add_u64 v[156:157], v[156:157], 0, s[36:37]
	s_mov_b32 m0, s38
	s_nop 0
	global_load_lds_dwordx4 v[156:157], off
	v_lshl_add_u64 v[156:157], v[210:211], 0, s[36:37]
	s_add_i32 m0, s38, 0x2000
	s_nop 0
	global_load_lds_dwordx4 v[156:157], off
	s_mov_b32 m0, s66
	v_lshl_add_u64 v[156:157], v[212:213], 0, s[36:37]
	global_load_lds_dwordx4 v[156:157], off
	v_lshl_add_u64 v[156:157], v[214:215], 0, s[36:37]
	s_mov_b32 m0, s67
	s_nop 0
	global_load_lds_dwordx4 v[156:157], off
	ds_read_b128 v[160:163], v139 offset:49152
	ds_read_b128 v[164:167], v139 offset:50176
	ds_read_b128 v[168:171], v139 offset:51200
	ds_read_b128 v[172:175], v139 offset:52224
	ds_read_b128 v[176:179], v139 offset:53248
	ds_read_b128 v[180:183], v139 offset:54272
	ds_read_b128 v[184:187], v139 offset:55296
	ds_read_b128 v[188:191], v139 offset:56320
	s_waitcnt vmcnt(4)
	s_waitcnt lgkmcnt(0)
	s_barrier
	s_setprio 1
	v_mfma_f32_16x16x32_bf16 v[62:65], v[140:143], v[160:163], v[62:65]
	v_mfma_f32_16x16x32_bf16 v[58:61], v[148:151], v[160:163], v[58:61]
	v_mfma_f32_16x16x32_bf16 v[54:57], v[140:143], v[168:171], v[54:57]
	v_mfma_f32_16x16x32_bf16 v[50:53], v[148:151], v[168:171], v[50:53]
	v_mfma_f32_16x16x32_bf16 v[38:41], v[140:143], v[176:179], v[38:41]
	v_mfma_f32_16x16x32_bf16 v[34:37], v[148:151], v[176:179], v[34:37]
	v_mfma_f32_16x16x32_bf16 v[22:25], v[140:143], v[184:187], v[22:25]
	v_mfma_f32_16x16x32_bf16 v[18:21], v[148:151], v[184:187], v[18:21]
	v_mfma_f32_16x16x32_bf16 v[62:65], v[144:147], v[164:167], v[62:65]
	v_mfma_f32_16x16x32_bf16 v[58:61], v[152:155], v[164:167], v[58:61]
	v_mfma_f32_16x16x32_bf16 v[54:57], v[144:147], v[172:175], v[54:57]
	v_mfma_f32_16x16x32_bf16 v[50:53], v[152:155], v[172:175], v[50:53]
	v_mfma_f32_16x16x32_bf16 v[38:41], v[144:147], v[180:183], v[38:41]
	v_mfma_f32_16x16x32_bf16 v[34:37], v[152:155], v[180:183], v[34:37]
	v_mfma_f32_16x16x32_bf16 v[22:25], v[144:147], v[188:191], v[22:25]
	v_mfma_f32_16x16x32_bf16 v[18:21], v[152:155], v[188:191], v[18:21]
	s_add_u32 s38, s54, 0x200080
	s_addc_u32 s39, s55, 0
	s_add_i32 s50, s51, s63
	v_lshl_add_u64 v[140:141], s[38:39], 0, v[0:1]
	s_mov_b32 m0, s50
	s_nop 0
	global_load_lds_dwordx4 v[140:141], off
	v_lshl_add_u64 v[140:141], s[38:39], 0, v[130:131]
	s_add_i32 m0, s50, 0x2000
	s_nop 0
	global_load_lds_dwordx4 v[140:141], off
	v_mfma_f32_16x16x32_bf16 v[46:49], v[192:195], v[160:163], v[46:49]
	v_mfma_f32_16x16x32_bf16 v[42:45], v[200:203], v[160:163], v[42:45]
	v_mfma_f32_16x16x32_bf16 v[30:33], v[192:195], v[168:171], v[30:33]
	v_mfma_f32_16x16x32_bf16 v[26:29], v[200:203], v[168:171], v[26:29]
	v_mfma_f32_16x16x32_bf16 v[14:17], v[192:195], v[176:179], v[14:17]
	v_mfma_f32_16x16x32_bf16 v[10:13], v[200:203], v[176:179], v[10:13]
	v_mfma_f32_16x16x32_bf16 v[6:9], v[192:195], v[184:187], v[6:9]
	v_mfma_f32_16x16x32_bf16 v[2:5], v[200:203], v[184:187], v[2:5]
	v_mfma_f32_16x16x32_bf16 v[46:49], v[196:199], v[164:167], v[46:49]
	v_mfma_f32_16x16x32_bf16 v[42:45], v[204:207], v[164:167], v[42:45]
	v_mfma_f32_16x16x32_bf16 v[30:33], v[196:199], v[172:175], v[30:33]
	v_mfma_f32_16x16x32_bf16 v[26:29], v[204:207], v[172:175], v[26:29]
	v_mfma_f32_16x16x32_bf16 v[14:17], v[196:199], v[180:183], v[14:17]
	v_mfma_f32_16x16x32_bf16 v[10:13], v[204:207], v[180:183], v[10:13]
	v_mfma_f32_16x16x32_bf16 v[6:9], v[196:199], v[188:191], v[6:9]
	v_mfma_f32_16x16x32_bf16 v[2:5], v[204:207], v[188:191], v[2:5]
	s_setprio 0
	s_add_i32 s71, s71, 2
	s_add_u32 s69, s69, 0x100
	s_addc_u32 s70, s70, 0
	s_cmp_gt_u32 s71, 29
	s_mov_b64 s[50:51], s[52:53]
	s_barrier
	s_cbranch_scc0 .LBB0_58
	s_ashr_i32 s11, s10, 31
	s_lshl_b64 s[10:11], s[10:11], 24
	v_lshl_or_b32 v140, s26, 8, v138
	s_add_u32 s10, s8, s10
	v_lshl_add_u32 v142, s24, 8, v136
	s_addc_u32 s11, s9, s11
	v_ashrrev_i32_e32 v141, 31, v140
	v_ashrrev_i32_e32 v143, 31, v142
	v_lshl_add_u64 v[140:141], v[140:141], 2, s[10:11]
	v_lshlrev_b64 v[144:145], 13, v[142:143]
	v_lshl_add_u64 v[144:145], v[140:141], 0, v[144:145]
	global_store_dwordx4 v[144:145], v[126:129], off
	global_store_dwordx4 v[144:145], v[122:125], off offset:64
	global_store_dwordx4 v[144:145], v[110:113], off offset:512
	global_store_dwordx4 v[144:145], v[102:105], off offset:576
	s_mov_b64 s[10:11], 0x100000
	s_mov_b32 s26, s40
	v_or_b32_e32 v102, 16, v142
	v_ashrrev_i32_e32 v103, 31, v102
	v_lshlrev_b64 v[102:103], 13, v[102:103]
	v_lshl_add_u64 v[102:103], v[140:141], 0, v[102:103]
	global_store_dwordx4 v[102:103], v[118:121], off
	global_store_dwordx4 v[102:103], v[114:117], off offset:64
	global_store_dwordx4 v[102:103], v[94:97], off offset:512
	global_store_dwordx4 v[102:103], v[86:89], off offset:576
	s_mov_b32 s24, s42
	s_mov_b64 s[52:53], s[48:49]
	v_or_b32_e32 v86, 32, v142
	v_ashrrev_i32_e32 v87, 31, v86
	v_lshlrev_b64 v[86:87], 13, v[86:87]
	v_lshl_add_u64 v[86:87], v[140:141], 0, v[86:87]
	global_store_dwordx4 v[86:87], v[106:109], off
	global_store_dwordx4 v[86:87], v[98:101], off offset:64
	global_store_dwordx4 v[86:87], v[78:81], off offset:512
	global_store_dwordx4 v[86:87], v[74:77], off offset:576
	s_mov_b64 s[50:51], s[46:47]
	s_nop 0
	v_or_b32_e32 v74, 48, v142
	v_ashrrev_i32_e32 v75, 31, v74
	v_lshlrev_b64 v[74:75], 13, v[74:75]
	v_lshl_add_u64 v[74:75], v[140:141], 0, v[74:75]
	global_store_dwordx4 v[74:75], v[90:93], off
	global_store_dwordx4 v[74:75], v[82:85], off offset:64
	global_store_dwordx4 v[74:75], v[70:73], off offset:512
	global_store_dwordx4 v[74:75], v[66:69], off offset:576
	s_nop 1
	v_add_co_u32_e32 v68, vcc, s93, v144
	v_lshl_add_u64 v[66:67], v[144:145], 0, s[10:11]
	s_nop 0
	v_addc_co_u32_e32 v69, vcc, 0, v145, vcc
	s_mov_b64 s[10:11], 0x120000
	global_store_dwordx4 v[68:69], v[62:65], off
	global_store_dwordx4 v[66:67], v[58:61], off offset:64
	global_store_dwordx4 v[66:67], v[46:49], off offset:512
	global_store_dwordx4 v[66:67], v[42:45], off offset:576
	s_nop 1
	v_lshl_add_u64 v[42:43], v[144:145], 0, s[10:11]
	s_mov_b32 s10, 0x120000
	v_add_co_u32_e32 v44, vcc, s10, v144
	s_mov_b64 s[10:11], 0x140000
	s_nop 0
	v_addc_co_u32_e32 v45, vcc, 0, v145, vcc
	global_store_dwordx4 v[44:45], v[54:57], off
	global_store_dwordx4 v[42:43], v[50:53], off offset:64
	global_store_dwordx4 v[42:43], v[30:33], off offset:512
	global_store_dwordx4 v[42:43], v[26:29], off offset:576
	s_nop 1
	v_lshl_add_u64 v[26:27], v[144:145], 0, s[10:11]
	s_mov_b32 s10, 0x140000
	v_add_co_u32_e32 v28, vcc, s10, v144
	s_mov_b64 s[10:11], 0x160000
	s_nop 0
	v_addc_co_u32_e32 v29, vcc, 0, v145, vcc
	global_store_dwordx4 v[28:29], v[38:41], off
	global_store_dwordx4 v[26:27], v[34:37], off offset:64
	global_store_dwordx4 v[26:27], v[14:17], off offset:512
	global_store_dwordx4 v[26:27], v[10:13], off offset:576
	s_nop 1
	v_add_co_u32_e32 v12, vcc, 0x160000, v144
	v_lshl_add_u64 v[10:11], v[144:145], 0, s[10:11]
	s_nop 0
	v_addc_co_u32_e32 v13, vcc, 0, v145, vcc
	s_and_b64 vcc, exec, s[44:45]
	s_mov_b32 s10, s28
	global_store_dwordx4 v[12:13], v[22:25], off
	global_store_dwordx4 v[10:11], v[18:21], off offset:64
	global_store_dwordx4 v[10:11], v[6:9], off offset:512
	global_store_dwordx4 v[10:11], v[2:5], off offset:576
	s_cbranch_vccz .LBB0_55
	s_waitcnt vmcnt(0)
	s_cmpk_gt_u32 s60, 0xff
	s_cbranch_scc1 .LBB0_62
	s_barrier

.LBB0_73:
	s_add_u32 s38, s46, 0xfff80080
	s_addc_u32 s39, s47, -1
	s_cmp_eq_u32 s73, 28
	s_cselect_b32 s51, s29, s39
	s_cselect_b32 s50, s69, s38
	s_cselect_b32 s49, s27, s72
	s_cselect_b32 s48, s70, s71
	v_lshl_add_u64 v[140:141], s[46:47], 0, v[138:139]
	s_add_i32 m0, s9, 0xc000
	s_nop 0
	global_load_lds_dwordx4 v[140:141], off
	v_lshl_add_u64 v[140:141], s[46:47], 0, v[136:137]
	s_add_i32 m0, s9, 0xe000
	s_nop 0
	global_load_lds_dwordx4 v[140:141], off
	s_add_i32 s74, 0, 0x10000
	v_add_u32_e32 v140, s74, v143
	ds_read_b128 v[146:149], v140
	ds_read_b128 v[150:153], v140 offset:1024
	ds_read_b128 v[154:157], v140 offset:2048
	ds_read_b128 v[160:163], v140 offset:3072
	ds_read_b128 v[164:167], v145
	ds_read_b128 v[168:171], v145 offset:1024
	ds_read_b128 v[172:175], v145 offset:2048
	ds_read_b128 v[176:179], v145 offset:3072
	ds_read_b128 v[180:183], v145 offset:4096
	ds_read_b128 v[184:187], v145 offset:5120
	ds_read_b128 v[188:191], v145 offset:6144
	ds_read_b128 v[192:195], v145 offset:7168
	s_add_i32 s75, 0, 0x14000
	v_add_u32_e32 v140, s75, v143
	ds_read_b128 v[196:199], v140
	ds_read_b128 v[200:203], v140 offset:1024
	ds_read_b128 v[204:207], v140 offset:2048
	ds_read_b128 v[210:213], v140 offset:3072
	s_waitcnt lgkmcnt(0)
	s_barrier
	s_setprio 1
	v_mfma_f32_16x16x32_bf16 v[126:129], v[146:149], v[164:167], v[126:129]
	v_mfma_f32_16x16x32_bf16 v[122:125], v[154:157], v[164:167], v[122:125]
	v_mfma_f32_16x16x32_bf16 v[110:113], v[146:149], v[172:175], v[110:113]
	v_mfma_f32_16x16x32_bf16 v[106:109], v[154:157], v[172:175], v[106:109]
	v_mfma_f32_16x16x32_bf16 v[94:97], v[146:149], v[180:183], v[94:97]
	v_mfma_f32_16x16x32_bf16 v[90:93], v[154:157], v[180:183], v[90:93]
	v_mfma_f32_16x16x32_bf16 v[78:81], v[146:149], v[188:191], v[78:81]
	v_mfma_f32_16x16x32_bf16 v[74:77], v[154:157], v[188:191], v[74:77]
	v_mfma_f32_16x16x32_bf16 v[126:129], v[150:153], v[168:171], v[126:129]
	v_mfma_f32_16x16x32_bf16 v[122:125], v[160:163], v[168:171], v[122:125]
	v_mfma_f32_16x16x32_bf16 v[110:113], v[150:153], v[176:179], v[110:113]
	v_mfma_f32_16x16x32_bf16 v[106:109], v[160:163], v[176:179], v[106:109]
	v_mfma_f32_16x16x32_bf16 v[94:97], v[150:153], v[184:187], v[94:97]
	v_mfma_f32_16x16x32_bf16 v[90:93], v[160:163], v[184:187], v[90:93]
	v_mfma_f32_16x16x32_bf16 v[78:81], v[150:153], v[192:195], v[78:81]
	v_mfma_f32_16x16x32_bf16 v[74:77], v[160:163], v[192:195], v[74:77]
	v_mfma_f32_16x16x32_bf16 v[118:121], v[196:199], v[164:167], v[118:121]
	v_mfma_f32_16x16x32_bf16 v[114:117], v[204:207], v[164:167], v[114:117]
	v_mfma_f32_16x16x32_bf16 v[102:105], v[196:199], v[172:175], v[102:105]
	v_mfma_f32_16x16x32_bf16 v[98:101], v[204:207], v[172:175], v[98:101]
	v_mfma_f32_16x16x32_bf16 v[86:89], v[196:199], v[180:183], v[86:89]
	v_mfma_f32_16x16x32_bf16 v[82:85], v[204:207], v[180:183], v[82:85]
	v_mfma_f32_16x16x32_bf16 v[70:73], v[196:199], v[188:191], v[70:73]
	v_mfma_f32_16x16x32_bf16 v[66:69], v[204:207], v[188:191], v[66:69]
	v_mfma_f32_16x16x32_bf16 v[118:121], v[200:203], v[168:171], v[118:121]
	v_mfma_f32_16x16x32_bf16 v[114:117], v[210:213], v[168:171], v[114:117]
	v_mfma_f32_16x16x32_bf16 v[102:105], v[200:203], v[176:179], v[102:105]
	v_mfma_f32_16x16x32_bf16 v[98:101], v[210:213], v[176:179], v[98:101]
	v_mfma_f32_16x16x32_bf16 v[86:89], v[200:203], v[184:187], v[86:89]
	v_mfma_f32_16x16x32_bf16 v[82:85], v[210:213], v[184:187], v[82:85]
	v_mfma_f32_16x16x32_bf16 v[70:73], v[200:203], v[192:195], v[70:73]
	v_mfma_f32_16x16x32_bf16 v[66:69], v[210:213], v[192:195], v[66:69]
	s_setprio 0
	s_barrier
	s_add_i32 s38, s74, s56
	v_lshl_add_u64 v[140:141], s[48:49], 0, v[0:1]
	s_mov_b32 m0, s38
	v_lshl_add_u64 v[214:215], s[48:49], 0, v[130:131]
	global_load_lds_dwordx4 v[140:141], off
	s_add_i32 m0, s38, 0x2000
	s_nop 0
	global_load_lds_dwordx4 v[214:215], off
	s_mov_b32 m0, s9
	v_lshl_add_u64 v[216:217], s[50:51], 0, v[134:135]
	global_load_lds_dwordx4 v[216:217], off
	v_lshl_add_u64 v[224:225], s[50:51], 0, v[132:133]
	s_mov_b32 m0, s60
	s_nop 0
	global_load_lds_dwordx4 v[224:225], off
	ds_read_b128 v[164:167], v145 offset:16384
	ds_read_b128 v[168:171], v145 offset:17408
	ds_read_b128 v[172:175], v145 offset:18432
	ds_read_b128 v[176:179], v145 offset:19456
	ds_read_b128 v[180:183], v145 offset:20480
	ds_read_b128 v[184:187], v145 offset:21504
	ds_read_b128 v[188:191], v145 offset:22528
	ds_read_b128 v[192:195], v145 offset:23552
	s_waitcnt vmcnt(4)
	s_waitcnt lgkmcnt(0)
	s_barrier
	s_setprio 1
	v_mfma_f32_16x16x32_bf16 v[62:65], v[146:149], v[164:167], v[62:65]
	v_mfma_f32_16x16x32_bf16 v[58:61], v[154:157], v[164:167], v[58:61]
	v_mfma_f32_16x16x32_bf16 v[46:49], v[146:149], v[172:175], v[46:49]
	v_mfma_f32_16x16x32_bf16 v[42:45], v[154:157], v[172:175], v[42:45]
	v_mfma_f32_16x16x32_bf16 v[30:33], v[146:149], v[180:183], v[30:33]
	v_mfma_f32_16x16x32_bf16 v[26:29], v[154:157], v[180:183], v[26:29]
	v_mfma_f32_16x16x32_bf16 v[14:17], v[146:149], v[188:191], v[14:17]
	v_mfma_f32_16x16x32_bf16 v[10:13], v[154:157], v[188:191], v[10:13]
	v_mfma_f32_16x16x32_bf16 v[62:65], v[150:153], v[168:171], v[62:65]
	v_mfma_f32_16x16x32_bf16 v[58:61], v[160:163], v[168:171], v[58:61]
	v_mfma_f32_16x16x32_bf16 v[46:49], v[150:153], v[176:179], v[46:49]
	v_mfma_f32_16x16x32_bf16 v[42:45], v[160:163], v[176:179], v[42:45]
	v_mfma_f32_16x16x32_bf16 v[30:33], v[150:153], v[184:187], v[30:33]
	v_mfma_f32_16x16x32_bf16 v[26:29], v[160:163], v[184:187], v[26:29]
	v_mfma_f32_16x16x32_bf16 v[14:17], v[150:153], v[192:195], v[14:17]
	v_mfma_f32_16x16x32_bf16 v[10:13], v[160:163], v[192:195], v[10:13]
	v_mfma_f32_16x16x32_bf16 v[54:57], v[196:199], v[164:167], v[54:57]
	v_mfma_f32_16x16x32_bf16 v[50:53], v[204:207], v[164:167], v[50:53]
	v_mfma_f32_16x16x32_bf16 v[38:41], v[196:199], v[172:175], v[38:41]
	v_mfma_f32_16x16x32_bf16 v[34:37], v[204:207], v[172:175], v[34:37]
	v_mfma_f32_16x16x32_bf16 v[22:25], v[196:199], v[180:183], v[22:25]
	v_mfma_f32_16x16x32_bf16 v[18:21], v[204:207], v[180:183], v[18:21]
	v_mfma_f32_16x16x32_bf16 v[6:9], v[196:199], v[188:191], v[6:9]
	v_mfma_f32_16x16x32_bf16 v[2:5], v[204:207], v[188:191], v[2:5]
	v_mfma_f32_16x16x32_bf16 v[54:57], v[200:203], v[168:171], v[54:57]
	v_mfma_f32_16x16x32_bf16 v[50:53], v[210:213], v[168:171], v[50:53]
	v_mfma_f32_16x16x32_bf16 v[38:41], v[200:203], v[176:179], v[38:41]
	v_mfma_f32_16x16x32_bf16 v[34:37], v[210:213], v[176:179], v[34:37]
	v_mfma_f32_16x16x32_bf16 v[22:25], v[200:203], v[184:187], v[22:25]
	v_mfma_f32_16x16x32_bf16 v[18:21], v[210:213], v[184:187], v[18:21]
	v_mfma_f32_16x16x32_bf16 v[6:9], v[200:203], v[192:195], v[6:9]
	v_mfma_f32_16x16x32_bf16 v[2:5], v[210:213], v[192:195], v[2:5]
	s_setprio 0
	s_barrier
	s_add_u32 s38, s48, 0x80000
	s_addc_u32 s39, s49, 0
	s_add_i32 s74, s75, s56
	v_lshl_add_u64 v[146:147], s[38:39], 0, v[0:1]
	s_mov_b32 m0, s74
	s_nop 0
	global_load_lds_dwordx4 v[146:147], off
	v_lshl_add_u64 v[146:147], s[38:39], 0, v[130:131]
	s_add_i32 m0, s74, 0x2000
	s_nop 0
	global_load_lds_dwordx4 v[146:147], off
	s_add_u32 s38, s50, 0x80000
	s_addc_u32 s39, s51, 0
	s_mov_b32 m0, s61
	v_lshl_add_u64 v[196:197], s[38:39], 0, v[134:135]
	global_load_lds_dwordx4 v[196:197], off
	v_lshl_add_u64 v[196:197], s[38:39], 0, v[132:133]
	s_mov_b32 m0, s62
	s_nop 0
	global_load_lds_dwordx4 v[196:197], off
	s_add_i32 s74, 0, 0x18000
	v_add_u32_e32 v160, s74, v143
	ds_read_b128 v[146:149], v160
	ds_read_b128 v[150:153], v160 offset:1024
	ds_read_b128 v[154:157], v160 offset:2048
	ds_read_b128 v[160:163], v160 offset:3072
	ds_read_b128 v[164:167], v145 offset:32768
	ds_read_b128 v[168:171], v145 offset:33792
	ds_read_b128 v[172:175], v145 offset:34816
	ds_read_b128 v[176:179], v145 offset:35840
	ds_read_b128 v[180:183], v145 offset:36864
	ds_read_b128 v[184:187], v145 offset:37888
	ds_read_b128 v[188:191], v145 offset:38912
	ds_read_b128 v[192:195], v145 offset:39936
	s_add_i32 s50, 0, 0x1c000
	v_add_u32_e32 v210, s50, v143
	ds_read_b128 v[196:199], v210
	ds_read_b128 v[200:203], v210 offset:1024
	ds_read_b128 v[204:207], v210 offset:2048
	ds_read_b128 v[210:213], v210 offset:3072
	s_waitcnt lgkmcnt(0)
	s_barrier
	s_setprio 1
	v_mfma_f32_16x16x32_bf16 v[126:129], v[146:149], v[164:167], v[126:129]
	v_mfma_f32_16x16x32_bf16 v[122:125], v[154:157], v[164:167], v[122:125]
	v_mfma_f32_16x16x32_bf16 v[110:113], v[146:149], v[172:175], v[110:113]
	v_mfma_f32_16x16x32_bf16 v[106:109], v[154:157], v[172:175], v[106:109]
	v_mfma_f32_16x16x32_bf16 v[94:97], v[146:149], v[180:183], v[94:97]
	v_mfma_f32_16x16x32_bf16 v[90:93], v[154:157], v[180:183], v[90:93]
	v_mfma_f32_16x16x32_bf16 v[78:81], v[146:149], v[188:191], v[78:81]
	v_mfma_f32_16x16x32_bf16 v[74:77], v[154:157], v[188:191], v[74:77]
	v_mfma_f32_16x16x32_bf16 v[126:129], v[150:153], v[168:171], v[126:129]
	v_mfma_f32_16x16x32_bf16 v[122:125], v[160:163], v[168:171], v[122:125]
	v_mfma_f32_16x16x32_bf16 v[110:113], v[150:153], v[176:179], v[110:113]
	v_mfma_f32_16x16x32_bf16 v[106:109], v[160:163], v[176:179], v[106:109]
	v_mfma_f32_16x16x32_bf16 v[94:97], v[150:153], v[184:187], v[94:97]
	v_mfma_f32_16x16x32_bf16 v[90:93], v[160:163], v[184:187], v[90:93]
	v_mfma_f32_16x16x32_bf16 v[78:81], v[150:153], v[192:195], v[78:81]
	v_mfma_f32_16x16x32_bf16 v[74:77], v[160:163], v[192:195], v[74:77]
	v_mfma_f32_16x16x32_bf16 v[118:121], v[196:199], v[164:167], v[118:121]
	v_mfma_f32_16x16x32_bf16 v[114:117], v[204:207], v[164:167], v[114:117]
	v_mfma_f32_16x16x32_bf16 v[102:105], v[196:199], v[172:175], v[102:105]
	v_mfma_f32_16x16x32_bf16 v[98:101], v[204:207], v[172:175], v[98:101]
	v_mfma_f32_16x16x32_bf16 v[86:89], v[196:199], v[180:183], v[86:89]
	v_mfma_f32_16x16x32_bf16 v[82:85], v[204:207], v[180:183], v[82:85]
	v_mfma_f32_16x16x32_bf16 v[70:73], v[196:199], v[188:191], v[70:73]
	v_mfma_f32_16x16x32_bf16 v[66:69], v[204:207], v[188:191], v[66:69]
	v_mfma_f32_16x16x32_bf16 v[118:121], v[200:203], v[168:171], v[118:121]
	v_mfma_f32_16x16x32_bf16 v[114:117], v[210:213], v[168:171], v[114:117]
	v_mfma_f32_16x16x32_bf16 v[102:105], v[200:203], v[176:179], v[102:105]
	v_mfma_f32_16x16x32_bf16 v[98:101], v[210:213], v[176:179], v[98:101]
	v_mfma_f32_16x16x32_bf16 v[86:89], v[200:203], v[184:187], v[86:89]
	v_mfma_f32_16x16x32_bf16 v[82:85], v[210:213], v[184:187], v[82:85]
	v_mfma_f32_16x16x32_bf16 v[70:73], v[200:203], v[192:195], v[70:73]
	v_mfma_f32_16x16x32_bf16 v[66:69], v[210:213], v[192:195], v[66:69]
	s_setprio 0
	s_barrier
	s_add_i32 s38, s74, s56
	v_lshl_add_u64 v[140:141], v[140:141], 0, s[36:37]
	s_mov_b32 m0, s38
	s_nop 0
	global_load_lds_dwordx4 v[140:141], off
	v_lshl_add_u64 v[140:141], v[214:215], 0, s[36:37]
	s_add_i32 m0, s38, 0x2000
	s_nop 0
	global_load_lds_dwordx4 v[140:141], off
	s_mov_b32 m0, s64
	v_lshl_add_u64 v[140:141], v[216:217], 0, s[36:37]
	global_load_lds_dwordx4 v[140:141], off
	v_lshl_add_u64 v[140:141], v[224:225], 0, s[36:37]
	s_mov_b32 m0, s65
	s_nop 0
	global_load_lds_dwordx4 v[140:141], off
	ds_read_b128 v[164:167], v145 offset:49152
	ds_read_b128 v[168:171], v145 offset:50176
	ds_read_b128 v[172:175], v145 offset:51200
	ds_read_b128 v[176:179], v145 offset:52224
	ds_read_b128 v[180:183], v145 offset:53248
	ds_read_b128 v[184:187], v145 offset:54272
	ds_read_b128 v[188:191], v145 offset:55296
	ds_read_b128 v[192:195], v145 offset:56320
	s_waitcnt vmcnt(4)
	s_waitcnt lgkmcnt(0)
	s_barrier
	s_setprio 1
	v_mfma_f32_16x16x32_bf16 v[62:65], v[146:149], v[164:167], v[62:65]
	v_mfma_f32_16x16x32_bf16 v[58:61], v[154:157], v[164:167], v[58:61]
	v_mfma_f32_16x16x32_bf16 v[46:49], v[146:149], v[172:175], v[46:49]
	v_mfma_f32_16x16x32_bf16 v[42:45], v[154:157], v[172:175], v[42:45]
	v_mfma_f32_16x16x32_bf16 v[30:33], v[146:149], v[180:183], v[30:33]
	v_mfma_f32_16x16x32_bf16 v[26:29], v[154:157], v[180:183], v[26:29]
	v_mfma_f32_16x16x32_bf16 v[14:17], v[146:149], v[188:191], v[14:17]
	v_mfma_f32_16x16x32_bf16 v[10:13], v[154:157], v[188:191], v[10:13]
	v_mfma_f32_16x16x32_bf16 v[62:65], v[150:153], v[168:171], v[62:65]
	v_mfma_f32_16x16x32_bf16 v[58:61], v[160:163], v[168:171], v[58:61]
	v_mfma_f32_16x16x32_bf16 v[46:49], v[150:153], v[176:179], v[46:49]
	v_mfma_f32_16x16x32_bf16 v[42:45], v[160:163], v[176:179], v[42:45]
	v_mfma_f32_16x16x32_bf16 v[30:33], v[150:153], v[184:187], v[30:33]
	v_mfma_f32_16x16x32_bf16 v[26:29], v[160:163], v[184:187], v[26:29]
	v_mfma_f32_16x16x32_bf16 v[14:17], v[150:153], v[192:195], v[14:17]
	v_mfma_f32_16x16x32_bf16 v[10:13], v[160:163], v[192:195], v[10:13]
	s_add_u32 s38, s48, 0x80080
	s_addc_u32 s39, s49, 0
	s_add_i32 s48, s50, s56
	v_lshl_add_u64 v[140:141], s[38:39], 0, v[0:1]
	s_mov_b32 m0, s48
	s_nop 0
	global_load_lds_dwordx4 v[140:141], off
	v_lshl_add_u64 v[140:141], s[38:39], 0, v[130:131]
	s_add_i32 m0, s48, 0x2000
	s_nop 0
	global_load_lds_dwordx4 v[140:141], off
	v_mfma_f32_16x16x32_bf16 v[54:57], v[196:199], v[164:167], v[54:57]
	v_mfma_f32_16x16x32_bf16 v[50:53], v[204:207], v[164:167], v[50:53]
	v_mfma_f32_16x16x32_bf16 v[38:41], v[196:199], v[172:175], v[38:41]
	v_mfma_f32_16x16x32_bf16 v[34:37], v[204:207], v[172:175], v[34:37]
	v_mfma_f32_16x16x32_bf16 v[22:25], v[196:199], v[180:183], v[22:25]
	v_mfma_f32_16x16x32_bf16 v[18:21], v[204:207], v[180:183], v[18:21]
	v_mfma_f32_16x16x32_bf16 v[6:9], v[196:199], v[188:191], v[6:9]
	v_mfma_f32_16x16x32_bf16 v[2:5], v[204:207], v[188:191], v[2:5]
	v_mfma_f32_16x16x32_bf16 v[54:57], v[200:203], v[168:171], v[54:57]
	v_mfma_f32_16x16x32_bf16 v[50:53], v[210:213], v[168:171], v[50:53]
	v_mfma_f32_16x16x32_bf16 v[38:41], v[200:203], v[176:179], v[38:41]
	v_mfma_f32_16x16x32_bf16 v[34:37], v[210:213], v[176:179], v[34:37]
	v_mfma_f32_16x16x32_bf16 v[22:25], v[200:203], v[184:187], v[22:25]
	v_mfma_f32_16x16x32_bf16 v[18:21], v[210:213], v[184:187], v[18:21]
	v_mfma_f32_16x16x32_bf16 v[6:9], v[200:203], v[192:195], v[6:9]
	v_mfma_f32_16x16x32_bf16 v[2:5], v[210:213], v[192:195], v[2:5]
	s_setprio 0
	s_add_i32 s73, s73, 2
	s_add_u32 s71, s71, 0x100
	s_addc_u32 s72, s72, 0
	s_add_u32 s46, s46, 0x100
	s_addc_u32 s47, s47, 0
	s_cmp_gt_u32 s73, 29
	s_barrier
	s_cbranch_scc0 .LBB0_73
	v_lshl_add_u32 v146, s8, 8, v142
	v_max_f32_e32 v122, v122, v122
	v_ashrrev_i32_e32 v147, 31, v146
	v_max_f32_e32 v122, 0, v122
	v_max_f32_e32 v123, v123, v123
	v_max_f32_e32 v124, v124, v124
	v_lshl_or_b32 v140, s68, 8, v144
	v_lshlrev_b64 v[148:149], 14, v[146:147]
	v_mul_f32_e32 v147, v122, v122
	v_max_f32_e32 v122, v127, v127
	v_max_f32_e32 v123, 0, v123
	v_max_f32_e32 v124, 0, v124
	v_ashrrev_i32_e32 v141, 31, v140
	v_max_f32_e32 v126, v126, v126
	v_max_f32_e32 v122, 0, v122
	v_mul_f32_e32 v127, v123, v123
	v_max_f32_e32 v123, v128, v128
	v_mul_f32_e32 v128, v124, v124
	v_max_f32_e32 v124, v129, v129
	v_max_f32_e32 v125, v125, v125
	v_lshl_add_u64 v[148:149], s[24:25], 0, v[148:149]
	v_lshlrev_b64 v[150:151], 1, v[140:141]
	v_max_f32_e32 v126, 0, v126
	v_mul_f32_e32 v122, v122, v122
	v_max_f32_e32 v123, 0, v123
	v_max_f32_e32 v124, 0, v124
	v_max_f32_e32 v125, 0, v125
	v_max_f32_e32 v114, v114, v114
	v_lshl_add_u64 v[140:141], v[148:149], 0, v[150:151]
	v_mul_f32_e32 v126, v126, v126
	v_mul_f32_e32 v123, v123, v123
	v_mul_f32_e32 v124, v124, v124
	v_mul_f32_e32 v125, v125, v125
	v_cvt_pk_bf16_f32 v122, v126, v122
	v_max_f32_e32 v114, 0, v114
	v_max_f32_e32 v115, v115, v115
	v_max_f32_e32 v116, v116, v116
	v_cvt_pk_bf16_f32 v123, v123, v124
	v_cvt_pk_bf16_f32 v124, v147, v127
	v_cvt_pk_bf16_f32 v125, v128, v125
	global_store_dwordx4 v[140:141], v[122:125], off nt
	v_max_f32_e32 v115, 0, v115
	v_max_f32_e32 v116, 0, v116
	v_mul_f32_e32 v122, v114, v114
	v_max_f32_e32 v114, v119, v119
	v_max_f32_e32 v118, v118, v118
	v_max_f32_e32 v114, 0, v114
	v_mul_f32_e32 v119, v115, v115
	v_max_f32_e32 v115, v120, v120
	v_mul_f32_e32 v120, v116, v116
	v_max_f32_e32 v116, v121, v121
	v_max_f32_e32 v117, v117, v117
	v_max_f32_e32 v118, 0, v118
	v_mul_f32_e32 v114, v114, v114
	v_max_f32_e32 v115, 0, v115
	v_max_f32_e32 v116, 0, v116
	v_max_f32_e32 v117, 0, v117
	v_mul_f32_e32 v118, v118, v118
	v_mul_f32_e32 v115, v115, v115
	v_mul_f32_e32 v116, v116, v116
	v_mul_f32_e32 v117, v117, v117
	v_cvt_pk_bf16_f32 v114, v118, v114
	v_max_f32_e32 v106, v106, v106
	v_cvt_pk_bf16_f32 v115, v115, v116
	v_cvt_pk_bf16_f32 v116, v122, v119
	v_cvt_pk_bf16_f32 v117, v120, v117
	global_store_dwordx4 v[140:141], v[114:117], off offset:256 nt
	v_max_f32_e32 v106, 0, v106
	v_max_f32_e32 v107, v107, v107
	v_or_b32_e32 v114, 16, v146
	v_max_f32_e32 v108, v108, v108
	v_ashrrev_i32_e32 v115, 31, v114
	v_mul_f32_e32 v116, v106, v106
	v_max_f32_e32 v106, v111, v111
	v_max_f32_e32 v107, 0, v107
	v_max_f32_e32 v108, 0, v108
	v_lshlrev_b64 v[114:115], 14, v[114:115]
	v_max_f32_e32 v110, v110, v110
	v_max_f32_e32 v106, 0, v106
	v_mul_f32_e32 v111, v107, v107
	v_max_f32_e32 v107, v112, v112
	v_mul_f32_e32 v112, v108, v108
	v_max_f32_e32 v108, v113, v113
	v_max_f32_e32 v109, v109, v109
	v_lshl_add_u64 v[114:115], s[24:25], 0, v[114:115]
	v_max_f32_e32 v110, 0, v110
	v_mul_f32_e32 v106, v106, v106
	v_max_f32_e32 v107, 0, v107
	v_max_f32_e32 v108, 0, v108
	v_max_f32_e32 v109, 0, v109
	v_max_f32_e32 v98, v98, v98
	v_lshl_add_u64 v[114:115], v[114:115], 0, v[150:151]
	v_mul_f32_e32 v110, v110, v110
	v_mul_f32_e32 v107, v107, v107
	v_mul_f32_e32 v108, v108, v108
	v_mul_f32_e32 v109, v109, v109
	v_cvt_pk_bf16_f32 v106, v110, v106
	v_max_f32_e32 v98, 0, v98
	v_max_f32_e32 v99, v99, v99
	v_max_f32_e32 v100, v100, v100
	v_cvt_pk_bf16_f32 v107, v107, v108
	v_cvt_pk_bf16_f32 v108, v116, v111
	v_cvt_pk_bf16_f32 v109, v112, v109
	global_store_dwordx4 v[114:115], v[106:109], off nt
	v_max_f32_e32 v99, 0, v99
	v_max_f32_e32 v100, 0, v100
	v_mul_f32_e32 v106, v98, v98
	v_max_f32_e32 v98, v103, v103
	v_max_f32_e32 v102, v102, v102
	v_max_f32_e32 v98, 0, v98
	v_mul_f32_e32 v103, v99, v99
	v_max_f32_e32 v99, v104, v104
	v_mul_f32_e32 v104, v100, v100
	v_max_f32_e32 v100, v105, v105
	v_max_f32_e32 v101, v101, v101
	v_max_f32_e32 v102, 0, v102
	v_mul_f32_e32 v98, v98, v98
	v_max_f32_e32 v99, 0, v99
	v_max_f32_e32 v100, 0, v100
	v_max_f32_e32 v101, 0, v101
	v_mul_f32_e32 v102, v102, v102
	v_mul_f32_e32 v99, v99, v99
	v_mul_f32_e32 v100, v100, v100
	v_mul_f32_e32 v101, v101, v101
	v_cvt_pk_bf16_f32 v98, v102, v98
	v_max_f32_e32 v90, v90, v90
	v_cvt_pk_bf16_f32 v99, v99, v100
	v_cvt_pk_bf16_f32 v100, v106, v103
	v_cvt_pk_bf16_f32 v101, v104, v101
	global_store_dwordx4 v[114:115], v[98:101], off offset:256 nt
	v_max_f32_e32 v90, 0, v90
	v_max_f32_e32 v91, v91, v91
	v_or_b32_e32 v98, 32, v146
	v_max_f32_e32 v92, v92, v92
	v_ashrrev_i32_e32 v99, 31, v98
	v_mul_f32_e32 v100, v90, v90
	v_max_f32_e32 v90, v95, v95
	v_max_f32_e32 v91, 0, v91
	v_max_f32_e32 v92, 0, v92
	v_lshlrev_b64 v[98:99], 14, v[98:99]
	v_max_f32_e32 v94, v94, v94
	v_max_f32_e32 v90, 0, v90
	v_mul_f32_e32 v95, v91, v91
	v_max_f32_e32 v91, v96, v96
	v_mul_f32_e32 v96, v92, v92
	v_max_f32_e32 v92, v97, v97
	v_max_f32_e32 v93, v93, v93
	v_lshl_add_u64 v[98:99], s[24:25], 0, v[98:99]
	v_max_f32_e32 v94, 0, v94
	v_mul_f32_e32 v90, v90, v90
	v_max_f32_e32 v91, 0, v91
	v_max_f32_e32 v92, 0, v92
	v_max_f32_e32 v93, 0, v93
	v_max_f32_e32 v82, v82, v82
	v_lshl_add_u64 v[98:99], v[98:99], 0, v[150:151]
	v_mul_f32_e32 v94, v94, v94
	v_mul_f32_e32 v91, v91, v91
	v_mul_f32_e32 v92, v92, v92
	v_mul_f32_e32 v93, v93, v93
	v_cvt_pk_bf16_f32 v90, v94, v90
	v_max_f32_e32 v82, 0, v82
	v_max_f32_e32 v83, v83, v83
	v_max_f32_e32 v84, v84, v84
	v_cvt_pk_bf16_f32 v91, v91, v92
	v_cvt_pk_bf16_f32 v92, v100, v95
	v_cvt_pk_bf16_f32 v93, v96, v93
	global_store_dwordx4 v[98:99], v[90:93], off nt
	v_max_f32_e32 v83, 0, v83
	v_max_f32_e32 v84, 0, v84
	v_mul_f32_e32 v90, v82, v82
	v_max_f32_e32 v82, v87, v87
	v_max_f32_e32 v86, v86, v86
	v_max_f32_e32 v82, 0, v82
	v_mul_f32_e32 v87, v83, v83
	v_max_f32_e32 v83, v88, v88
	v_mul_f32_e32 v88, v84, v84
	v_max_f32_e32 v84, v89, v89
	v_max_f32_e32 v85, v85, v85
	v_max_f32_e32 v86, 0, v86
	v_mul_f32_e32 v82, v82, v82
	v_max_f32_e32 v83, 0, v83
	v_max_f32_e32 v84, 0, v84
	v_max_f32_e32 v85, 0, v85
	v_mul_f32_e32 v86, v86, v86
	v_mul_f32_e32 v83, v83, v83
	v_mul_f32_e32 v84, v84, v84
	v_mul_f32_e32 v85, v85, v85
	v_cvt_pk_bf16_f32 v82, v86, v82
	v_max_f32_e32 v74, v74, v74
	v_cvt_pk_bf16_f32 v83, v83, v84
	v_cvt_pk_bf16_f32 v84, v90, v87
	v_cvt_pk_bf16_f32 v85, v88, v85
	global_store_dwordx4 v[98:99], v[82:85], off offset:256 nt
	v_max_f32_e32 v74, 0, v74
	v_max_f32_e32 v75, v75, v75
	v_or_b32_e32 v82, 48, v146
	v_max_f32_e32 v76, v76, v76
	v_ashrrev_i32_e32 v83, 31, v82
	v_mul_f32_e32 v84, v74, v74
	v_max_f32_e32 v74, v79, v79
	v_max_f32_e32 v75, 0, v75
	v_max_f32_e32 v76, 0, v76
	v_lshlrev_b64 v[82:83], 14, v[82:83]
	v_max_f32_e32 v78, v78, v78
	v_max_f32_e32 v74, 0, v74
	v_mul_f32_e32 v79, v75, v75
	v_max_f32_e32 v75, v80, v80
	v_mul_f32_e32 v80, v76, v76
	v_max_f32_e32 v76, v81, v81
	v_max_f32_e32 v77, v77, v77
	v_lshl_add_u64 v[82:83], s[24:25], 0, v[82:83]
	v_max_f32_e32 v78, 0, v78
	v_mul_f32_e32 v74, v74, v74
	v_max_f32_e32 v75, 0, v75
	v_max_f32_e32 v76, 0, v76
	v_max_f32_e32 v77, 0, v77
	v_max_f32_e32 v66, v66, v66
	v_max_f32_e32 v67, v67, v67
	v_max_f32_e32 v68, v68, v68
	v_lshl_add_u64 v[82:83], v[82:83], 0, v[150:151]
	v_mul_f32_e32 v78, v78, v78
	v_mul_f32_e32 v75, v75, v75
	v_mul_f32_e32 v76, v76, v76
	v_mul_f32_e32 v77, v77, v77
	v_cvt_pk_bf16_f32 v74, v78, v74
	v_max_f32_e32 v66, 0, v66
	v_max_f32_e32 v67, 0, v67
	v_max_f32_e32 v68, 0, v68
	v_cvt_pk_bf16_f32 v75, v75, v76
	v_cvt_pk_bf16_f32 v76, v84, v79
	v_cvt_pk_bf16_f32 v77, v80, v77
	global_store_dwordx4 v[82:83], v[74:77], off nt
	v_max_f32_e32 v69, v69, v69
	v_max_f32_e32 v70, v70, v70
	v_mul_f32_e32 v74, v66, v66
	v_max_f32_e32 v66, v71, v71
	v_mul_f32_e32 v71, v67, v67
	v_max_f32_e32 v67, v72, v72
	v_mul_f32_e32 v72, v68, v68
	v_max_f32_e32 v68, v73, v73
	v_max_f32_e32 v67, 0, v67
	v_max_f32_e32 v68, 0, v68
	v_max_f32_e32 v66, 0, v66
	v_mul_f32_e32 v67, v67, v67
	v_max_f32_e32 v69, 0, v69
	v_mul_f32_e32 v68, v68, v68
	v_max_f32_e32 v58, v58, v58
	v_max_f32_e32 v70, 0, v70
	v_mul_f32_e32 v66, v66, v66
	v_mul_f32_e32 v69, v69, v69
	v_cvt_pk_bf16_f32 v67, v67, v68
	v_cvt_pk_bf16_f32 v68, v74, v71
	v_max_f32_e32 v58, 0, v58
	v_max_f32_e32 v59, v59, v59
	v_max_f32_e32 v60, v60, v60
	v_mul_f32_e32 v70, v70, v70
	v_cvt_pk_bf16_f32 v66, v70, v66
	v_cvt_pk_bf16_f32 v69, v72, v69
	global_store_dwordx4 v[82:83], v[66:69], off offset:256 nt
	v_max_f32_e32 v62, v62, v62
	v_max_f32_e32 v59, 0, v59
	v_mul_f32_e32 v68, v58, v58
	v_max_f32_e32 v58, v63, v63
	v_max_f32_e32 v60, 0, v60
	v_max_f32_e32 v62, 0, v62
	v_max_f32_e32 v58, 0, v58
	v_mul_f32_e32 v63, v59, v59
	v_max_f32_e32 v59, v64, v64
	v_mul_f32_e32 v64, v60, v60
	v_max_f32_e32 v60, v65, v65
	v_mul_f32_e32 v62, v62, v62
	v_mul_f32_e32 v58, v58, v58
	v_max_f32_e32 v59, 0, v59
	v_max_f32_e32 v60, 0, v60
	v_max_f32_e32 v61, v61, v61
	s_mov_b32 s8, 0x200000
	v_mul_f32_e32 v59, v59, v59
	v_max_f32_e32 v61, 0, v61
	v_mul_f32_e32 v60, v60, v60
	v_cvt_pk_bf16_f32 v58, v62, v58
	v_add_co_u32_e32 v62, vcc, s8, v140
	v_max_f32_e32 v50, v50, v50
	v_max_f32_e32 v51, v51, v51
	v_max_f32_e32 v52, v52, v52
	v_mul_f32_e32 v61, v61, v61
	v_cvt_pk_bf16_f32 v59, v59, v60
	v_cvt_pk_bf16_f32 v60, v68, v63
	v_addc_co_u32_e32 v63, vcc, 0, v141, vcc
	v_max_f32_e32 v50, 0, v50
	v_max_f32_e32 v51, 0, v51
	v_max_f32_e32 v52, 0, v52
	v_cvt_pk_bf16_f32 v61, v64, v61
	global_store_dwordx4 v[62:63], v[58:61], off nt
	v_max_f32_e32 v53, v53, v53
	s_mov_b64 s[38:39], 0x200000
	v_mul_f32_e32 v58, v50, v50
	v_max_f32_e32 v50, v55, v55
	v_mul_f32_e32 v55, v51, v51
	v_max_f32_e32 v51, v56, v56
	v_mul_f32_e32 v56, v52, v52
	v_max_f32_e32 v52, v57, v57
	v_max_f32_e32 v51, 0, v51
	v_max_f32_e32 v52, 0, v52
	v_max_f32_e32 v54, v54, v54
	v_max_f32_e32 v50, 0, v50
	v_mul_f32_e32 v51, v51, v51
	v_max_f32_e32 v53, 0, v53
	v_mul_f32_e32 v52, v52, v52
	v_max_f32_e32 v42, v42, v42
	v_lshl_add_u64 v[66:67], v[140:141], 0, s[38:39]
	v_max_f32_e32 v54, 0, v54
	v_mul_f32_e32 v50, v50, v50
	v_mul_f32_e32 v53, v53, v53
	v_cvt_pk_bf16_f32 v51, v51, v52
	v_cvt_pk_bf16_f32 v52, v58, v55
	v_max_f32_e32 v42, 0, v42
	v_max_f32_e32 v43, v43, v43
	v_max_f32_e32 v44, v44, v44
	v_mul_f32_e32 v54, v54, v54
	v_cvt_pk_bf16_f32 v50, v54, v50
	v_cvt_pk_bf16_f32 v53, v56, v53
	global_store_dwordx4 v[66:67], v[50:53], off offset:256 nt
	v_max_f32_e32 v46, v46, v46
	v_max_f32_e32 v43, 0, v43
	v_mul_f32_e32 v52, v42, v42
	v_max_f32_e32 v42, v47, v47
	v_max_f32_e32 v44, 0, v44
	v_max_f32_e32 v46, 0, v46
	v_max_f32_e32 v42, 0, v42
	v_mul_f32_e32 v47, v43, v43
	v_max_f32_e32 v43, v48, v48
	v_mul_f32_e32 v48, v44, v44
	v_max_f32_e32 v44, v49, v49
	v_mul_f32_e32 v46, v46, v46
	v_mul_f32_e32 v42, v42, v42
	v_max_f32_e32 v43, 0, v43
	v_max_f32_e32 v44, 0, v44
	v_max_f32_e32 v45, v45, v45
	s_mov_b32 s8, 0x240000
	v_mul_f32_e32 v43, v43, v43
	v_max_f32_e32 v45, 0, v45
	v_mul_f32_e32 v44, v44, v44
	v_cvt_pk_bf16_f32 v42, v46, v42
	v_add_co_u32_e32 v46, vcc, s8, v140
	v_max_f32_e32 v34, v34, v34
	v_max_f32_e32 v35, v35, v35
	v_max_f32_e32 v36, v36, v36
	v_mul_f32_e32 v45, v45, v45
	v_cvt_pk_bf16_f32 v43, v43, v44
	v_cvt_pk_bf16_f32 v44, v52, v47
	v_addc_co_u32_e32 v47, vcc, 0, v141, vcc
	v_max_f32_e32 v34, 0, v34
	v_max_f32_e32 v35, 0, v35
	v_max_f32_e32 v36, 0, v36
	v_cvt_pk_bf16_f32 v45, v48, v45
	global_store_dwordx4 v[46:47], v[42:45], off nt
	v_max_f32_e32 v37, v37, v37
	s_mov_b64 s[38:39], 0x240000
	v_mul_f32_e32 v42, v34, v34
	v_max_f32_e32 v34, v39, v39
	v_mul_f32_e32 v39, v35, v35
	v_max_f32_e32 v35, v40, v40
	v_mul_f32_e32 v40, v36, v36
	v_max_f32_e32 v36, v41, v41
	v_max_f32_e32 v35, 0, v35
	v_max_f32_e32 v36, 0, v36
	v_max_f32_e32 v38, v38, v38
	v_max_f32_e32 v34, 0, v34
	v_mul_f32_e32 v35, v35, v35
	v_max_f32_e32 v37, 0, v37
	v_mul_f32_e32 v36, v36, v36
	v_max_f32_e32 v26, v26, v26
	v_lshl_add_u64 v[50:51], v[140:141], 0, s[38:39]
	v_max_f32_e32 v38, 0, v38
	v_mul_f32_e32 v34, v34, v34
	v_mul_f32_e32 v37, v37, v37
	v_cvt_pk_bf16_f32 v35, v35, v36
	v_cvt_pk_bf16_f32 v36, v42, v39
	v_max_f32_e32 v26, 0, v26
	v_max_f32_e32 v27, v27, v27
	v_max_f32_e32 v28, v28, v28
	v_mul_f32_e32 v38, v38, v38
	v_cvt_pk_bf16_f32 v34, v38, v34
	v_cvt_pk_bf16_f32 v37, v40, v37
	global_store_dwordx4 v[50:51], v[34:37], off offset:256 nt
	v_max_f32_e32 v30, v30, v30
	v_max_f32_e32 v27, 0, v27
	v_mul_f32_e32 v36, v26, v26
	v_max_f32_e32 v26, v31, v31
	v_max_f32_e32 v28, 0, v28
	v_max_f32_e32 v30, 0, v30
; __device__ __forceinline__ unsigned cvt_pk_bf16(float lo, float hi) { unsigned r; asm("v_cvt_pk_bf16_f32 %0, %1, %2" : "=v"(r) : "v"(lo), "v"(hi)); return r; }
; #define PG8_WAIT_V(n) asm volatile("s_waitcnt vmcnt(" #n ")" ::: "memory")
; #define PG8_BAR __builtin_amdgcn_s_barrier()
;     __device__ __forceinline__ void operator()(const f32x4 (&acc)[2][2][4][2], const Unit& u, int wr, int wc, int fr, int fq) const {
;     ...
;                 for (int bj = 0; bj < 2; ++bj) { f32x4 v0 = acc[ai][bj][m][0], v1 = acc[ai][bj][m][1];
;                     if (ACT == 1) {
; #pragma unroll
;                         for (int j = 0; j < 4; ++j) { float a = fmaxf(v0[j], 0.f), b = fmaxf(v1[j], 0.f); v0[j] = a * a; v1[j] = b * b; } }
;                     u32x4 w; w.x = cvt_pk_bf16(v0[0], v0[1]); w.y = cvt_pk_bf16(v0[2], v0[3]); w.z = cvt_pk_bf16(v1[0], v1[1]); w.w = cvt_pk_bf16(v1[2], v1[3]);
;                     if (ACT == 1) __builtin_nontemporal_store(w, (u32x4*)(rowp + bj * HALF));
;                     else *(u32x4*)(rowp + bj * HALF) = w; } }
; template <class Epi, class Sched>
; __device__ __forceinline__ void gemm_phase(LAS unsigned char* lds, const Gemm g, const Sched& S, const Epi& E) {
;     ...
;         if (!has_next) break;
; #pragma unroll
;         for (int a = 0; a < 2; ++a)
; #pragma unroll
;             for (int b = 0; b < 2; ++b)
; #pragma unroll
;                 for (int m = 0; m < 4; ++m)
; #pragma unroll
;                     for (int n = 0; n < 2; ++n) acc[a][b][m][n] = (f32x4){0.f, 0.f, 0.f, 0.f};
;         cur = nxt; cA = nA; cB = nB; ++ui;
;     }
;     PG8_WAIT_V(0);
;     if (wr == 0) PG8_BAR;
;     PG8_BAR;
	v_max_f32_e32 v26, 0, v26
	v_mul_f32_e32 v31, v27, v27
	v_max_f32_e32 v27, v32, v32
	v_mul_f32_e32 v32, v28, v28
	v_max_f32_e32 v28, v33, v33
	v_mul_f32_e32 v30, v30, v30
	v_mul_f32_e32 v26, v26, v26
	v_max_f32_e32 v27, 0, v27
	v_max_f32_e32 v28, 0, v28
	v_max_f32_e32 v29, v29, v29
	s_mov_b32 s8, 0x280000
	v_mul_f32_e32 v27, v27, v27
	v_max_f32_e32 v29, 0, v29
	v_mul_f32_e32 v28, v28, v28
	v_cvt_pk_bf16_f32 v26, v30, v26
	v_add_co_u32_e32 v30, vcc, s8, v140
	v_max_f32_e32 v18, v18, v18
	v_max_f32_e32 v19, v19, v19
	v_max_f32_e32 v20, v20, v20
	v_mul_f32_e32 v29, v29, v29
	v_cvt_pk_bf16_f32 v27, v27, v28
	v_cvt_pk_bf16_f32 v28, v36, v31
	v_addc_co_u32_e32 v31, vcc, 0, v141, vcc
	v_max_f32_e32 v18, 0, v18
	v_max_f32_e32 v19, 0, v19
	v_max_f32_e32 v20, 0, v20
	v_cvt_pk_bf16_f32 v29, v32, v29
	global_store_dwordx4 v[30:31], v[26:29], off nt
	v_max_f32_e32 v21, v21, v21
	s_mov_b64 s[38:39], 0x280000
	v_mul_f32_e32 v26, v18, v18
	v_max_f32_e32 v18, v23, v23
	v_mul_f32_e32 v23, v19, v19
	v_max_f32_e32 v19, v24, v24
	v_mul_f32_e32 v24, v20, v20
	v_max_f32_e32 v20, v25, v25
	v_max_f32_e32 v19, 0, v19
	v_max_f32_e32 v20, 0, v20
	v_max_f32_e32 v22, v22, v22
	v_max_f32_e32 v18, 0, v18
	v_mul_f32_e32 v19, v19, v19
	v_max_f32_e32 v21, 0, v21
	v_mul_f32_e32 v20, v20, v20
	v_max_f32_e32 v10, v10, v10
	v_lshl_add_u64 v[34:35], v[140:141], 0, s[38:39]
	v_max_f32_e32 v22, 0, v22
	v_mul_f32_e32 v18, v18, v18
	v_mul_f32_e32 v21, v21, v21
	v_cvt_pk_bf16_f32 v19, v19, v20
	v_cvt_pk_bf16_f32 v20, v26, v23
	v_max_f32_e32 v10, 0, v10
	v_max_f32_e32 v11, v11, v11
	v_max_f32_e32 v12, v12, v12
	v_mul_f32_e32 v22, v22, v22
	v_cvt_pk_bf16_f32 v18, v22, v18
	v_cvt_pk_bf16_f32 v21, v24, v21
	global_store_dwordx4 v[34:35], v[18:21], off offset:256 nt
	v_max_f32_e32 v14, v14, v14
	v_max_f32_e32 v11, 0, v11
	v_mul_f32_e32 v20, v10, v10
	v_max_f32_e32 v10, v15, v15
	v_max_f32_e32 v12, 0, v12
	v_max_f32_e32 v14, 0, v14
	v_max_f32_e32 v10, 0, v10
	v_mul_f32_e32 v15, v11, v11
	v_max_f32_e32 v11, v16, v16
	v_mul_f32_e32 v16, v12, v12
	v_max_f32_e32 v12, v17, v17
	v_mul_f32_e32 v14, v14, v14
	v_mul_f32_e32 v10, v10, v10
	v_max_f32_e32 v11, 0, v11
	v_max_f32_e32 v12, 0, v12
	v_max_f32_e32 v13, v13, v13
	s_mov_b32 s8, 0x2c0000
	v_mul_f32_e32 v11, v11, v11
	v_max_f32_e32 v13, 0, v13
	v_mul_f32_e32 v12, v12, v12
	v_cvt_pk_bf16_f32 v10, v14, v10
	v_add_co_u32_e32 v14, vcc, s8, v140
	v_max_f32_e32 v2, v2, v2
	v_max_f32_e32 v3, v3, v3
	v_max_f32_e32 v4, v4, v4
	v_mul_f32_e32 v13, v13, v13
	v_cvt_pk_bf16_f32 v11, v11, v12
	v_cvt_pk_bf16_f32 v12, v20, v15
	v_addc_co_u32_e32 v15, vcc, 0, v141, vcc
	v_max_f32_e32 v2, 0, v2
	v_max_f32_e32 v3, 0, v3
	v_max_f32_e32 v4, 0, v4
	v_cvt_pk_bf16_f32 v13, v16, v13
	global_store_dwordx4 v[14:15], v[10:13], off nt
	v_max_f32_e32 v5, v5, v5
	s_mov_b64 s[38:39], 0x2c0000
	v_mul_f32_e32 v10, v2, v2
	v_max_f32_e32 v2, v7, v7
	v_mul_f32_e32 v7, v3, v3
	v_max_f32_e32 v3, v8, v8
	v_mul_f32_e32 v8, v4, v4
	v_max_f32_e32 v4, v9, v9
	v_max_f32_e32 v6, v6, v6
	v_max_f32_e32 v2, 0, v2
	v_max_f32_e32 v3, 0, v3
	v_max_f32_e32 v4, 0, v4
	v_max_f32_e32 v5, 0, v5
	v_lshl_add_u64 v[18:19], v[140:141], 0, s[38:39]
	v_max_f32_e32 v6, 0, v6
	v_mul_f32_e32 v2, v2, v2
	v_mul_f32_e32 v3, v3, v3
	v_mul_f32_e32 v4, v4, v4
	v_mul_f32_e32 v5, v5, v5
	s_and_b64 vcc, exec, s[40:41]
	s_mov_b32 s68, s26
	s_mov_b32 s8, s28
	s_mov_b64 s[46:47], s[44:45]
	s_mov_b64 s[48:49], s[42:43]
	v_mul_f32_e32 v6, v6, v6
	v_cvt_pk_bf16_f32 v2, v6, v2
	v_cvt_pk_bf16_f32 v3, v3, v4
	v_cvt_pk_bf16_f32 v4, v10, v7
	v_cvt_pk_bf16_f32 v5, v8, v5
	global_store_dwordx4 v[18:19], v[2:5], off offset:256 nt
	s_cbranch_vccz .LBB0_70
	s_waitcnt vmcnt(0)
	s_cmpk_gt_u32 s52, 0xff
	s_cbranch_scc1 .LBB0_77
	s_barrier

; #define PG8_STAGE(bufoff, gbase, voff) do { _Pragma("unroll") for (int _i = 0; _i < 2; ++_i) \
;         __builtin_amdgcn_global_load_lds((const unsigned*)((const char*)(gbase) + (voff)[_i]), (LAS unsigned*)(lds + (bufoff) + ldsw + _i * 8192), 16, 0, 0); } while (0)
; #define PG8_LDA(dst, b, h) do { _Pragma("unroll") for (int m = 0; m < 4; ++m) _Pragma("unroll") for (int k = 0; k < 2; ++k) dst[m][k] = *(const LAS bf16x8*)(lds + PG8_SA(b, h) + aoff + m * 2048 + k * 1024); } while (0)
; #define PG8_LDB(dst, b, h) do { _Pragma("unroll") for (int n = 0; n < 2; ++n) _Pragma("unroll") for (int k = 0; k < 2; ++k) dst[n][k] = *(const LAS bf16x8*)(lds + PG8_SB(b, h) + boff + n * 2048 + k * 1024); } while (0)
; #define PG8_MMA(ai, bj, At, Bt) do { __builtin_amdgcn_s_setprio(1); _Pragma("unroll") for (int m = 0; m < 4; ++m) _Pragma("unroll") for (int n = 0; n < 2; ++n) _Pragma("unroll") for (int k = 0; k < 2; ++k) \
;         acc[ai][bj][m][n] = __builtin_amdgcn_mfma_f32_16x16x32_bf16(Bt[n][k], At[m][k], acc[ai][bj][m][n], 0, 0, 0); __builtin_amdgcn_s_setprio(0); } while (0)
; #define PG8_WAIT_V(n) asm volatile("s_waitcnt vmcnt(" #n ")" ::: "memory")
; #define PG8_WAIT_L(n) asm volatile("s_waitcnt lgkmcnt(" #n ")" ::: "memory")
; template <class Epi, class Sched>
; __device__ __forceinline__ void gemm_phase(LAS unsigned char* lds, const Gemm g, const Sched& S, const Epi& E) {
;     ...
;         for (int t = 0; t < nt; t += 2) {
;             const bool last = (t == nt - 2);
;             const char* a1 = cA + (size_t)(t + 1) * kstep;
;             const char* a2 = last ? nA : cA + (size_t)(t + 2) * kstep; const char* b2 = last ? nB : cB + (size_t)(t + 2) * kstep;
;             const char* a3 = a2 + kstep; const char* b3 = b2 + kstep;
;             PG8_LDB(B0, 0, 0); PG8_SCHED; PG8_LDA(At, 0, 0); PG8_STAGE(PG8_SA(1, 1), a1 + hstep, voffA);
;             PG8_WAIT_L(8); PG8_BAR; PG8_WAIT_L(0); PG8_MMA(0, 0, At, B0); PG8_BAR; PG8_SCHED;
;             PG8_LDB(B1, 0, 1); PG8_STAGE(PG8_SB(0, 0), b2, voffB);
;             PG8_BAR; PG8_WAIT_L(0); PG8_MMA(0, 1, At, B1); PG8_BAR;
;             PG8_LDA(At, 0, 1); PG8_STAGE(PG8_SA(0, 0), a2, voffA);
;             PG8_BAR; PG8_WAIT_L(0); PG8_MMA(1, 0, At, B0); PG8_BAR; PG8_SCHED;
;             PG8_STAGE(PG8_SB(0, 1), b2 + hstep, voffB);
;             PG8_WAIT_V(6); PG8_BAR; PG8_MMA(1, 1, At, B1); PG8_BAR;
.LBB0_99:
	s_add_u32 s56, s28, 0x100
	s_addc_u32 s57, s29, 0
	s_cmp_eq_u32 s81, 28
	s_cselect_b32 s61, s51, s57
	s_cselect_b32 s60, s77, s56
	s_cselect_b32 s59, s49, s80
	s_cselect_b32 s58, s78, s79
	v_lshl_add_u64 v[156:157], s[28:29], 0, v[150:151]
	s_add_i32 m0, s9, 0xc000
	s_nop 0
	global_load_lds_dwordx4 v[156:157], off
	v_lshl_add_u64 v[156:157], s[28:29], 0, v[148:149]
	s_add_i32 m0, s9, 0xe000
	s_nop 0
	global_load_lds_dwordx4 v[156:157], off
	s_add_i32 s38, 0, 0x10000
	v_add_u32_e32 v110, s38, v169
	ds_read_b128 v[98:101], v110
	ds_read_b128 v[102:105], v110 offset:1024
	ds_read_b128 v[106:109], v110 offset:2048
	ds_read_b128 v[110:113], v110 offset:3072
	ds_read_b128 v[152:155], v171
	ds_read_b128 v[160:163], v171 offset:1024
	ds_read_b128 v[164:167], v171 offset:2048
	ds_read_b128 v[172:175], v171 offset:3072
	ds_read_b128 v[176:179], v171 offset:4096
	ds_read_b128 v[180:183], v171 offset:5120
	ds_read_b128 v[184:187], v171 offset:6144
	ds_read_b128 v[188:191], v171 offset:7168
	s_add_i32 s39, 0, 0x14000
	v_add_u32_e32 v156, s39, v169
	ds_read_b128 v[192:195], v156
	ds_read_b128 v[196:199], v156 offset:1024
	ds_read_b128 v[200:203], v156 offset:2048
	ds_read_b128 v[204:207], v156 offset:3072
	s_waitcnt lgkmcnt(0)
	s_barrier
	s_setprio 1
	v_mfma_f32_16x16x32_bf16 v[142:145], v[98:101], v[152:155], v[142:145]
	v_mfma_f32_16x16x32_bf16 v[138:141], v[106:109], v[152:155], v[138:141]
	v_mfma_f32_16x16x32_bf16 v[126:129], v[98:101], v[164:167], v[126:129]
	v_mfma_f32_16x16x32_bf16 v[122:125], v[106:109], v[164:167], v[122:125]
	v_mfma_f32_16x16x32_bf16 v[94:97], v[98:101], v[176:179], v[94:97]
	v_mfma_f32_16x16x32_bf16 v[90:93], v[106:109], v[176:179], v[90:93]
	v_mfma_f32_16x16x32_bf16 v[86:89], v[98:101], v[184:187], v[86:89]
	v_mfma_f32_16x16x32_bf16 v[82:85], v[106:109], v[184:187], v[82:85]
	v_mfma_f32_16x16x32_bf16 v[142:145], v[102:105], v[160:163], v[142:145]
	v_mfma_f32_16x16x32_bf16 v[138:141], v[110:113], v[160:163], v[138:141]
	v_mfma_f32_16x16x32_bf16 v[126:129], v[102:105], v[172:175], v[126:129]
	v_mfma_f32_16x16x32_bf16 v[122:125], v[110:113], v[172:175], v[122:125]
	v_mfma_f32_16x16x32_bf16 v[94:97], v[102:105], v[180:183], v[94:97]
	v_mfma_f32_16x16x32_bf16 v[90:93], v[110:113], v[180:183], v[90:93]
	v_mfma_f32_16x16x32_bf16 v[86:89], v[102:105], v[188:191], v[86:89]
	v_mfma_f32_16x16x32_bf16 v[82:85], v[110:113], v[188:191], v[82:85]
	v_mfma_f32_16x16x32_bf16 v[134:137], v[192:195], v[152:155], v[134:137]
	v_mfma_f32_16x16x32_bf16 v[130:133], v[200:203], v[152:155], v[130:133]
	v_mfma_f32_16x16x32_bf16 v[118:121], v[192:195], v[164:167], v[118:121]
	v_mfma_f32_16x16x32_bf16 v[114:117], v[200:203], v[164:167], v[114:117]
	v_mfma_f32_16x16x32_bf16 v[78:81], v[192:195], v[176:179], v[78:81]
	v_mfma_f32_16x16x32_bf16 v[74:77], v[200:203], v[176:179], v[74:77]
	v_mfma_f32_16x16x32_bf16 v[70:73], v[192:195], v[184:187], v[70:73]
	v_mfma_f32_16x16x32_bf16 v[66:69], v[200:203], v[184:187], v[66:69]
	v_mfma_f32_16x16x32_bf16 v[134:137], v[196:199], v[160:163], v[134:137]
	v_mfma_f32_16x16x32_bf16 v[130:133], v[204:207], v[160:163], v[130:133]
	v_mfma_f32_16x16x32_bf16 v[118:121], v[196:199], v[172:175], v[118:121]
	v_mfma_f32_16x16x32_bf16 v[114:117], v[204:207], v[172:175], v[114:117]
	v_mfma_f32_16x16x32_bf16 v[78:81], v[196:199], v[180:183], v[78:81]
	v_mfma_f32_16x16x32_bf16 v[74:77], v[204:207], v[180:183], v[74:77]
	v_mfma_f32_16x16x32_bf16 v[70:73], v[196:199], v[188:191], v[70:73]
	v_mfma_f32_16x16x32_bf16 v[66:69], v[204:207], v[188:191], v[66:69]
	s_setprio 0
	s_barrier
	s_add_i32 s28, s38, s67
	v_lshl_add_u64 v[156:157], s[58:59], 0, v[0:1]
	s_mov_b32 m0, s28
	v_lshl_add_u64 v[210:211], s[58:59], 0, v[146:147]
	global_load_lds_dwordx4 v[156:157], off
	s_add_i32 m0, s28, 0x2000
	s_nop 0
	global_load_lds_dwordx4 v[210:211], off
	s_mov_b32 m0, s9
	v_lshl_add_u64 v[212:213], s[60:61], 0, v[0:1]
	global_load_lds_dwordx4 v[212:213], off
	v_lshl_add_u64 v[214:215], s[60:61], 0, v[146:147]
	s_mov_b32 m0, s68
	s_nop 0
	global_load_lds_dwordx4 v[214:215], off
	ds_read_b128 v[152:155], v171 offset:16384
	ds_read_b128 v[160:163], v171 offset:17408
	ds_read_b128 v[164:167], v171 offset:18432
	ds_read_b128 v[172:175], v171 offset:19456
	ds_read_b128 v[176:179], v171 offset:20480
	ds_read_b128 v[180:183], v171 offset:21504
	ds_read_b128 v[184:187], v171 offset:22528
	ds_read_b128 v[188:191], v171 offset:23552
	s_waitcnt vmcnt(4)
	s_waitcnt lgkmcnt(0)
	s_barrier
	s_setprio 1
	v_mfma_f32_16x16x32_bf16 v[62:65], v[98:101], v[152:155], v[62:65]
	v_mfma_f32_16x16x32_bf16 v[58:61], v[106:109], v[152:155], v[58:61]
	v_mfma_f32_16x16x32_bf16 v[46:49], v[98:101], v[164:167], v[46:49]
	v_mfma_f32_16x16x32_bf16 v[42:45], v[106:109], v[164:167], v[42:45]
	v_mfma_f32_16x16x32_bf16 v[30:33], v[98:101], v[176:179], v[30:33]
	v_mfma_f32_16x16x32_bf16 v[26:29], v[106:109], v[176:179], v[26:29]
	v_mfma_f32_16x16x32_bf16 v[22:25], v[98:101], v[184:187], v[22:25]
	v_mfma_f32_16x16x32_bf16 v[18:21], v[106:109], v[184:187], v[18:21]
	v_mfma_f32_16x16x32_bf16 v[62:65], v[102:105], v[160:163], v[62:65]
	v_mfma_f32_16x16x32_bf16 v[58:61], v[110:113], v[160:163], v[58:61]
	v_mfma_f32_16x16x32_bf16 v[46:49], v[102:105], v[172:175], v[46:49]
	v_mfma_f32_16x16x32_bf16 v[42:45], v[110:113], v[172:175], v[42:45]
	v_mfma_f32_16x16x32_bf16 v[30:33], v[102:105], v[180:183], v[30:33]
	v_mfma_f32_16x16x32_bf16 v[26:29], v[110:113], v[180:183], v[26:29]
	v_mfma_f32_16x16x32_bf16 v[22:25], v[102:105], v[188:191], v[22:25]
	v_mfma_f32_16x16x32_bf16 v[18:21], v[110:113], v[188:191], v[18:21]
	v_mfma_f32_16x16x32_bf16 v[54:57], v[192:195], v[152:155], v[54:57]
	v_mfma_f32_16x16x32_bf16 v[50:53], v[200:203], v[152:155], v[50:53]
	v_mfma_f32_16x16x32_bf16 v[38:41], v[192:195], v[164:167], v[38:41]
	v_mfma_f32_16x16x32_bf16 v[34:37], v[200:203], v[164:167], v[34:37]
	v_mfma_f32_16x16x32_bf16 v[14:17], v[192:195], v[176:179], v[14:17]
	v_mfma_f32_16x16x32_bf16 v[10:13], v[200:203], v[176:179], v[10:13]
	v_mfma_f32_16x16x32_bf16 v[6:9], v[192:195], v[184:187], v[6:9]
	v_mfma_f32_16x16x32_bf16 v[2:5], v[200:203], v[184:187], v[2:5]
	v_mfma_f32_16x16x32_bf16 v[54:57], v[196:199], v[160:163], v[54:57]
	v_mfma_f32_16x16x32_bf16 v[50:53], v[204:207], v[160:163], v[50:53]
	v_mfma_f32_16x16x32_bf16 v[38:41], v[196:199], v[172:175], v[38:41]
	v_mfma_f32_16x16x32_bf16 v[34:37], v[204:207], v[172:175], v[34:37]
	v_mfma_f32_16x16x32_bf16 v[14:17], v[196:199], v[180:183], v[14:17]
	v_mfma_f32_16x16x32_bf16 v[10:13], v[204:207], v[180:183], v[10:13]
	v_mfma_f32_16x16x32_bf16 v[6:9], v[196:199], v[188:191], v[6:9]
	v_mfma_f32_16x16x32_bf16 v[2:5], v[204:207], v[188:191], v[2:5]
	s_setprio 0
	s_barrier
; #define PG8_STAGE(bufoff, gbase, voff) do { _Pragma("unroll") for (int _i = 0; _i < 2; ++_i) \
;         __builtin_amdgcn_global_load_lds((const unsigned*)((const char*)(gbase) + (voff)[_i]), (LAS unsigned*)(lds + (bufoff) + ldsw + _i * 8192), 16, 0, 0); } while (0)
; #define PG8_LDA(dst, b, h) do { _Pragma("unroll") for (int m = 0; m < 4; ++m) _Pragma("unroll") for (int k = 0; k < 2; ++k) dst[m][k] = *(const LAS bf16x8*)(lds + PG8_SA(b, h) + aoff + m * 2048 + k * 1024); } while (0)
; #define PG8_LDB(dst, b, h) do { _Pragma("unroll") for (int n = 0; n < 2; ++n) _Pragma("unroll") for (int k = 0; k < 2; ++k) dst[n][k] = *(const LAS bf16x8*)(lds + PG8_SB(b, h) + boff + n * 2048 + k * 1024); } while (0)
; #define PG8_MMA(ai, bj, At, Bt) do { __builtin_amdgcn_s_setprio(1); _Pragma("unroll") for (int m = 0; m < 4; ++m) _Pragma("unroll") for (int n = 0; n < 2; ++n) _Pragma("unroll") for (int k = 0; k < 2; ++k) \
;         acc[ai][bj][m][n] = __builtin_amdgcn_mfma_f32_16x16x32_bf16(Bt[n][k], At[m][k], acc[ai][bj][m][n], 0, 0, 0); __builtin_amdgcn_s_setprio(0); } while (0)
; #define PG8_WAIT_L(n) asm volatile("s_waitcnt lgkmcnt(" #n ")" ::: "memory")
; #define PG8_BAR __builtin_amdgcn_s_barrier()
; #define PG8_SCHED __builtin_amdgcn_sched_barrier(0)
; template <class Epi, class Sched>
; __device__ __forceinline__ void gemm_phase(LAS unsigned char* lds, const Gemm g, const Sched& S, const Epi& E) {
;     ...
;             PG8_LDB(B0, 1, 0); PG8_SCHED; PG8_LDA(At, 1, 0); PG8_STAGE(PG8_SA(0, 1), a2 + hstep, voffA);
;             PG8_WAIT_L(8); PG8_BAR; PG8_WAIT_L(0); PG8_MMA(0, 0, At, B0); PG8_BAR; PG8_SCHED;
;             PG8_LDB(B1, 1, 1); PG8_STAGE(PG8_SB(1, 0), b3, voffB);
;             PG8_BAR; PG8_WAIT_L(0); PG8_MMA(0, 1, At, B1); PG8_BAR;
;             PG8_LDA(At, 1, 1); PG8_STAGE(PG8_SA(1, 0), a3, voffA);
;             PG8_BAR; PG8_WAIT_L(0); PG8_MMA(1, 0, At, B0); PG8_BAR; PG8_SCHED;
	s_add_u32 s28, s58, 0x80000
	s_addc_u32 s29, s59, 0
	s_add_i32 s38, s39, s67
	v_lshl_add_u64 v[98:99], s[28:29], 0, v[0:1]
	s_mov_b32 m0, s38
	s_nop 0
	global_load_lds_dwordx4 v[98:99], off
	v_lshl_add_u64 v[98:99], s[28:29], 0, v[146:147]
	s_add_i32 m0, s38, 0x2000
	s_nop 0
	global_load_lds_dwordx4 v[98:99], off
	s_add_u32 s28, s60, 0x80000
	s_addc_u32 s29, s61, 0
	s_mov_b32 m0, s69
	v_lshl_add_u64 v[192:193], s[28:29], 0, v[0:1]
	global_load_lds_dwordx4 v[192:193], off
	v_lshl_add_u64 v[192:193], s[28:29], 0, v[146:147]
	s_mov_b32 m0, s70
	s_nop 0
	global_load_lds_dwordx4 v[192:193], off
	s_add_i32 s38, 0, 0x18000
	v_add_u32_e32 v110, s38, v169
	ds_read_b128 v[98:101], v110
	ds_read_b128 v[102:105], v110 offset:1024
	ds_read_b128 v[106:109], v110 offset:2048
	ds_read_b128 v[110:113], v110 offset:3072
	ds_read_b128 v[152:155], v171 offset:32768
	ds_read_b128 v[160:163], v171 offset:33792
	ds_read_b128 v[164:167], v171 offset:34816
	ds_read_b128 v[172:175], v171 offset:35840
	ds_read_b128 v[176:179], v171 offset:36864
	ds_read_b128 v[180:183], v171 offset:37888
	ds_read_b128 v[184:187], v171 offset:38912
	ds_read_b128 v[188:191], v171 offset:39936
	s_add_i32 s39, 0, 0x1c000
	v_add_u32_e32 v204, s39, v169
	ds_read_b128 v[192:195], v204
	ds_read_b128 v[196:199], v204 offset:1024
	ds_read_b128 v[200:203], v204 offset:2048
	ds_read_b128 v[204:207], v204 offset:3072
	s_waitcnt lgkmcnt(0)
	s_barrier
	s_setprio 1
	v_mfma_f32_16x16x32_bf16 v[142:145], v[98:101], v[152:155], v[142:145]
	v_mfma_f32_16x16x32_bf16 v[138:141], v[106:109], v[152:155], v[138:141]
	v_mfma_f32_16x16x32_bf16 v[126:129], v[98:101], v[164:167], v[126:129]
	v_mfma_f32_16x16x32_bf16 v[122:125], v[106:109], v[164:167], v[122:125]
	v_mfma_f32_16x16x32_bf16 v[94:97], v[98:101], v[176:179], v[94:97]
	v_mfma_f32_16x16x32_bf16 v[90:93], v[106:109], v[176:179], v[90:93]
	v_mfma_f32_16x16x32_bf16 v[86:89], v[98:101], v[184:187], v[86:89]
	v_mfma_f32_16x16x32_bf16 v[82:85], v[106:109], v[184:187], v[82:85]
	v_mfma_f32_16x16x32_bf16 v[142:145], v[102:105], v[160:163], v[142:145]
	v_mfma_f32_16x16x32_bf16 v[138:141], v[110:113], v[160:163], v[138:141]
	v_mfma_f32_16x16x32_bf16 v[126:129], v[102:105], v[172:175], v[126:129]
	v_mfma_f32_16x16x32_bf16 v[122:125], v[110:113], v[172:175], v[122:125]
	v_mfma_f32_16x16x32_bf16 v[94:97], v[102:105], v[180:183], v[94:97]
	v_mfma_f32_16x16x32_bf16 v[90:93], v[110:113], v[180:183], v[90:93]
	v_mfma_f32_16x16x32_bf16 v[86:89], v[102:105], v[188:191], v[86:89]
	v_mfma_f32_16x16x32_bf16 v[82:85], v[110:113], v[188:191], v[82:85]
	v_mfma_f32_16x16x32_bf16 v[134:137], v[192:195], v[152:155], v[134:137]
	v_mfma_f32_16x16x32_bf16 v[130:133], v[200:203], v[152:155], v[130:133]
	v_mfma_f32_16x16x32_bf16 v[118:121], v[192:195], v[164:167], v[118:121]
	v_mfma_f32_16x16x32_bf16 v[114:117], v[200:203], v[164:167], v[114:117]
	v_mfma_f32_16x16x32_bf16 v[78:81], v[192:195], v[176:179], v[78:81]
	v_mfma_f32_16x16x32_bf16 v[74:77], v[200:203], v[176:179], v[74:77]
	v_mfma_f32_16x16x32_bf16 v[70:73], v[192:195], v[184:187], v[70:73]
	v_mfma_f32_16x16x32_bf16 v[66:69], v[200:203], v[184:187], v[66:69]
	v_mfma_f32_16x16x32_bf16 v[134:137], v[196:199], v[160:163], v[134:137]
	v_mfma_f32_16x16x32_bf16 v[130:133], v[204:207], v[160:163], v[130:133]
	v_mfma_f32_16x16x32_bf16 v[118:121], v[196:199], v[172:175], v[118:121]
	v_mfma_f32_16x16x32_bf16 v[114:117], v[204:207], v[172:175], v[114:117]
	v_mfma_f32_16x16x32_bf16 v[78:81], v[196:199], v[180:183], v[78:81]
	v_mfma_f32_16x16x32_bf16 v[74:77], v[204:207], v[180:183], v[74:77]
	v_mfma_f32_16x16x32_bf16 v[70:73], v[196:199], v[188:191], v[70:73]
	v_mfma_f32_16x16x32_bf16 v[66:69], v[204:207], v[188:191], v[66:69]
	s_setprio 0
	s_barrier
; #define PG8_STAGE(bufoff, gbase, voff) do { _Pragma("unroll") for (int _i = 0; _i < 2; ++_i) \
;         __builtin_amdgcn_global_load_lds((const unsigned*)((const char*)(gbase) + (voff)[_i]), (LAS unsigned*)(lds + (bufoff) + ldsw + _i * 8192), 16, 0, 0); } while (0)
; #define PG8_LDA(dst, b, h) do { _Pragma("unroll") for (int m = 0; m < 4; ++m) _Pragma("unroll") for (int k = 0; k < 2; ++k) dst[m][k] = *(const LAS bf16x8*)(lds + PG8_SA(b, h) + aoff + m * 2048 + k * 1024); } while (0)
; #define PG8_MMA(ai, bj, At, Bt) do { __builtin_amdgcn_s_setprio(1); _Pragma("unroll") for (int m = 0; m < 4; ++m) _Pragma("unroll") for (int n = 0; n < 2; ++n) _Pragma("unroll") for (int k = 0; k < 2; ++k) \
;         acc[ai][bj][m][n] = __builtin_amdgcn_mfma_f32_16x16x32_bf16(Bt[n][k], At[m][k], acc[ai][bj][m][n], 0, 0, 0); __builtin_amdgcn_s_setprio(0); } while (0)
; #define PG8_WAIT_V(n) asm volatile("s_waitcnt vmcnt(" #n ")" ::: "memory")
; #define PG8_WAIT_L(n) asm volatile("s_waitcnt lgkmcnt(" #n ")" ::: "memory")
; #define PG8_BAR __builtin_amdgcn_s_barrier()
; #define PG8_SCHED __builtin_amdgcn_sched_barrier(0)
; template <class Epi, class Sched>
; __device__ __forceinline__ void gemm_phase(LAS unsigned char* lds, const Gemm g, const Sched& S, const Epi& E) {
;     ...
;             PG8_LDA(At, 1, 1); PG8_STAGE(PG8_SA(1, 0), a3, voffA);
;             PG8_BAR; PG8_WAIT_L(0); PG8_MMA(1, 0, At, B0); PG8_BAR; PG8_SCHED;
;             PG8_STAGE(PG8_SB(1, 1), b3 + hstep, voffB);
;             PG8_WAIT_V(6); PG8_BAR; PG8_MMA(1, 1, At, B1); PG8_BAR;
;         }
;         E(acc, cur, wr, wc, fr, fq);
;         if (!has_next) break;
	s_add_i32 s28, s38, s67
	v_lshl_add_u64 v[156:157], v[156:157], 0, s[36:37]
	s_mov_b32 m0, s28
	s_nop 0
	global_load_lds_dwordx4 v[156:157], off
	v_lshl_add_u64 v[156:157], v[210:211], 0, s[36:37]
	s_add_i32 m0, s28, 0x2000
	s_nop 0
	global_load_lds_dwordx4 v[156:157], off
	s_mov_b32 m0, s72
	v_lshl_add_u64 v[156:157], v[212:213], 0, s[36:37]
	global_load_lds_dwordx4 v[156:157], off
	v_lshl_add_u64 v[156:157], v[214:215], 0, s[36:37]
	s_mov_b32 m0, s73
	s_nop 0
	global_load_lds_dwordx4 v[156:157], off
	ds_read_b128 v[152:155], v171 offset:49152
	ds_read_b128 v[160:163], v171 offset:50176
	ds_read_b128 v[164:167], v171 offset:51200
	ds_read_b128 v[172:175], v171 offset:52224
	ds_read_b128 v[176:179], v171 offset:53248
	ds_read_b128 v[180:183], v171 offset:54272
	ds_read_b128 v[184:187], v171 offset:55296
	ds_read_b128 v[188:191], v171 offset:56320
	s_waitcnt vmcnt(4)
	s_waitcnt lgkmcnt(0)
	s_barrier
	s_setprio 1
	v_mfma_f32_16x16x32_bf16 v[62:65], v[98:101], v[152:155], v[62:65]
	v_mfma_f32_16x16x32_bf16 v[58:61], v[106:109], v[152:155], v[58:61]
	v_mfma_f32_16x16x32_bf16 v[46:49], v[98:101], v[164:167], v[46:49]
	v_mfma_f32_16x16x32_bf16 v[42:45], v[106:109], v[164:167], v[42:45]
	v_mfma_f32_16x16x32_bf16 v[30:33], v[98:101], v[176:179], v[30:33]
	v_mfma_f32_16x16x32_bf16 v[26:29], v[106:109], v[176:179], v[26:29]
	v_mfma_f32_16x16x32_bf16 v[22:25], v[98:101], v[184:187], v[22:25]
	v_mfma_f32_16x16x32_bf16 v[18:21], v[106:109], v[184:187], v[18:21]
	v_mfma_f32_16x16x32_bf16 v[62:65], v[102:105], v[160:163], v[62:65]
	v_mfma_f32_16x16x32_bf16 v[58:61], v[110:113], v[160:163], v[58:61]
	v_mfma_f32_16x16x32_bf16 v[46:49], v[102:105], v[172:175], v[46:49]
	v_mfma_f32_16x16x32_bf16 v[42:45], v[110:113], v[172:175], v[42:45]
	v_mfma_f32_16x16x32_bf16 v[30:33], v[102:105], v[180:183], v[30:33]
	v_mfma_f32_16x16x32_bf16 v[26:29], v[110:113], v[180:183], v[26:29]
	v_mfma_f32_16x16x32_bf16 v[22:25], v[102:105], v[188:191], v[22:25]
	v_mfma_f32_16x16x32_bf16 v[18:21], v[110:113], v[188:191], v[18:21]
	s_add_u32 s28, s58, 0x80080
	s_addc_u32 s29, s59, 0
	s_add_i32 s38, s39, s67
	v_lshl_add_u64 v[98:99], s[28:29], 0, v[0:1]
	s_mov_b32 m0, s38
	s_nop 0
	global_load_lds_dwordx4 v[98:99], off
	v_lshl_add_u64 v[98:99], s[28:29], 0, v[146:147]
	s_add_i32 m0, s38, 0x2000
	s_nop 0
	global_load_lds_dwordx4 v[98:99], off
	v_mfma_f32_16x16x32_bf16 v[54:57], v[192:195], v[152:155], v[54:57]
	v_mfma_f32_16x16x32_bf16 v[50:53], v[200:203], v[152:155], v[50:53]
	v_mfma_f32_16x16x32_bf16 v[38:41], v[192:195], v[164:167], v[38:41]
	v_mfma_f32_16x16x32_bf16 v[34:37], v[200:203], v[164:167], v[34:37]
	v_mfma_f32_16x16x32_bf16 v[14:17], v[192:195], v[176:179], v[14:17]
	v_mfma_f32_16x16x32_bf16 v[10:13], v[200:203], v[176:179], v[10:13]
	v_mfma_f32_16x16x32_bf16 v[6:9], v[192:195], v[184:187], v[6:9]
	v_mfma_f32_16x16x32_bf16 v[2:5], v[200:203], v[184:187], v[2:5]
	v_mfma_f32_16x16x32_bf16 v[54:57], v[196:199], v[160:163], v[54:57]
	v_mfma_f32_16x16x32_bf16 v[50:53], v[204:207], v[160:163], v[50:53]
	v_mfma_f32_16x16x32_bf16 v[38:41], v[196:199], v[172:175], v[38:41]
	v_mfma_f32_16x16x32_bf16 v[34:37], v[204:207], v[172:175], v[34:37]
	v_mfma_f32_16x16x32_bf16 v[14:17], v[196:199], v[180:183], v[14:17]
	v_mfma_f32_16x16x32_bf16 v[10:13], v[204:207], v[180:183], v[10:13]
	v_mfma_f32_16x16x32_bf16 v[6:9], v[196:199], v[188:191], v[6:9]
	v_mfma_f32_16x16x32_bf16 v[2:5], v[204:207], v[188:191], v[2:5]
	s_setprio 0
	s_add_i32 s81, s81, 2
	s_add_u32 s79, s79, 0x100
	s_addc_u32 s80, s80, 0
	s_cmp_gt_u32 s81, 29
	s_mov_b64 s[28:29], s[56:57]
	s_barrier
	s_cbranch_scc0 .LBB0_99
	s_cmp_lt_i32 s8, 64
	s_cselect_b64 s[58:59], -1, 0
	s_cmp_gt_i32 s8, 63
	s_cbranch_scc0 .LBB0_90
	s_mov_b64 s[60:61], 0x18000
	s_mov_b64 s[28:29], s[46:47]
	s_mov_b64 s[56:57], s[24:25]
	s_branch .LBB0_91

; #define PG8_STAGE(bufoff, gbase, voff) do { _Pragma("unroll") for (int _i = 0; _i < 2; ++_i) \
;         __builtin_amdgcn_global_load_lds((const unsigned*)((const char*)(gbase) + (voff)[_i]), (LAS unsigned*)(lds + (bufoff) + ldsw + _i * 8192), 16, 0, 0); } while (0)
; #define PG8_LDA(dst, b, h) do { _Pragma("unroll") for (int m = 0; m < 4; ++m) _Pragma("unroll") for (int k = 0; k < 2; ++k) dst[m][k] = *(const LAS bf16x8*)(lds + PG8_SA(b, h) + aoff + m * 2048 + k * 1024); } while (0)
; #define PG8_LDB(dst, b, h) do { _Pragma("unroll") for (int n = 0; n < 2; ++n) _Pragma("unroll") for (int k = 0; k < 2; ++k) dst[n][k] = *(const LAS bf16x8*)(lds + PG8_SB(b, h) + boff + n * 2048 + k * 1024); } while (0)
; #define PG8_MMA(ai, bj, At, Bt) do { __builtin_amdgcn_s_setprio(1); _Pragma("unroll") for (int m = 0; m < 4; ++m) _Pragma("unroll") for (int n = 0; n < 2; ++n) _Pragma("unroll") for (int k = 0; k < 2; ++k) \
;         acc[ai][bj][m][n] = __builtin_amdgcn_mfma_f32_16x16x32_bf16(Bt[n][k], At[m][k], acc[ai][bj][m][n], 0, 0, 0); __builtin_amdgcn_s_setprio(0); } while (0)
; #define PG8_WAIT_V(n) asm volatile("s_waitcnt vmcnt(" #n ")" ::: "memory")
; #define PG8_WAIT_L(n) asm volatile("s_waitcnt lgkmcnt(" #n ")" ::: "memory")
; template <class Epi, class Sched>
; __device__ __forceinline__ void gemm_phase(LAS unsigned char* lds, const Gemm g, const Sched& S, const Epi& E) {
;     ...
;         for (int t = 0; t < nt; t += 2) {
;             const bool last = (t == nt - 2);
;             const char* a1 = cA + (size_t)(t + 1) * kstep;
;             const char* a2 = last ? nA : cA + (size_t)(t + 2) * kstep; const char* b2 = last ? nB : cB + (size_t)(t + 2) * kstep;
;             const char* a3 = a2 + kstep; const char* b3 = b2 + kstep;
;             PG8_LDB(B0, 0, 0); PG8_SCHED; PG8_LDA(At, 0, 0); PG8_STAGE(PG8_SA(1, 1), a1 + hstep, voffA);
;             PG8_WAIT_L(8); PG8_BAR; PG8_WAIT_L(0); PG8_MMA(0, 0, At, B0); PG8_BAR; PG8_SCHED;
;             PG8_LDB(B1, 0, 1); PG8_STAGE(PG8_SB(0, 0), b2, voffB);
;             PG8_BAR; PG8_WAIT_L(0); PG8_MMA(0, 1, At, B1); PG8_BAR;
;             PG8_LDA(At, 0, 1); PG8_STAGE(PG8_SA(0, 0), a2, voffA);
;             PG8_BAR; PG8_WAIT_L(0); PG8_MMA(1, 0, At, B0); PG8_BAR; PG8_SCHED;
;             PG8_STAGE(PG8_SB(0, 1), b2 + hstep, voffB);
;             PG8_WAIT_V(6); PG8_BAR; PG8_MMA(1, 1, At, B1); PG8_BAR;
.LBB0_113:
	s_add_u32 s54, s52, 0x100
	s_addc_u32 s55, s53, 0
	s_cmp_eq_u32 s73, 4
	s_cselect_b32 s59, s11, s55
	s_cselect_b32 s58, s29, s54
	s_cselect_b32 s57, s41, s72
	s_cselect_b32 s56, s45, s71
	v_lshl_add_u64 v[156:157], s[52:53], 0, v[134:135]
	s_add_i32 m0, s25, 0xc000
	s_nop 0
	global_load_lds_dwordx4 v[156:157], off
	v_lshl_add_u64 v[156:157], s[52:53], 0, v[132:133]
	s_add_i32 m0, s25, 0xe000
	s_nop 0
	global_load_lds_dwordx4 v[156:157], off
	s_add_i32 s38, 0, 0x10000
	v_add_u32_e32 v152, s38, v137
	ds_read_b128 v[140:143], v152
	ds_read_b128 v[144:147], v152 offset:1024
	ds_read_b128 v[148:151], v152 offset:2048
	ds_read_b128 v[152:155], v152 offset:3072
	ds_read_b128 v[160:163], v139
	ds_read_b128 v[164:167], v139 offset:1024
	ds_read_b128 v[168:171], v139 offset:2048
	ds_read_b128 v[172:175], v139 offset:3072
	ds_read_b128 v[176:179], v139 offset:4096
	ds_read_b128 v[180:183], v139 offset:5120
	ds_read_b128 v[184:187], v139 offset:6144
	ds_read_b128 v[188:191], v139 offset:7168
	s_add_i32 s52, 0, 0x14000
	v_add_u32_e32 v156, s52, v137
	ds_read_b128 v[192:195], v156
	ds_read_b128 v[196:199], v156 offset:1024
	ds_read_b128 v[200:203], v156 offset:2048
	ds_read_b128 v[204:207], v156 offset:3072
	s_waitcnt lgkmcnt(0)
	s_barrier
	s_setprio 1
	v_mfma_f32_16x16x32_bf16 v[126:129], v[140:143], v[160:163], v[126:129]
	v_mfma_f32_16x16x32_bf16 v[122:125], v[148:151], v[160:163], v[122:125]
	v_mfma_f32_16x16x32_bf16 v[118:121], v[140:143], v[168:171], v[118:121]
	v_mfma_f32_16x16x32_bf16 v[114:117], v[148:151], v[168:171], v[114:117]
	v_mfma_f32_16x16x32_bf16 v[106:109], v[140:143], v[176:179], v[106:109]
	v_mfma_f32_16x16x32_bf16 v[98:101], v[148:151], v[176:179], v[98:101]
	v_mfma_f32_16x16x32_bf16 v[90:93], v[140:143], v[184:187], v[90:93]
	v_mfma_f32_16x16x32_bf16 v[82:85], v[148:151], v[184:187], v[82:85]
	v_mfma_f32_16x16x32_bf16 v[126:129], v[144:147], v[164:167], v[126:129]
	v_mfma_f32_16x16x32_bf16 v[122:125], v[152:155], v[164:167], v[122:125]
	v_mfma_f32_16x16x32_bf16 v[118:121], v[144:147], v[172:175], v[118:121]
	v_mfma_f32_16x16x32_bf16 v[114:117], v[152:155], v[172:175], v[114:117]
	v_mfma_f32_16x16x32_bf16 v[106:109], v[144:147], v[180:183], v[106:109]
	v_mfma_f32_16x16x32_bf16 v[98:101], v[152:155], v[180:183], v[98:101]
	v_mfma_f32_16x16x32_bf16 v[90:93], v[144:147], v[188:191], v[90:93]
	v_mfma_f32_16x16x32_bf16 v[82:85], v[152:155], v[188:191], v[82:85]
	v_mfma_f32_16x16x32_bf16 v[110:113], v[192:195], v[160:163], v[110:113]
	v_mfma_f32_16x16x32_bf16 v[102:105], v[200:203], v[160:163], v[102:105]
	v_mfma_f32_16x16x32_bf16 v[94:97], v[192:195], v[168:171], v[94:97]
	v_mfma_f32_16x16x32_bf16 v[86:89], v[200:203], v[168:171], v[86:89]
	v_mfma_f32_16x16x32_bf16 v[78:81], v[192:195], v[176:179], v[78:81]
	v_mfma_f32_16x16x32_bf16 v[74:77], v[200:203], v[176:179], v[74:77]
	v_mfma_f32_16x16x32_bf16 v[70:73], v[192:195], v[184:187], v[70:73]
	v_mfma_f32_16x16x32_bf16 v[66:69], v[200:203], v[184:187], v[66:69]
	v_mfma_f32_16x16x32_bf16 v[110:113], v[196:199], v[164:167], v[110:113]
	v_mfma_f32_16x16x32_bf16 v[102:105], v[204:207], v[164:167], v[102:105]
	v_mfma_f32_16x16x32_bf16 v[94:97], v[196:199], v[172:175], v[94:97]
	v_mfma_f32_16x16x32_bf16 v[86:89], v[204:207], v[172:175], v[86:89]
	v_mfma_f32_16x16x32_bf16 v[78:81], v[196:199], v[180:183], v[78:81]
	v_mfma_f32_16x16x32_bf16 v[74:77], v[204:207], v[180:183], v[74:77]
	v_mfma_f32_16x16x32_bf16 v[70:73], v[196:199], v[188:191], v[70:73]
	v_mfma_f32_16x16x32_bf16 v[66:69], v[204:207], v[188:191], v[66:69]
	s_setprio 0
	s_barrier
	s_add_i32 s38, s38, s65
	v_lshl_add_u64 v[156:157], s[56:57], 0, v[0:1]
	s_mov_b32 m0, s38
	v_lshl_add_u64 v[210:211], s[56:57], 0, v[130:131]
	global_load_lds_dwordx4 v[156:157], off
	s_add_i32 m0, s38, 0x2000
	s_nop 0
	global_load_lds_dwordx4 v[210:211], off
	s_mov_b32 m0, s25
	v_lshl_add_u64 v[212:213], s[58:59], 0, v[0:1]
	global_load_lds_dwordx4 v[212:213], off
	v_lshl_add_u64 v[214:215], s[58:59], 0, v[130:131]
	s_mov_b32 m0, s27
	s_nop 0
	global_load_lds_dwordx4 v[214:215], off
	ds_read_b128 v[160:163], v139 offset:16384
	ds_read_b128 v[164:167], v139 offset:17408
	ds_read_b128 v[168:171], v139 offset:18432
	ds_read_b128 v[172:175], v139 offset:19456
	ds_read_b128 v[176:179], v139 offset:20480
	ds_read_b128 v[180:183], v139 offset:21504
	ds_read_b128 v[184:187], v139 offset:22528
	ds_read_b128 v[188:191], v139 offset:23552
	s_waitcnt vmcnt(4)
	s_waitcnt lgkmcnt(0)
	s_barrier
	s_setprio 1
	v_mfma_f32_16x16x32_bf16 v[62:65], v[140:143], v[160:163], v[62:65]
	v_mfma_f32_16x16x32_bf16 v[58:61], v[148:151], v[160:163], v[58:61]
	v_mfma_f32_16x16x32_bf16 v[54:57], v[140:143], v[168:171], v[54:57]
	v_mfma_f32_16x16x32_bf16 v[50:53], v[148:151], v[168:171], v[50:53]
	v_mfma_f32_16x16x32_bf16 v[38:41], v[140:143], v[176:179], v[38:41]
	v_mfma_f32_16x16x32_bf16 v[34:37], v[148:151], v[176:179], v[34:37]
	v_mfma_f32_16x16x32_bf16 v[22:25], v[140:143], v[184:187], v[22:25]
	v_mfma_f32_16x16x32_bf16 v[18:21], v[148:151], v[184:187], v[18:21]
	v_mfma_f32_16x16x32_bf16 v[62:65], v[144:147], v[164:167], v[62:65]
	v_mfma_f32_16x16x32_bf16 v[58:61], v[152:155], v[164:167], v[58:61]
	v_mfma_f32_16x16x32_bf16 v[54:57], v[144:147], v[172:175], v[54:57]
	v_mfma_f32_16x16x32_bf16 v[50:53], v[152:155], v[172:175], v[50:53]
	v_mfma_f32_16x16x32_bf16 v[38:41], v[144:147], v[180:183], v[38:41]
	v_mfma_f32_16x16x32_bf16 v[34:37], v[152:155], v[180:183], v[34:37]
	v_mfma_f32_16x16x32_bf16 v[22:25], v[144:147], v[188:191], v[22:25]
	v_mfma_f32_16x16x32_bf16 v[18:21], v[152:155], v[188:191], v[18:21]
	v_mfma_f32_16x16x32_bf16 v[46:49], v[192:195], v[160:163], v[46:49]
	v_mfma_f32_16x16x32_bf16 v[42:45], v[200:203], v[160:163], v[42:45]
	v_mfma_f32_16x16x32_bf16 v[30:33], v[192:195], v[168:171], v[30:33]
	v_mfma_f32_16x16x32_bf16 v[26:29], v[200:203], v[168:171], v[26:29]
	v_mfma_f32_16x16x32_bf16 v[14:17], v[192:195], v[176:179], v[14:17]
	v_mfma_f32_16x16x32_bf16 v[10:13], v[200:203], v[176:179], v[10:13]
	v_mfma_f32_16x16x32_bf16 v[6:9], v[192:195], v[184:187], v[6:9]
	v_mfma_f32_16x16x32_bf16 v[2:5], v[200:203], v[184:187], v[2:5]
	v_mfma_f32_16x16x32_bf16 v[46:49], v[196:199], v[164:167], v[46:49]
	v_mfma_f32_16x16x32_bf16 v[42:45], v[204:207], v[164:167], v[42:45]
	v_mfma_f32_16x16x32_bf16 v[30:33], v[196:199], v[172:175], v[30:33]
	v_mfma_f32_16x16x32_bf16 v[26:29], v[204:207], v[172:175], v[26:29]
	v_mfma_f32_16x16x32_bf16 v[14:17], v[196:199], v[180:183], v[14:17]
	v_mfma_f32_16x16x32_bf16 v[10:13], v[204:207], v[180:183], v[10:13]
	v_mfma_f32_16x16x32_bf16 v[6:9], v[196:199], v[188:191], v[6:9]
	v_mfma_f32_16x16x32_bf16 v[2:5], v[204:207], v[188:191], v[2:5]
	s_setprio 0
	s_barrier
; #define PG8_STAGE(bufoff, gbase, voff) do { _Pragma("unroll") for (int _i = 0; _i < 2; ++_i) \
;         __builtin_amdgcn_global_load_lds((const unsigned*)((const char*)(gbase) + (voff)[_i]), (LAS unsigned*)(lds + (bufoff) + ldsw + _i * 8192), 16, 0, 0); } while (0)
; #define PG8_LDA(dst, b, h) do { _Pragma("unroll") for (int m = 0; m < 4; ++m) _Pragma("unroll") for (int k = 0; k < 2; ++k) dst[m][k] = *(const LAS bf16x8*)(lds + PG8_SA(b, h) + aoff + m * 2048 + k * 1024); } while (0)
; #define PG8_LDB(dst, b, h) do { _Pragma("unroll") for (int n = 0; n < 2; ++n) _Pragma("unroll") for (int k = 0; k < 2; ++k) dst[n][k] = *(const LAS bf16x8*)(lds + PG8_SB(b, h) + boff + n * 2048 + k * 1024); } while (0)
; #define PG8_MMA(ai, bj, At, Bt) do { __builtin_amdgcn_s_setprio(1); _Pragma("unroll") for (int m = 0; m < 4; ++m) _Pragma("unroll") for (int n = 0; n < 2; ++n) _Pragma("unroll") for (int k = 0; k < 2; ++k) \
;         acc[ai][bj][m][n] = __builtin_amdgcn_mfma_f32_16x16x32_bf16(Bt[n][k], At[m][k], acc[ai][bj][m][n], 0, 0, 0); __builtin_amdgcn_s_setprio(0); } while (0)
; #define PG8_WAIT_L(n) asm volatile("s_waitcnt lgkmcnt(" #n ")" ::: "memory")
; #define PG8_BAR __builtin_amdgcn_s_barrier()
; #define PG8_SCHED __builtin_amdgcn_sched_barrier(0)
; template <class Epi, class Sched>
; __device__ __forceinline__ void gemm_phase(LAS unsigned char* lds, const Gemm g, const Sched& S, const Epi& E) {
;     ...
;             PG8_LDB(B0, 1, 0); PG8_SCHED; PG8_LDA(At, 1, 0); PG8_STAGE(PG8_SA(0, 1), a2 + hstep, voffA);
;             PG8_WAIT_L(8); PG8_BAR; PG8_WAIT_L(0); PG8_MMA(0, 0, At, B0); PG8_BAR; PG8_SCHED;
;             PG8_LDB(B1, 1, 1); PG8_STAGE(PG8_SB(1, 0), b3, voffB);
;             PG8_BAR; PG8_WAIT_L(0); PG8_MMA(0, 1, At, B1); PG8_BAR;
;             PG8_LDA(At, 1, 1); PG8_STAGE(PG8_SA(1, 0), a3, voffA);
;             PG8_BAR; PG8_WAIT_L(0); PG8_MMA(1, 0, At, B0); PG8_BAR; PG8_SCHED;
	s_add_u32 s38, s56, 0x80000
	s_addc_u32 s39, s57, 0
	s_add_i32 s52, s52, s65
	v_lshl_add_u64 v[140:141], s[38:39], 0, v[0:1]
	s_mov_b32 m0, s52
	s_nop 0
	global_load_lds_dwordx4 v[140:141], off
	v_lshl_add_u64 v[140:141], s[38:39], 0, v[130:131]
	s_add_i32 m0, s52, 0x2000
	s_nop 0
	global_load_lds_dwordx4 v[140:141], off
	s_add_u32 s38, s58, 0x80000
	s_addc_u32 s39, s59, 0
	s_mov_b32 m0, s66
	v_lshl_add_u64 v[192:193], s[38:39], 0, v[0:1]
	global_load_lds_dwordx4 v[192:193], off
	v_lshl_add_u64 v[192:193], s[38:39], 0, v[130:131]
	s_mov_b32 m0, s67
	s_nop 0
	global_load_lds_dwordx4 v[192:193], off
	s_add_i32 s52, 0, 0x18000
	v_add_u32_e32 v152, s52, v137
	ds_read_b128 v[140:143], v152
	ds_read_b128 v[144:147], v152 offset:1024
	ds_read_b128 v[148:151], v152 offset:2048
	ds_read_b128 v[152:155], v152 offset:3072
	ds_read_b128 v[160:163], v139 offset:32768
	ds_read_b128 v[164:167], v139 offset:33792
	ds_read_b128 v[168:171], v139 offset:34816
	ds_read_b128 v[172:175], v139 offset:35840
	ds_read_b128 v[176:179], v139 offset:36864
	ds_read_b128 v[180:183], v139 offset:37888
	ds_read_b128 v[184:187], v139 offset:38912
	ds_read_b128 v[188:191], v139 offset:39936
	s_add_i32 s53, 0, 0x1c000
	v_add_u32_e32 v204, s53, v137
	ds_read_b128 v[192:195], v204
	ds_read_b128 v[196:199], v204 offset:1024
	ds_read_b128 v[200:203], v204 offset:2048
	ds_read_b128 v[204:207], v204 offset:3072
	s_waitcnt lgkmcnt(0)
	s_barrier
	s_setprio 1
	v_mfma_f32_16x16x32_bf16 v[126:129], v[140:143], v[160:163], v[126:129]
	v_mfma_f32_16x16x32_bf16 v[122:125], v[148:151], v[160:163], v[122:125]
	v_mfma_f32_16x16x32_bf16 v[118:121], v[140:143], v[168:171], v[118:121]
	v_mfma_f32_16x16x32_bf16 v[114:117], v[148:151], v[168:171], v[114:117]
	v_mfma_f32_16x16x32_bf16 v[106:109], v[140:143], v[176:179], v[106:109]
	v_mfma_f32_16x16x32_bf16 v[98:101], v[148:151], v[176:179], v[98:101]
	v_mfma_f32_16x16x32_bf16 v[90:93], v[140:143], v[184:187], v[90:93]
	v_mfma_f32_16x16x32_bf16 v[82:85], v[148:151], v[184:187], v[82:85]
	v_mfma_f32_16x16x32_bf16 v[126:129], v[144:147], v[164:167], v[126:129]
	v_mfma_f32_16x16x32_bf16 v[122:125], v[152:155], v[164:167], v[122:125]
	v_mfma_f32_16x16x32_bf16 v[118:121], v[144:147], v[172:175], v[118:121]
	v_mfma_f32_16x16x32_bf16 v[114:117], v[152:155], v[172:175], v[114:117]
	v_mfma_f32_16x16x32_bf16 v[106:109], v[144:147], v[180:183], v[106:109]
	v_mfma_f32_16x16x32_bf16 v[98:101], v[152:155], v[180:183], v[98:101]
	v_mfma_f32_16x16x32_bf16 v[90:93], v[144:147], v[188:191], v[90:93]
	v_mfma_f32_16x16x32_bf16 v[82:85], v[152:155], v[188:191], v[82:85]
	v_mfma_f32_16x16x32_bf16 v[110:113], v[192:195], v[160:163], v[110:113]
	v_mfma_f32_16x16x32_bf16 v[102:105], v[200:203], v[160:163], v[102:105]
	v_mfma_f32_16x16x32_bf16 v[94:97], v[192:195], v[168:171], v[94:97]
	v_mfma_f32_16x16x32_bf16 v[86:89], v[200:203], v[168:171], v[86:89]
	v_mfma_f32_16x16x32_bf16 v[78:81], v[192:195], v[176:179], v[78:81]
	v_mfma_f32_16x16x32_bf16 v[74:77], v[200:203], v[176:179], v[74:77]
	v_mfma_f32_16x16x32_bf16 v[70:73], v[192:195], v[184:187], v[70:73]
	v_mfma_f32_16x16x32_bf16 v[66:69], v[200:203], v[184:187], v[66:69]
	v_mfma_f32_16x16x32_bf16 v[110:113], v[196:199], v[164:167], v[110:113]
	v_mfma_f32_16x16x32_bf16 v[102:105], v[204:207], v[164:167], v[102:105]
	v_mfma_f32_16x16x32_bf16 v[94:97], v[196:199], v[172:175], v[94:97]
	v_mfma_f32_16x16x32_bf16 v[86:89], v[204:207], v[172:175], v[86:89]
	v_mfma_f32_16x16x32_bf16 v[78:81], v[196:199], v[180:183], v[78:81]
	v_mfma_f32_16x16x32_bf16 v[74:77], v[204:207], v[180:183], v[74:77]
	v_mfma_f32_16x16x32_bf16 v[70:73], v[196:199], v[188:191], v[70:73]
	v_mfma_f32_16x16x32_bf16 v[66:69], v[204:207], v[188:191], v[66:69]
	s_setprio 0
	s_barrier
	s_add_i32 s38, s52, s65
	v_lshl_add_u64 v[156:157], v[156:157], 0, s[36:37]
	s_mov_b32 m0, s38
	s_nop 0
	global_load_lds_dwordx4 v[156:157], off
	v_lshl_add_u64 v[156:157], v[210:211], 0, s[36:37]
	s_add_i32 m0, s38, 0x2000
	s_nop 0
	global_load_lds_dwordx4 v[156:157], off
	s_mov_b32 m0, s68
	v_lshl_add_u64 v[156:157], v[212:213], 0, s[36:37]
	global_load_lds_dwordx4 v[156:157], off
	v_lshl_add_u64 v[156:157], v[214:215], 0, s[36:37]
	s_mov_b32 m0, s69
	s_nop 0
	global_load_lds_dwordx4 v[156:157], off
	ds_read_b128 v[160:163], v139 offset:49152
	ds_read_b128 v[164:167], v139 offset:50176
	ds_read_b128 v[168:171], v139 offset:51200
	ds_read_b128 v[172:175], v139 offset:52224
	ds_read_b128 v[176:179], v139 offset:53248
	ds_read_b128 v[180:183], v139 offset:54272
	ds_read_b128 v[184:187], v139 offset:55296
	ds_read_b128 v[188:191], v139 offset:56320
	s_waitcnt vmcnt(4)
	s_waitcnt lgkmcnt(0)
	s_barrier
; #define PG8_STAGE(bufoff, gbase, voff) do { _Pragma("unroll") for (int _i = 0; _i < 2; ++_i) \
;         __builtin_amdgcn_global_load_lds((const unsigned*)((const char*)(gbase) + (voff)[_i]), (LAS unsigned*)(lds + (bufoff) + ldsw + _i * 8192), 16, 0, 0); } while (0)
; #define PG8_MMA(ai, bj, At, Bt) do { __builtin_amdgcn_s_setprio(1); _Pragma("unroll") for (int m = 0; m < 4; ++m) _Pragma("unroll") for (int n = 0; n < 2; ++n) _Pragma("unroll") for (int k = 0; k < 2; ++k) \
;         acc[ai][bj][m][n] = __builtin_amdgcn_mfma_f32_16x16x32_bf16(Bt[n][k], At[m][k], acc[ai][bj][m][n], 0, 0, 0); __builtin_amdgcn_s_setprio(0); } while (0)
; #define PG8_WAIT_V(n) asm volatile("s_waitcnt vmcnt(" #n ")" ::: "memory")
; #define PG8_BAR __builtin_amdgcn_s_barrier()
;     __device__ __forceinline__ void operator()(const f32x4 (&acc)[2][2][4][2], const Unit& u, int wr, int wc, int fr, int fq) const {
;         const int row0 = u.pm * BM + wr * 64 + fr, col0 = u.pn * BM + wc * 32 + 4 * fq;
;         float* base = part + (size_t)u.ks * Mp * ldc;
; #pragma unroll
;         for (int ai = 0; ai < 2; ++ai)
; #pragma unroll
;             for (int m = 0; m < 4; ++m) { float* rowp = base + (size_t)(row0 + ai * HALF + m * 16) * ldc + col0;
; #pragma unroll
;                 for (int bj = 0; bj < 2; ++bj)
; #pragma unroll
;                     for (int n = 0; n < 2; ++n) *(f32x4*)(rowp + bj * HALF + n * 16) = acc[ai][bj][m][n]; }
;     }
; template <class Epi, class Sched>
; __device__ __forceinline__ void gemm_phase(LAS unsigned char* lds, const Gemm g, const Sched& S, const Epi& E) {
;     ...
;             PG8_STAGE(PG8_SB(1, 1), b3 + hstep, voffB);
;             PG8_WAIT_V(6); PG8_BAR; PG8_MMA(1, 1, At, B1); PG8_BAR;
;         }
;         E(acc, cur, wr, wc, fr, fq);
;         if (!has_next) break;
	s_setprio 1
	v_mfma_f32_16x16x32_bf16 v[62:65], v[140:143], v[160:163], v[62:65]
	v_mfma_f32_16x16x32_bf16 v[58:61], v[148:151], v[160:163], v[58:61]
	v_mfma_f32_16x16x32_bf16 v[54:57], v[140:143], v[168:171], v[54:57]
	v_mfma_f32_16x16x32_bf16 v[50:53], v[148:151], v[168:171], v[50:53]
	v_mfma_f32_16x16x32_bf16 v[38:41], v[140:143], v[176:179], v[38:41]
	v_mfma_f32_16x16x32_bf16 v[34:37], v[148:151], v[176:179], v[34:37]
	v_mfma_f32_16x16x32_bf16 v[22:25], v[140:143], v[184:187], v[22:25]
	v_mfma_f32_16x16x32_bf16 v[18:21], v[148:151], v[184:187], v[18:21]
	v_mfma_f32_16x16x32_bf16 v[62:65], v[144:147], v[164:167], v[62:65]
	v_mfma_f32_16x16x32_bf16 v[58:61], v[152:155], v[164:167], v[58:61]
	v_mfma_f32_16x16x32_bf16 v[54:57], v[144:147], v[172:175], v[54:57]
	v_mfma_f32_16x16x32_bf16 v[50:53], v[152:155], v[172:175], v[50:53]
	v_mfma_f32_16x16x32_bf16 v[38:41], v[144:147], v[180:183], v[38:41]
	v_mfma_f32_16x16x32_bf16 v[34:37], v[152:155], v[180:183], v[34:37]
	v_mfma_f32_16x16x32_bf16 v[22:25], v[144:147], v[188:191], v[22:25]
	v_mfma_f32_16x16x32_bf16 v[18:21], v[152:155], v[188:191], v[18:21]
	s_add_u32 s38, s56, 0x80080
	s_addc_u32 s39, s57, 0
	s_add_i32 s52, s53, s65
	v_lshl_add_u64 v[140:141], s[38:39], 0, v[0:1]
	s_mov_b32 m0, s52
	s_nop 0
	global_load_lds_dwordx4 v[140:141], off
	v_lshl_add_u64 v[140:141], s[38:39], 0, v[130:131]
	s_add_i32 m0, s52, 0x2000
	s_nop 0
	global_load_lds_dwordx4 v[140:141], off
	v_mfma_f32_16x16x32_bf16 v[46:49], v[192:195], v[160:163], v[46:49]
	v_mfma_f32_16x16x32_bf16 v[42:45], v[200:203], v[160:163], v[42:45]
	v_mfma_f32_16x16x32_bf16 v[30:33], v[192:195], v[168:171], v[30:33]
	v_mfma_f32_16x16x32_bf16 v[26:29], v[200:203], v[168:171], v[26:29]
	v_mfma_f32_16x16x32_bf16 v[14:17], v[192:195], v[176:179], v[14:17]
	v_mfma_f32_16x16x32_bf16 v[10:13], v[200:203], v[176:179], v[10:13]
	v_mfma_f32_16x16x32_bf16 v[6:9], v[192:195], v[184:187], v[6:9]
	v_mfma_f32_16x16x32_bf16 v[2:5], v[200:203], v[184:187], v[2:5]
	v_mfma_f32_16x16x32_bf16 v[46:49], v[196:199], v[164:167], v[46:49]
	v_mfma_f32_16x16x32_bf16 v[42:45], v[204:207], v[164:167], v[42:45]
	v_mfma_f32_16x16x32_bf16 v[30:33], v[196:199], v[172:175], v[30:33]
	v_mfma_f32_16x16x32_bf16 v[26:29], v[204:207], v[172:175], v[26:29]
	v_mfma_f32_16x16x32_bf16 v[14:17], v[196:199], v[180:183], v[14:17]
	v_mfma_f32_16x16x32_bf16 v[10:13], v[204:207], v[180:183], v[10:13]
	v_mfma_f32_16x16x32_bf16 v[6:9], v[196:199], v[188:191], v[6:9]
	v_mfma_f32_16x16x32_bf16 v[2:5], v[204:207], v[188:191], v[2:5]
	s_setprio 0
	s_add_i32 s73, s73, 2
	s_add_u32 s71, s71, 0x100
	s_addc_u32 s72, s72, 0
	s_cmp_gt_u32 s73, 5
	s_mov_b64 s[52:53], s[54:55]
	s_barrier
	s_cbranch_scc0 .LBB0_113
	s_ashr_i32 s11, s10, 31
	s_lshl_b64 s[10:11], s[10:11], 24
	v_lshl_or_b32 v140, s26, 8, v138
	s_add_u32 s10, s8, s10
	v_lshl_add_u32 v142, s24, 8, v136
	s_addc_u32 s11, s9, s11
	v_ashrrev_i32_e32 v141, 31, v140
	v_ashrrev_i32_e32 v143, 31, v142
	v_lshl_add_u64 v[140:141], v[140:141], 2, s[10:11]
	v_lshlrev_b64 v[144:145], 13, v[142:143]
	v_lshl_add_u64 v[144:145], v[140:141], 0, v[144:145]
	global_store_dwordx4 v[144:145], v[126:129], off
	global_store_dwordx4 v[144:145], v[122:125], off offset:64
	global_store_dwordx4 v[144:145], v[110:113], off offset:512
	global_store_dwordx4 v[144:145], v[102:105], off offset:576
	s_mov_b64 s[10:11], 0x100000
	s_mov_b32 s26, s40
	v_or_b32_e32 v102, 16, v142
	v_ashrrev_i32_e32 v103, 31, v102
	v_lshlrev_b64 v[102:103], 13, v[102:103]
	v_lshl_add_u64 v[102:103], v[140:141], 0, v[102:103]
	global_store_dwordx4 v[102:103], v[118:121], off
	global_store_dwordx4 v[102:103], v[114:117], off offset:64
	global_store_dwordx4 v[102:103], v[94:97], off offset:512
	global_store_dwordx4 v[102:103], v[86:89], off offset:576
	s_mov_b32 s24, s44
	s_mov_b64 s[54:55], s[50:51]
	v_or_b32_e32 v86, 32, v142
	v_ashrrev_i32_e32 v87, 31, v86
	v_lshlrev_b64 v[86:87], 13, v[86:87]
	v_lshl_add_u64 v[86:87], v[140:141], 0, v[86:87]
	global_store_dwordx4 v[86:87], v[106:109], off
	global_store_dwordx4 v[86:87], v[98:101], off offset:64
	global_store_dwordx4 v[86:87], v[78:81], off offset:512
	global_store_dwordx4 v[86:87], v[74:77], off offset:576
	s_mov_b64 s[52:53], s[48:49]
	s_nop 0
	v_or_b32_e32 v74, 48, v142
	v_ashrrev_i32_e32 v75, 31, v74
	v_lshlrev_b64 v[74:75], 13, v[74:75]
	v_lshl_add_u64 v[74:75], v[140:141], 0, v[74:75]
	global_store_dwordx4 v[74:75], v[90:93], off
	global_store_dwordx4 v[74:75], v[82:85], off offset:64
	global_store_dwordx4 v[74:75], v[70:73], off offset:512
	global_store_dwordx4 v[74:75], v[66:69], off offset:576
	s_nop 1
	v_add_co_u32_e32 v68, vcc, s93, v144
	v_lshl_add_u64 v[66:67], v[144:145], 0, s[10:11]
	s_nop 0
	v_addc_co_u32_e32 v69, vcc, 0, v145, vcc
	s_mov_b64 s[10:11], 0x120000
	global_store_dwordx4 v[68:69], v[62:65], off
	global_store_dwordx4 v[66:67], v[58:61], off offset:64
	global_store_dwordx4 v[66:67], v[46:49], off offset:512
	global_store_dwordx4 v[66:67], v[42:45], off offset:576
	s_nop 1
	v_lshl_add_u64 v[42:43], v[144:145], 0, s[10:11]
	s_mov_b32 s10, 0x120000
	v_add_co_u32_e32 v44, vcc, s10, v144
	s_mov_b64 s[10:11], 0x140000
	s_nop 0
	v_addc_co_u32_e32 v45, vcc, 0, v145, vcc
	global_store_dwordx4 v[44:45], v[54:57], off
	global_store_dwordx4 v[42:43], v[50:53], off offset:64
	global_store_dwordx4 v[42:43], v[30:33], off offset:512
	global_store_dwordx4 v[42:43], v[26:29], off offset:576
	s_nop 1
	v_lshl_add_u64 v[26:27], v[144:145], 0, s[10:11]
	s_mov_b32 s10, 0x140000
	v_add_co_u32_e32 v28, vcc, s10, v144
	s_mov_b64 s[10:11], 0x160000
	s_nop 0
	v_addc_co_u32_e32 v29, vcc, 0, v145, vcc
	global_store_dwordx4 v[28:29], v[38:41], off
	global_store_dwordx4 v[26:27], v[34:37], off offset:64
	global_store_dwordx4 v[26:27], v[14:17], off offset:512
	global_store_dwordx4 v[26:27], v[10:13], off offset:576
	s_nop 1
	v_add_co_u32_e32 v12, vcc, 0x160000, v144
	v_lshl_add_u64 v[10:11], v[144:145], 0, s[10:11]
	s_nop 0
	v_addc_co_u32_e32 v13, vcc, 0, v145, vcc
	s_and_b64 vcc, exec, s[46:47]
	s_mov_b32 s10, s28
	global_store_dwordx4 v[12:13], v[22:25], off
	global_store_dwordx4 v[10:11], v[18:21], off offset:64
	global_store_dwordx4 v[10:11], v[6:9], off offset:512
	global_store_dwordx4 v[10:11], v[2:5], off offset:576
	s_cbranch_vccz .LBB0_110
	s_waitcnt vmcnt(0)
	s_cmpk_gt_u32 s60, 0xff
	s_cbranch_scc1 .LBB0_117
	s_barrier

; #define PG8_STAGE(bufoff, gbase, voff) do { _Pragma("unroll") for (int _i = 0; _i < 2; ++_i) \
;         __builtin_amdgcn_global_load_lds((const unsigned*)((const char*)(gbase) + (voff)[_i]), (LAS unsigned*)(lds + (bufoff) + ldsw + _i * 8192), 16, 0, 0); } while (0)
; #define PG8_LDA(dst, b, h) do { _Pragma("unroll") for (int m = 0; m < 4; ++m) _Pragma("unroll") for (int k = 0; k < 2; ++k) dst[m][k] = *(const LAS bf16x8*)(lds + PG8_SA(b, h) + aoff + m * 2048 + k * 1024); } while (0)
; #define PG8_LDB(dst, b, h) do { _Pragma("unroll") for (int n = 0; n < 2; ++n) _Pragma("unroll") for (int k = 0; k < 2; ++k) dst[n][k] = *(const LAS bf16x8*)(lds + PG8_SB(b, h) + boff + n * 2048 + k * 1024); } while (0)
; #define PG8_MMA(ai, bj, At, Bt) do { __builtin_amdgcn_s_setprio(1); _Pragma("unroll") for (int m = 0; m < 4; ++m) _Pragma("unroll") for (int n = 0; n < 2; ++n) _Pragma("unroll") for (int k = 0; k < 2; ++k) \
;         acc[ai][bj][m][n] = __builtin_amdgcn_mfma_f32_16x16x32_bf16(Bt[n][k], At[m][k], acc[ai][bj][m][n], 0, 0, 0); __builtin_amdgcn_s_setprio(0); } while (0)
; #define PG8_WAIT_V(n) asm volatile("s_waitcnt vmcnt(" #n ")" ::: "memory")
; #define PG8_WAIT_L(n) asm volatile("s_waitcnt lgkmcnt(" #n ")" ::: "memory")
; template <class Epi, class Sched>
; __device__ __forceinline__ void gemm_phase(LAS unsigned char* lds, const Gemm g, const Sched& S, const Epi& E) {
;     ...
;         for (int t = 0; t < nt; t += 2) {
;             const bool last = (t == nt - 2);
;             const char* a1 = cA + (size_t)(t + 1) * kstep;
;             const char* a2 = last ? nA : cA + (size_t)(t + 2) * kstep; const char* b2 = last ? nB : cB + (size_t)(t + 2) * kstep;
;             const char* a3 = a2 + kstep; const char* b3 = b2 + kstep;
;             PG8_LDB(B0, 0, 0); PG8_SCHED; PG8_LDA(At, 0, 0); PG8_STAGE(PG8_SA(1, 1), a1 + hstep, voffA);
;             PG8_WAIT_L(8); PG8_BAR; PG8_WAIT_L(0); PG8_MMA(0, 0, At, B0); PG8_BAR; PG8_SCHED;
;             PG8_LDB(B1, 0, 1); PG8_STAGE(PG8_SB(0, 0), b2, voffB);
;             PG8_BAR; PG8_WAIT_L(0); PG8_MMA(0, 1, At, B1); PG8_BAR;
;             PG8_LDA(At, 0, 1); PG8_STAGE(PG8_SA(0, 0), a2, voffA);
;             PG8_BAR; PG8_WAIT_L(0); PG8_MMA(1, 0, At, B0); PG8_BAR; PG8_SCHED;
;             PG8_STAGE(PG8_SB(0, 1), b2 + hstep, voffB);
;             PG8_WAIT_V(6); PG8_BAR; PG8_MMA(1, 1, At, B1); PG8_BAR;
.LBB0_354:
	s_add_u32 s38, s50, 0xfff80080
	s_addc_u32 s39, s51, -1
	s_cmp_eq_u32 s70, 28
	s_cselect_b32 s55, s9, s39
	s_cselect_b32 s54, s66, s38
	s_cselect_b32 s53, s43, s69
	s_cselect_b32 s52, s67, s68
	v_lshl_add_u64 v[156:157], s[50:51], 0, v[138:139]
	s_add_i32 m0, s29, 0xc000
	s_nop 0
	global_load_lds_dwordx4 v[156:157], off
	v_lshl_add_u64 v[156:157], s[50:51], 0, v[136:137]
	s_add_i32 m0, s29, 0xe000
	s_nop 0
	global_load_lds_dwordx4 v[156:157], off
	s_add_i32 s71, 0, 0x10000
	v_add_u32_e32 v156, s71, v145
	ds_read_b128 v[140:143], v156
	ds_read_b128 v[148:151], v156 offset:1024
	ds_read_b128 v[152:155], v156 offset:2048
	ds_read_b128 v[160:163], v156 offset:3072
	ds_read_b128 v[164:167], v147
	ds_read_b128 v[168:171], v147 offset:1024
	ds_read_b128 v[172:175], v147 offset:2048
	ds_read_b128 v[176:179], v147 offset:3072
	ds_read_b128 v[180:183], v147 offset:4096
	ds_read_b128 v[184:187], v147 offset:5120
	ds_read_b128 v[188:191], v147 offset:6144
	ds_read_b128 v[192:195], v147 offset:7168
	s_add_i32 s38, 0, 0x14000
	v_add_u32_e32 v156, s38, v145
	ds_read_b128 v[196:199], v156
	ds_read_b128 v[200:203], v156 offset:1024
	ds_read_b128 v[204:207], v156 offset:2048
	ds_read_b128 v[210:213], v156 offset:3072
	s_waitcnt lgkmcnt(0)
	s_barrier
	s_setprio 1
	v_mfma_f32_16x16x32_bf16 v[126:129], v[140:143], v[164:167], v[126:129]
	v_mfma_f32_16x16x32_bf16 v[122:125], v[152:155], v[164:167], v[122:125]
	v_mfma_f32_16x16x32_bf16 v[118:121], v[140:143], v[172:175], v[118:121]
	v_mfma_f32_16x16x32_bf16 v[110:113], v[152:155], v[172:175], v[110:113]
	v_mfma_f32_16x16x32_bf16 v[102:105], v[140:143], v[180:183], v[102:105]
	v_mfma_f32_16x16x32_bf16 v[94:97], v[152:155], v[180:183], v[94:97]
	v_mfma_f32_16x16x32_bf16 v[86:89], v[140:143], v[188:191], v[86:89]
	v_mfma_f32_16x16x32_bf16 v[78:81], v[152:155], v[188:191], v[78:81]
	v_mfma_f32_16x16x32_bf16 v[126:129], v[148:151], v[168:171], v[126:129]
	v_mfma_f32_16x16x32_bf16 v[122:125], v[160:163], v[168:171], v[122:125]
	v_mfma_f32_16x16x32_bf16 v[118:121], v[148:151], v[176:179], v[118:121]
	v_mfma_f32_16x16x32_bf16 v[110:113], v[160:163], v[176:179], v[110:113]
	v_mfma_f32_16x16x32_bf16 v[102:105], v[148:151], v[184:187], v[102:105]
	v_mfma_f32_16x16x32_bf16 v[94:97], v[160:163], v[184:187], v[94:97]
	v_mfma_f32_16x16x32_bf16 v[86:89], v[148:151], v[192:195], v[86:89]
	v_mfma_f32_16x16x32_bf16 v[78:81], v[160:163], v[192:195], v[78:81]
	v_mfma_f32_16x16x32_bf16 v[114:117], v[196:199], v[164:167], v[114:117]
	v_mfma_f32_16x16x32_bf16 v[106:109], v[204:207], v[164:167], v[106:109]
	v_mfma_f32_16x16x32_bf16 v[98:101], v[196:199], v[172:175], v[98:101]
	v_mfma_f32_16x16x32_bf16 v[90:93], v[204:207], v[172:175], v[90:93]
	v_mfma_f32_16x16x32_bf16 v[82:85], v[196:199], v[180:183], v[82:85]
	v_mfma_f32_16x16x32_bf16 v[74:77], v[204:207], v[180:183], v[74:77]
	v_mfma_f32_16x16x32_bf16 v[70:73], v[196:199], v[188:191], v[70:73]
	v_mfma_f32_16x16x32_bf16 v[66:69], v[204:207], v[188:191], v[66:69]
	v_mfma_f32_16x16x32_bf16 v[114:117], v[200:203], v[168:171], v[114:117]
	v_mfma_f32_16x16x32_bf16 v[106:109], v[210:213], v[168:171], v[106:109]
	v_mfma_f32_16x16x32_bf16 v[98:101], v[200:203], v[176:179], v[98:101]
	v_mfma_f32_16x16x32_bf16 v[90:93], v[210:213], v[176:179], v[90:93]
	v_mfma_f32_16x16x32_bf16 v[82:85], v[200:203], v[184:187], v[82:85]
	v_mfma_f32_16x16x32_bf16 v[74:77], v[210:213], v[184:187], v[74:77]
	v_mfma_f32_16x16x32_bf16 v[70:73], v[200:203], v[192:195], v[70:73]
	v_mfma_f32_16x16x32_bf16 v[66:69], v[210:213], v[192:195], v[66:69]
	s_setprio 0
	s_barrier
	s_add_i32 s39, s71, s56
	v_lshl_add_u64 v[156:157], s[52:53], 0, v[0:1]
	s_mov_b32 m0, s39
	v_lshl_add_u64 v[214:215], s[52:53], 0, v[134:135]
	global_load_lds_dwordx4 v[156:157], off
	s_add_i32 m0, s39, 0x2000
	s_nop 0
	global_load_lds_dwordx4 v[214:215], off
	s_mov_b32 m0, s29
	v_lshl_add_u64 v[216:217], s[54:55], 0, v[130:131]
	global_load_lds_dwordx4 v[216:217], off
	v_lshl_add_u64 v[224:225], s[54:55], 0, v[132:133]
	s_mov_b32 m0, s41
	s_nop 0
	global_load_lds_dwordx4 v[224:225], off
	ds_read_b128 v[164:167], v147 offset:16384
	ds_read_b128 v[168:171], v147 offset:17408
	ds_read_b128 v[172:175], v147 offset:18432
	ds_read_b128 v[176:179], v147 offset:19456
	ds_read_b128 v[180:183], v147 offset:20480
	ds_read_b128 v[184:187], v147 offset:21504
	ds_read_b128 v[188:191], v147 offset:22528
	ds_read_b128 v[192:195], v147 offset:23552
	s_waitcnt vmcnt(4)
	s_waitcnt lgkmcnt(0)
	s_barrier
	s_setprio 1
	v_mfma_f32_16x16x32_bf16 v[62:65], v[140:143], v[164:167], v[62:65]
	v_mfma_f32_16x16x32_bf16 v[58:61], v[152:155], v[164:167], v[58:61]
	v_mfma_f32_16x16x32_bf16 v[54:57], v[140:143], v[172:175], v[54:57]
	v_mfma_f32_16x16x32_bf16 v[46:49], v[152:155], v[172:175], v[46:49]
	v_mfma_f32_16x16x32_bf16 v[38:41], v[140:143], v[180:183], v[38:41]
	v_mfma_f32_16x16x32_bf16 v[30:33], v[152:155], v[180:183], v[30:33]
	v_mfma_f32_16x16x32_bf16 v[22:25], v[140:143], v[188:191], v[22:25]
	v_mfma_f32_16x16x32_bf16 v[14:17], v[152:155], v[188:191], v[14:17]
	v_mfma_f32_16x16x32_bf16 v[62:65], v[148:151], v[168:171], v[62:65]
	v_mfma_f32_16x16x32_bf16 v[58:61], v[160:163], v[168:171], v[58:61]
	v_mfma_f32_16x16x32_bf16 v[54:57], v[148:151], v[176:179], v[54:57]
	v_mfma_f32_16x16x32_bf16 v[46:49], v[160:163], v[176:179], v[46:49]
	v_mfma_f32_16x16x32_bf16 v[38:41], v[148:151], v[184:187], v[38:41]
	v_mfma_f32_16x16x32_bf16 v[30:33], v[160:163], v[184:187], v[30:33]
	v_mfma_f32_16x16x32_bf16 v[22:25], v[148:151], v[192:195], v[22:25]
	v_mfma_f32_16x16x32_bf16 v[14:17], v[160:163], v[192:195], v[14:17]
	v_mfma_f32_16x16x32_bf16 v[50:53], v[196:199], v[164:167], v[50:53]
	v_mfma_f32_16x16x32_bf16 v[42:45], v[204:207], v[164:167], v[42:45]
	v_mfma_f32_16x16x32_bf16 v[34:37], v[196:199], v[172:175], v[34:37]
	v_mfma_f32_16x16x32_bf16 v[26:29], v[204:207], v[172:175], v[26:29]
	v_mfma_f32_16x16x32_bf16 v[18:21], v[196:199], v[180:183], v[18:21]
	v_mfma_f32_16x16x32_bf16 v[10:13], v[204:207], v[180:183], v[10:13]
	v_mfma_f32_16x16x32_bf16 v[6:9], v[196:199], v[188:191], v[6:9]
	v_mfma_f32_16x16x32_bf16 v[2:5], v[204:207], v[188:191], v[2:5]
	v_mfma_f32_16x16x32_bf16 v[50:53], v[200:203], v[168:171], v[50:53]
	v_mfma_f32_16x16x32_bf16 v[42:45], v[210:213], v[168:171], v[42:45]
	v_mfma_f32_16x16x32_bf16 v[34:37], v[200:203], v[176:179], v[34:37]
	v_mfma_f32_16x16x32_bf16 v[26:29], v[210:213], v[176:179], v[26:29]
	v_mfma_f32_16x16x32_bf16 v[18:21], v[200:203], v[184:187], v[18:21]
	v_mfma_f32_16x16x32_bf16 v[10:13], v[210:213], v[184:187], v[10:13]
	v_mfma_f32_16x16x32_bf16 v[6:9], v[200:203], v[192:195], v[6:9]
	v_mfma_f32_16x16x32_bf16 v[2:5], v[210:213], v[192:195], v[2:5]
	s_setprio 0
	s_barrier
; #define PG8_STAGE(bufoff, gbase, voff) do { _Pragma("unroll") for (int _i = 0; _i < 2; ++_i) \
;         __builtin_amdgcn_global_load_lds((const unsigned*)((const char*)(gbase) + (voff)[_i]), (LAS unsigned*)(lds + (bufoff) + ldsw + _i * 8192), 16, 0, 0); } while (0)
; #define PG8_LDA(dst, b, h) do { _Pragma("unroll") for (int m = 0; m < 4; ++m) _Pragma("unroll") for (int k = 0; k < 2; ++k) dst[m][k] = *(const LAS bf16x8*)(lds + PG8_SA(b, h) + aoff + m * 2048 + k * 1024); } while (0)
; #define PG8_LDB(dst, b, h) do { _Pragma("unroll") for (int n = 0; n < 2; ++n) _Pragma("unroll") for (int k = 0; k < 2; ++k) dst[n][k] = *(const LAS bf16x8*)(lds + PG8_SB(b, h) + boff + n * 2048 + k * 1024); } while (0)
; #define PG8_MMA(ai, bj, At, Bt) do { __builtin_amdgcn_s_setprio(1); _Pragma("unroll") for (int m = 0; m < 4; ++m) _Pragma("unroll") for (int n = 0; n < 2; ++n) _Pragma("unroll") for (int k = 0; k < 2; ++k) \
;         acc[ai][bj][m][n] = __builtin_amdgcn_mfma_f32_16x16x32_bf16(Bt[n][k], At[m][k], acc[ai][bj][m][n], 0, 0, 0); __builtin_amdgcn_s_setprio(0); } while (0)
; #define PG8_WAIT_L(n) asm volatile("s_waitcnt lgkmcnt(" #n ")" ::: "memory")
; #define PG8_BAR __builtin_amdgcn_s_barrier()
; #define PG8_SCHED __builtin_amdgcn_sched_barrier(0)
; template <class Epi, class Sched>
; __device__ __forceinline__ void gemm_phase(LAS unsigned char* lds, const Gemm g, const Sched& S, const Epi& E) {
;     ...
;             PG8_LDB(B0, 1, 0); PG8_SCHED; PG8_LDA(At, 1, 0); PG8_STAGE(PG8_SA(0, 1), a2 + hstep, voffA);
;             PG8_WAIT_L(8); PG8_BAR; PG8_WAIT_L(0); PG8_MMA(0, 0, At, B0); PG8_BAR; PG8_SCHED;
;             PG8_LDB(B1, 1, 1); PG8_STAGE(PG8_SB(1, 0), b3, voffB);
;             PG8_BAR; PG8_WAIT_L(0); PG8_MMA(0, 1, At, B1); PG8_BAR;
;             PG8_LDA(At, 1, 1); PG8_STAGE(PG8_SA(1, 0), a3, voffA);
;             PG8_BAR; PG8_WAIT_L(0); PG8_MMA(1, 0, At, B0); PG8_BAR; PG8_SCHED;
	s_add_u32 s72, s52, 0x80000
	s_addc_u32 s73, s53, 0
	s_add_i32 s38, s38, s56
	v_lshl_add_u64 v[140:141], s[72:73], 0, v[0:1]
	s_mov_b32 m0, s38
	s_nop 0
	global_load_lds_dwordx4 v[140:141], off
	v_lshl_add_u64 v[140:141], s[72:73], 0, v[134:135]
	s_add_i32 m0, s38, 0x2000
	s_nop 0
	global_load_lds_dwordx4 v[140:141], off
	s_add_u32 s54, s54, 0x80000
	s_addc_u32 s55, s55, 0
	s_mov_b32 m0, s57
	v_lshl_add_u64 v[196:197], s[54:55], 0, v[130:131]
	global_load_lds_dwordx4 v[196:197], off
	v_lshl_add_u64 v[196:197], s[54:55], 0, v[132:133]
	s_mov_b32 m0, s58
	s_nop 0
	global_load_lds_dwordx4 v[196:197], off
	s_add_i32 s38, 0, 0x18000
	v_add_u32_e32 v160, s38, v145
	ds_read_b128 v[140:143], v160
	ds_read_b128 v[148:151], v160 offset:1024
	ds_read_b128 v[152:155], v160 offset:2048
	ds_read_b128 v[160:163], v160 offset:3072
	ds_read_b128 v[164:167], v147 offset:32768
	ds_read_b128 v[168:171], v147 offset:33792
	ds_read_b128 v[172:175], v147 offset:34816
	ds_read_b128 v[176:179], v147 offset:35840
	ds_read_b128 v[180:183], v147 offset:36864
	ds_read_b128 v[184:187], v147 offset:37888
	ds_read_b128 v[188:191], v147 offset:38912
	ds_read_b128 v[192:195], v147 offset:39936
	s_add_i32 s39, 0, 0x1c000
	v_add_u32_e32 v210, s39, v145
	ds_read_b128 v[196:199], v210
	ds_read_b128 v[200:203], v210 offset:1024
	ds_read_b128 v[204:207], v210 offset:2048
	ds_read_b128 v[210:213], v210 offset:3072
	s_waitcnt lgkmcnt(0)
	s_barrier
	s_setprio 1
	v_mfma_f32_16x16x32_bf16 v[126:129], v[140:143], v[164:167], v[126:129]
	v_mfma_f32_16x16x32_bf16 v[122:125], v[152:155], v[164:167], v[122:125]
	v_mfma_f32_16x16x32_bf16 v[118:121], v[140:143], v[172:175], v[118:121]
	v_mfma_f32_16x16x32_bf16 v[110:113], v[152:155], v[172:175], v[110:113]
	v_mfma_f32_16x16x32_bf16 v[102:105], v[140:143], v[180:183], v[102:105]
	v_mfma_f32_16x16x32_bf16 v[94:97], v[152:155], v[180:183], v[94:97]
	v_mfma_f32_16x16x32_bf16 v[86:89], v[140:143], v[188:191], v[86:89]
	v_mfma_f32_16x16x32_bf16 v[78:81], v[152:155], v[188:191], v[78:81]
	v_mfma_f32_16x16x32_bf16 v[126:129], v[148:151], v[168:171], v[126:129]
	v_mfma_f32_16x16x32_bf16 v[122:125], v[160:163], v[168:171], v[122:125]
	v_mfma_f32_16x16x32_bf16 v[118:121], v[148:151], v[176:179], v[118:121]
	v_mfma_f32_16x16x32_bf16 v[110:113], v[160:163], v[176:179], v[110:113]
	v_mfma_f32_16x16x32_bf16 v[102:105], v[148:151], v[184:187], v[102:105]
	v_mfma_f32_16x16x32_bf16 v[94:97], v[160:163], v[184:187], v[94:97]
	v_mfma_f32_16x16x32_bf16 v[86:89], v[148:151], v[192:195], v[86:89]
	v_mfma_f32_16x16x32_bf16 v[78:81], v[160:163], v[192:195], v[78:81]
	v_mfma_f32_16x16x32_bf16 v[114:117], v[196:199], v[164:167], v[114:117]
	v_mfma_f32_16x16x32_bf16 v[106:109], v[204:207], v[164:167], v[106:109]
	v_mfma_f32_16x16x32_bf16 v[98:101], v[196:199], v[172:175], v[98:101]
	v_mfma_f32_16x16x32_bf16 v[90:93], v[204:207], v[172:175], v[90:93]
	v_mfma_f32_16x16x32_bf16 v[82:85], v[196:199], v[180:183], v[82:85]
	v_mfma_f32_16x16x32_bf16 v[74:77], v[204:207], v[180:183], v[74:77]
	v_mfma_f32_16x16x32_bf16 v[70:73], v[196:199], v[188:191], v[70:73]
	v_mfma_f32_16x16x32_bf16 v[66:69], v[204:207], v[188:191], v[66:69]
	v_mfma_f32_16x16x32_bf16 v[114:117], v[200:203], v[168:171], v[114:117]
	v_mfma_f32_16x16x32_bf16 v[106:109], v[210:213], v[168:171], v[106:109]
	v_mfma_f32_16x16x32_bf16 v[98:101], v[200:203], v[176:179], v[98:101]
	v_mfma_f32_16x16x32_bf16 v[90:93], v[210:213], v[176:179], v[90:93]
	v_mfma_f32_16x16x32_bf16 v[82:85], v[200:203], v[184:187], v[82:85]
	v_mfma_f32_16x16x32_bf16 v[74:77], v[210:213], v[184:187], v[74:77]
	v_mfma_f32_16x16x32_bf16 v[70:73], v[200:203], v[192:195], v[70:73]
	v_mfma_f32_16x16x32_bf16 v[66:69], v[210:213], v[192:195], v[66:69]
	s_setprio 0
	s_barrier
	s_add_i32 s38, s38, s56
	v_lshl_add_u64 v[156:157], v[156:157], 0, s[36:37]
	s_mov_b32 m0, s38
	s_nop 0
	global_load_lds_dwordx4 v[156:157], off
	v_lshl_add_u64 v[156:157], v[214:215], 0, s[36:37]
	s_add_i32 m0, s38, 0x2000
	s_nop 0
	global_load_lds_dwordx4 v[156:157], off
	s_mov_b32 m0, s59
	v_lshl_add_u64 v[156:157], v[216:217], 0, s[36:37]
	global_load_lds_dwordx4 v[156:157], off
	v_lshl_add_u64 v[156:157], v[224:225], 0, s[36:37]
	s_mov_b32 m0, s60
	s_nop 0
	global_load_lds_dwordx4 v[156:157], off
	ds_read_b128 v[164:167], v147 offset:49152
	ds_read_b128 v[168:171], v147 offset:50176
	ds_read_b128 v[172:175], v147 offset:51200
	ds_read_b128 v[176:179], v147 offset:52224
	ds_read_b128 v[180:183], v147 offset:53248
	ds_read_b128 v[184:187], v147 offset:54272
	ds_read_b128 v[188:191], v147 offset:55296
	ds_read_b128 v[192:195], v147 offset:56320
	s_waitcnt vmcnt(4)
	s_waitcnt lgkmcnt(0)
	s_barrier
; #define PG8_STAGE(bufoff, gbase, voff) do { _Pragma("unroll") for (int _i = 0; _i < 2; ++_i) \
;         __builtin_amdgcn_global_load_lds((const unsigned*)((const char*)(gbase) + (voff)[_i]), (LAS unsigned*)(lds + (bufoff) + ldsw + _i * 8192), 16, 0, 0); } while (0)
; #define PG8_LDA(dst, b, h) do { _Pragma("unroll") for (int m = 0; m < 4; ++m) _Pragma("unroll") for (int k = 0; k < 2; ++k) dst[m][k] = *(const LAS bf16x8*)(lds + PG8_SA(b, h) + aoff + m * 2048 + k * 1024); } while (0)
; #define PG8_MMA(ai, bj, At, Bt) do { __builtin_amdgcn_s_setprio(1); _Pragma("unroll") for (int m = 0; m < 4; ++m) _Pragma("unroll") for (int n = 0; n < 2; ++n) _Pragma("unroll") for (int k = 0; k < 2; ++k) \
;         acc[ai][bj][m][n] = __builtin_amdgcn_mfma_f32_16x16x32_bf16(Bt[n][k], At[m][k], acc[ai][bj][m][n], 0, 0, 0); __builtin_amdgcn_s_setprio(0); } while (0)
; #define PG8_WAIT_V(n) asm volatile("s_waitcnt vmcnt(" #n ")" ::: "memory")
; #define PG8_WAIT_L(n) asm volatile("s_waitcnt lgkmcnt(" #n ")" ::: "memory")
; #define PG8_BAR __builtin_amdgcn_s_barrier()
; #define PG8_SCHED __builtin_amdgcn_sched_barrier(0)
; template <class Epi, class Sched>
; __device__ __forceinline__ void gemm_phase(LAS unsigned char* lds, const Gemm g, const Sched& S, const Epi& E) {
;     ...
;             PG8_LDA(At, 1, 1); PG8_STAGE(PG8_SA(1, 0), a3, voffA);
;             PG8_BAR; PG8_WAIT_L(0); PG8_MMA(1, 0, At, B0); PG8_BAR; PG8_SCHED;
;             PG8_STAGE(PG8_SB(1, 1), b3 + hstep, voffB);
;             PG8_WAIT_V(6); PG8_BAR; PG8_MMA(1, 1, At, B1); PG8_BAR;
;         }
	s_setprio 1
	v_mfma_f32_16x16x32_bf16 v[62:65], v[140:143], v[164:167], v[62:65]
	v_mfma_f32_16x16x32_bf16 v[58:61], v[152:155], v[164:167], v[58:61]
	v_mfma_f32_16x16x32_bf16 v[54:57], v[140:143], v[172:175], v[54:57]
	v_mfma_f32_16x16x32_bf16 v[46:49], v[152:155], v[172:175], v[46:49]
	v_mfma_f32_16x16x32_bf16 v[38:41], v[140:143], v[180:183], v[38:41]
	v_mfma_f32_16x16x32_bf16 v[30:33], v[152:155], v[180:183], v[30:33]
	v_mfma_f32_16x16x32_bf16 v[22:25], v[140:143], v[188:191], v[22:25]
	v_mfma_f32_16x16x32_bf16 v[14:17], v[152:155], v[188:191], v[14:17]
	v_mfma_f32_16x16x32_bf16 v[62:65], v[148:151], v[168:171], v[62:65]
	v_mfma_f32_16x16x32_bf16 v[58:61], v[160:163], v[168:171], v[58:61]
	v_mfma_f32_16x16x32_bf16 v[54:57], v[148:151], v[176:179], v[54:57]
	v_mfma_f32_16x16x32_bf16 v[46:49], v[160:163], v[176:179], v[46:49]
	v_mfma_f32_16x16x32_bf16 v[38:41], v[148:151], v[184:187], v[38:41]
	v_mfma_f32_16x16x32_bf16 v[30:33], v[160:163], v[184:187], v[30:33]
	v_mfma_f32_16x16x32_bf16 v[22:25], v[148:151], v[192:195], v[22:25]
	v_mfma_f32_16x16x32_bf16 v[14:17], v[160:163], v[192:195], v[14:17]
	s_add_u32 s52, s52, 0x80080
	s_addc_u32 s53, s53, 0
	s_add_i32 s38, s39, s56
	v_lshl_add_u64 v[140:141], s[52:53], 0, v[0:1]
	s_mov_b32 m0, s38
	s_nop 0
	global_load_lds_dwordx4 v[140:141], off
	v_lshl_add_u64 v[140:141], s[52:53], 0, v[134:135]
	s_add_i32 m0, s38, 0x2000
	s_nop 0
	global_load_lds_dwordx4 v[140:141], off
	v_mfma_f32_16x16x32_bf16 v[50:53], v[196:199], v[164:167], v[50:53]
	v_mfma_f32_16x16x32_bf16 v[42:45], v[204:207], v[164:167], v[42:45]
	v_mfma_f32_16x16x32_bf16 v[34:37], v[196:199], v[172:175], v[34:37]
	v_mfma_f32_16x16x32_bf16 v[26:29], v[204:207], v[172:175], v[26:29]
	v_mfma_f32_16x16x32_bf16 v[18:21], v[196:199], v[180:183], v[18:21]
	v_mfma_f32_16x16x32_bf16 v[10:13], v[204:207], v[180:183], v[10:13]
	v_mfma_f32_16x16x32_bf16 v[6:9], v[196:199], v[188:191], v[6:9]
	v_mfma_f32_16x16x32_bf16 v[2:5], v[204:207], v[188:191], v[2:5]
	v_mfma_f32_16x16x32_bf16 v[50:53], v[200:203], v[168:171], v[50:53]
	v_mfma_f32_16x16x32_bf16 v[42:45], v[210:213], v[168:171], v[42:45]
	v_mfma_f32_16x16x32_bf16 v[34:37], v[200:203], v[176:179], v[34:37]
	v_mfma_f32_16x16x32_bf16 v[26:29], v[210:213], v[176:179], v[26:29]
	v_mfma_f32_16x16x32_bf16 v[18:21], v[200:203], v[184:187], v[18:21]
	v_mfma_f32_16x16x32_bf16 v[10:13], v[210:213], v[184:187], v[10:13]
	v_mfma_f32_16x16x32_bf16 v[6:9], v[200:203], v[192:195], v[6:9]
	v_mfma_f32_16x16x32_bf16 v[2:5], v[210:213], v[192:195], v[2:5]
	s_setprio 0
	s_add_i32 s70, s70, 2
	s_add_u32 s68, s68, 0x100
	s_addc_u32 s69, s69, 0
	s_add_u32 s50, s50, 0x100
	s_addc_u32 s51, s51, 0
	s_cmp_gt_u32 s70, 29
	s_barrier
	s_cbranch_scc0 .LBB0_354
; __device__ __forceinline__ unsigned cvt_pk_bf16(float lo, float hi) { unsigned r; asm("v_cvt_pk_bf16_f32 %0, %1, %2" : "=v"(r) : "v"(lo), "v"(hi)); return r; }
;     __device__ __forceinline__ void operator()(const f32x4 (&acc)[2][2][4][2], const Unit& u, int wr, int wc, int fr, int fq) const {
;         const int row0 = u.pm * BM + wr * 64 + fr, col0 = u.pn * BM + wc * 32 + 8 * fq;
; #pragma unroll
;         for (int ai = 0; ai < 2; ++ai)
; #pragma unroll
;             for (int m = 0; m < 4; ++m) { bf16_t* rowp = O + (size_t)(row0 + ai * HALF + m * 16) * ldc + col0;
; #pragma unroll
;                 for (int bj = 0; bj < 2; ++bj) { f32x4 v0 = acc[ai][bj][m][0], v1 = acc[ai][bj][m][1];
;                     if (ACT == 1) {
; #pragma unroll
;                         for (int j = 0; j < 4; ++j) { float a = fmaxf(v0[j], 0.f), b = fmaxf(v1[j], 0.f); v0[j] = a * a; v1[j] = b * b; } }
;                     u32x4 w; w.x = cvt_pk_bf16(v0[0], v0[1]); w.y = cvt_pk_bf16(v0[2], v0[3]); w.z = cvt_pk_bf16(v1[0], v1[1]); w.w = cvt_pk_bf16(v1[2], v1[3]);
;                     if (ACT == 1) __builtin_nontemporal_store(w, (u32x4*)(rowp + bj * HALF));
;                     else *(u32x4*)(rowp + bj * HALF) = w; } }
	s_load_dwordx2 s[50:51], s[0:1], 0xc0
	v_lshl_add_u32 v150, s28, 8, v144
	v_lshl_or_b32 v142, s40, 8, v146
	v_ashrrev_i32_e32 v143, 31, v142
	v_cvt_pk_bf16_f32 v70, v70, v71
	s_waitcnt lgkmcnt(0)
	v_mov_b64_e32 v[140:141], s[50:51]
	v_cvt_pk_bf16_f32 v71, v72, v73
	v_cvt_pk_bf16_f32 v72, v66, v67
	v_add_u32_e32 v66, 0x80, v150
	v_mad_i64_i32 v[148:149], s[50:51], v150, s17, v[140:141]
	v_lshlrev_b64 v[142:143], 1, v[142:143]
	v_cvt_pk_bf16_f32 v114, v114, v115
	v_cvt_pk_bf16_f32 v115, v116, v117
	v_cvt_pk_bf16_f32 v116, v106, v107
	v_or_b32_e32 v106, 16, v150
	v_mad_i64_i32 v[66:67], s[50:51], v66, s17, v[140:141]
	v_cvt_pk_bf16_f32 v50, v50, v51
	v_cvt_pk_bf16_f32 v51, v52, v53
	v_cvt_pk_bf16_f32 v52, v42, v43
	v_add_u32_e32 v42, 0x90, v150
	v_lshl_add_u64 v[148:149], v[148:149], 0, v[142:143]
	v_mad_i64_i32 v[106:107], s[50:51], v106, s17, v[140:141]
	v_cvt_pk_bf16_f32 v98, v98, v99
	v_cvt_pk_bf16_f32 v99, v100, v101
	v_cvt_pk_bf16_f32 v100, v90, v91
	v_or_b32_e32 v90, 32, v150
	v_lshl_add_u64 v[66:67], v[66:67], 0, v[142:143]
	v_mad_i64_i32 v[42:43], s[50:51], v42, s17, v[140:141]
	v_cvt_pk_bf16_f32 v34, v34, v35
	v_cvt_pk_bf16_f32 v35, v36, v37
	v_cvt_pk_bf16_f32 v36, v26, v27
	v_add_u32_e32 v26, 0xa0, v150
	v_cvt_pk_bf16_f32 v117, v108, v109
	global_store_dwordx4 v[148:149], v[114:117], off offset:256
	v_mad_i64_i32 v[90:91], s[50:51], v90, s17, v[140:141]
	s_nop 0
	v_lshl_add_u64 v[114:115], v[106:107], 0, v[142:143]
	v_cvt_pk_bf16_f32 v82, v82, v83
	v_cvt_pk_bf16_f32 v83, v84, v85
	v_cvt_pk_bf16_f32 v84, v74, v75
	v_or_b32_e32 v74, 48, v150
	v_cvt_pk_bf16_f32 v53, v44, v45
	global_store_dwordx4 v[66:67], v[50:53], off offset:256
	v_mad_i64_i32 v[26:27], s[50:51], v26, s17, v[140:141]
	s_nop 0
	v_lshl_add_u64 v[50:51], v[42:43], 0, v[142:143]
	v_cvt_pk_bf16_f32 v18, v18, v19
	v_cvt_pk_bf16_f32 v19, v20, v21
	v_cvt_pk_bf16_f32 v20, v10, v11
	v_add_u32_e32 v10, 0xb0, v150
	v_cvt_pk_bf16_f32 v101, v92, v93
	global_store_dwordx4 v[114:115], v[98:101], off offset:256
	v_mad_i64_i32 v[74:75], s[50:51], v74, s17, v[140:141]
	s_nop 0
	v_lshl_add_u64 v[98:99], v[90:91], 0, v[142:143]
	v_cvt_pk_bf16_f32 v37, v28, v29
	global_store_dwordx4 v[50:51], v[34:37], off offset:256
	v_mad_i64_i32 v[10:11], s[50:51], v10, s17, v[140:141]
	s_nop 0
	v_lshl_add_u64 v[34:35], v[26:27], 0, v[142:143]
	v_cvt_pk_bf16_f32 v85, v76, v77
	global_store_dwordx4 v[98:99], v[82:85], off offset:256
	v_cvt_pk_bf16_f32 v21, v12, v13
	global_store_dwordx4 v[34:35], v[18:21], off offset:256
	s_and_b64 vcc, exec, s[46:47]
	v_lshl_add_u64 v[82:83], v[74:75], 0, v[142:143]
	v_lshl_add_u64 v[18:19], v[10:11], 0, v[142:143]
	s_mov_b32 s40, s42
	s_mov_b32 s28, s8
	s_mov_b32 s43, s42
	s_mov_b32 s46, s8
	s_mov_b64 s[50:51], s[48:49]
	s_mov_b64 s[52:53], s[44:45]
	v_cvt_pk_bf16_f32 v126, v126, v127
	v_cvt_pk_bf16_f32 v127, v128, v129
	v_cvt_pk_bf16_f32 v128, v122, v123
	v_cvt_pk_bf16_f32 v129, v124, v125
	global_store_dwordx4 v[148:149], v[126:129], off
	v_cvt_pk_bf16_f32 v106, v118, v119
	v_cvt_pk_bf16_f32 v107, v120, v121
	v_cvt_pk_bf16_f32 v108, v110, v111
	v_cvt_pk_bf16_f32 v109, v112, v113
	global_store_dwordx4 v[114:115], v[106:109], off
	v_cvt_pk_bf16_f32 v90, v102, v103
	v_cvt_pk_bf16_f32 v91, v104, v105
	v_cvt_pk_bf16_f32 v92, v94, v95
	v_cvt_pk_bf16_f32 v93, v96, v97
	global_store_dwordx4 v[98:99], v[90:93], off
	v_cvt_pk_bf16_f32 v74, v86, v87
	v_cvt_pk_bf16_f32 v75, v88, v89
	v_cvt_pk_bf16_f32 v76, v78, v79
	v_cvt_pk_bf16_f32 v77, v80, v81
	global_store_dwordx4 v[82:83], v[74:77], off
	v_cvt_pk_bf16_f32 v73, v68, v69
	global_store_dwordx4 v[82:83], v[70:73], off offset:256
	v_cvt_pk_bf16_f32 v62, v62, v63
	v_cvt_pk_bf16_f32 v63, v64, v65
	v_cvt_pk_bf16_f32 v64, v58, v59
	v_cvt_pk_bf16_f32 v65, v60, v61
	global_store_dwordx4 v[66:67], v[62:65], off
	v_cvt_pk_bf16_f32 v42, v54, v55
	v_cvt_pk_bf16_f32 v43, v56, v57
	v_cvt_pk_bf16_f32 v44, v46, v47
	v_cvt_pk_bf16_f32 v45, v48, v49
	global_store_dwordx4 v[50:51], v[42:45], off
	v_cvt_pk_bf16_f32 v26, v38, v39
	v_cvt_pk_bf16_f32 v27, v40, v41
	v_cvt_pk_bf16_f32 v28, v30, v31
	v_cvt_pk_bf16_f32 v29, v32, v33
	global_store_dwordx4 v[34:35], v[26:29], off
	v_cvt_pk_bf16_f32 v10, v22, v23
	v_cvt_pk_bf16_f32 v11, v24, v25
	v_cvt_pk_bf16_f32 v12, v14, v15
	v_cvt_pk_bf16_f32 v13, v16, v17
	global_store_dwordx4 v[18:19], v[10:13], off
	v_cvt_pk_bf16_f32 v6, v6, v7
	v_cvt_pk_bf16_f32 v7, v8, v9
	v_cvt_pk_bf16_f32 v8, v2, v3
	v_cvt_pk_bf16_f32 v9, v4, v5
	global_store_dwordx4 v[18:19], v[6:9], off offset:256
	s_cbranch_vccz .LBB0_346
	s_waitcnt vmcnt(0)
	s_cmpk_gt_u32 s25, 0xff
	s_cbranch_scc1 .LBB0_358
	s_barrier
